# RWKV: LDS operand reads waited for every other step (one full lgkmcnt wait per two steps)
# speedup vs baseline: 1.0220x; 1.0006x over previous
; DEVINL u16 f2bf(float a) { return (u16)(pk2(a, 0.f) & 0xffffu); }
; #define RW_STEP2(B) RW_STEP(B, WvA, XA, KrA, vhA, WvB, XB, KrB, vhB); RW_STEP((B) + 1, WvB, XB, KrB, vhB, WvA, XA, KrA, vhA)
; #define RW_STEP4(B) RW_STEP2(B); RW_STEP2((B) + 2)
; template <int DIR>
; DEVINL void rwkv_scan_dir(const Params& p, int task, int lane, int wave) {
;     ...
;   for (int st = 0; st < 4096; st += 32) {
;     RW_STEP(0, WvA, XA, KrA, vhA, WvB, XB, KrB, vhB);
;     if (st > 0) { const int q0 = st - 16 + seg; yo[(long)(DIR ? (4095 - q0) : q0) * 1024] = f2bf(ykeep); }
;     RW_STEP(1, WvB, XB, KrB, vhB, WvA, XA, KrA, vhA);
;     RW_STEP2(2); RW_STEP4(4); RW_STEP4(8); RW_STEP4(12);
.Lrw_ready_d0b0:
	s_add_u32 m0, s41, 16
	s_nop 0
	global_load_lds_dwordx4 v5, s[10:11] offset:0
	global_load_lds_dwordx4 v5, s[10:11] offset:1024
	global_load_lds_dwordx4 v5, s[10:11] offset:2048
	global_load_lds_dwordx4 v5, s[10:11] offset:3072
	s_add_u32 s10, s10, 0x4000
	s_addc_u32 s11, s11, 0
	s_add_u32 s41, s41, 0x4000
	s_and_b32 s41, s41, 0x1ffff
	ds_read_b64 v[72:73], v6 offset:2064
	ds_read_b128 v[74:77], v6 offset:2320
	ds_read_b128 v[78:81], v6 offset:2576
	ds_read_u16 v82, v7 offset:2064
	v_fma_mix_f32 v14, v10, v26, 0 op_sel:[0,0,0] op_sel_hi:[0,1,0]
	v_fma_mix_f32 v63, v10, v92, 0 op_sel:[0,0,0] op_sel_hi:[0,1,0]
	v_fma_mix_f32 v14, v11, v26, v14 op_sel:[0,1,0] op_sel_hi:[0,1,0]
	v_fma_mix_f32 v63, v11, v92, v63 op_sel:[0,1,0] op_sel_hi:[0,1,0]
	v_fma_mix_f32 v14, v12, v27, v14 op_sel:[0,0,0] op_sel_hi:[0,1,0]
	v_fma_mix_f32 v63, v12, v93, v63 op_sel:[0,0,0] op_sel_hi:[0,1,0]
	v_fma_mix_f32 v14, v13, v27, v14 op_sel:[0,1,0] op_sel_hi:[0,1,0]
	v_fma_mix_f32 v16, v10, v24, 0 op_sel:[0,0,0] op_sel_hi:[0,1,0]
	v_fma_mix_f32 v17, v11, v24, 0 op_sel:[0,1,0] op_sel_hi:[0,1,0]
	v_add_f32_dpp v20, v14, v14 quad_perm:[1,0,3,2] row_mask:0xf bank_mask:0xf bound_ctrl:1
	v_fma_mix_f32 v63, v13, v93, v63 op_sel:[0,1,0] op_sel_hi:[0,1,0]
	v_fma_mix_f32 v18, v12, v25, 0 op_sel:[0,0,0] op_sel_hi:[0,1,0]
	v_add_f32_dpp v20, v20, v20 quad_perm:[2,3,0,1] row_mask:0xf bank_mask:0xf bound_ctrl:1
	v_fma_mix_f32 v19, v13, v25, 0 op_sel:[0,1,0] op_sel_hi:[0,1,0]
	v_fma_mix_f32 v16, v34, v30, v16 op_sel:[0,0,0] op_sel_hi:[1,1,0]
	v_add_f32_dpp v20, v20, v20 row_half_mirror row_mask:0xf bank_mask:0xf bound_ctrl:1
	v_fma_mix_f32 v17, v34, v30, v17 op_sel:[0,1,0] op_sel_hi:[1,1,0]
	v_fma_mix_f32 v18, v34, v31, v18 op_sel:[0,0,0] op_sel_hi:[1,1,0]
	v_add_f32_dpp v20, v20, v20 row_mirror row_mask:0xf bank_mask:0xf bound_ctrl:1
	v_fma_mix_f32 v19, v34, v31, v19 op_sel:[0,1,0] op_sel_hi:[1,1,0]
	v_fma_mix_f32 v10, v20, v28, v16 op_sel:[0,0,0] op_sel_hi:[0,1,0]
	v_fma_mix_f32 v11, v20, v28, v17 op_sel:[0,1,0] op_sel_hi:[0,1,0]
	v_fma_mix_f32 v12, v20, v29, v18 op_sel:[0,0,0] op_sel_hi:[0,1,0]
	v_fma_mix_f32 v13, v20, v29, v19 op_sel:[0,1,0] op_sel_hi:[0,1,0]
	ds_read_b64 v[84:85], v6 offset:3088
	ds_read_b128 v[86:89], v6 offset:3344
	ds_read_b128 v[90:93], v6 offset:3600
	ds_read_u16 v94, v7 offset:3088
	v_fma_mix_f32 v14, v10, v38, 0 op_sel:[0,0,0] op_sel_hi:[0,1,0]
	v_fma_mix_f32 v48, v10, v32, 0 op_sel:[0,0,0] op_sel_hi:[0,1,0]
	v_fma_mix_f32 v14, v11, v38, v14 op_sel:[0,1,0] op_sel_hi:[0,1,0]
	v_fma_mix_f32 v48, v11, v32, v48 op_sel:[0,1,0] op_sel_hi:[0,1,0]
	v_fma_mix_f32 v14, v12, v39, v14 op_sel:[0,0,0] op_sel_hi:[0,1,0]
	v_fma_mix_f32 v48, v12, v33, v48 op_sel:[0,0,0] op_sel_hi:[0,1,0]
	v_fma_mix_f32 v14, v13, v39, v14 op_sel:[0,1,0] op_sel_hi:[0,1,0]
	v_fma_mix_f32 v16, v10, v36, 0 op_sel:[0,0,0] op_sel_hi:[0,1,0]
	v_fma_mix_f32 v17, v11, v36, 0 op_sel:[0,1,0] op_sel_hi:[0,1,0]
	v_add_f32_dpp v20, v14, v14 quad_perm:[1,0,3,2] row_mask:0xf bank_mask:0xf bound_ctrl:1
	v_fma_mix_f32 v48, v13, v33, v48 op_sel:[0,1,0] op_sel_hi:[0,1,0]
	v_fma_mix_f32 v18, v12, v37, 0 op_sel:[0,0,0] op_sel_hi:[0,1,0]
	v_add_f32_dpp v20, v20, v20 quad_perm:[2,3,0,1] row_mask:0xf bank_mask:0xf bound_ctrl:1
	v_fma_mix_f32 v19, v13, v37, 0 op_sel:[0,1,0] op_sel_hi:[0,1,0]
	v_fma_mix_f32 v16, v46, v42, v16 op_sel:[0,0,0] op_sel_hi:[1,1,0]
	v_add_f32_dpp v20, v20, v20 row_half_mirror row_mask:0xf bank_mask:0xf bound_ctrl:1
	v_fma_mix_f32 v17, v46, v42, v17 op_sel:[0,1,0] op_sel_hi:[1,1,0]
	v_fma_mix_f32 v18, v46, v43, v18 op_sel:[0,0,0] op_sel_hi:[1,1,0]
	v_add_f32_dpp v20, v20, v20 row_mirror row_mask:0xf bank_mask:0xf bound_ctrl:1
	v_fma_mix_f32 v19, v46, v43, v19 op_sel:[0,1,0] op_sel_hi:[1,1,0]
	v_fma_mix_f32 v10, v20, v40, v16 op_sel:[0,0,0] op_sel_hi:[0,1,0]
	v_fma_mix_f32 v11, v20, v40, v17 op_sel:[0,1,0] op_sel_hi:[0,1,0]
	v_fma_mix_f32 v12, v20, v41, v18 op_sel:[0,0,0] op_sel_hi:[0,1,0]
	v_fma_mix_f32 v13, v20, v41, v19 op_sel:[0,1,0] op_sel_hi:[0,1,0]
	s_waitcnt lgkmcnt(0)
	ds_read_b64 v[24:25], v6 offset:4112
	ds_read_b128 v[26:29], v6 offset:4368
	ds_read_b128 v[30:33], v6 offset:4624
	ds_read_u16 v34, v7 offset:4112
	v_fma_mix_f32 v14, v10, v74, 0 op_sel:[0,0,0] op_sel_hi:[0,1,0]
	v_fma_mix_f32 v49, v10, v44, 0 op_sel:[0,0,0] op_sel_hi:[0,1,0]
	v_fma_mix_f32 v14, v11, v74, v14 op_sel:[0,1,0] op_sel_hi:[0,1,0]
	v_fma_mix_f32 v49, v11, v44, v49 op_sel:[0,1,0] op_sel_hi:[0,1,0]
	v_fma_mix_f32 v14, v12, v75, v14 op_sel:[0,0,0] op_sel_hi:[0,1,0]
	v_fma_mix_f32 v49, v12, v45, v49 op_sel:[0,0,0] op_sel_hi:[0,1,0]
	v_fma_mix_f32 v14, v13, v75, v14 op_sel:[0,1,0] op_sel_hi:[0,1,0]
	v_fma_mix_f32 v16, v10, v72, 0 op_sel:[0,0,0] op_sel_hi:[0,1,0]
	v_fma_mix_f32 v17, v11, v72, 0 op_sel:[0,1,0] op_sel_hi:[0,1,0]
	v_add_f32_dpp v20, v14, v14 quad_perm:[1,0,3,2] row_mask:0xf bank_mask:0xf bound_ctrl:1
	v_fma_mix_f32 v49, v13, v45, v49 op_sel:[0,1,0] op_sel_hi:[0,1,0]
	v_fma_mix_f32 v18, v12, v73, 0 op_sel:[0,0,0] op_sel_hi:[0,1,0]
	v_add_f32_dpp v20, v20, v20 quad_perm:[2,3,0,1] row_mask:0xf bank_mask:0xf bound_ctrl:1
	v_fma_mix_f32 v19, v13, v73, 0 op_sel:[0,1,0] op_sel_hi:[0,1,0]
	v_fma_mix_f32 v16, v82, v78, v16 op_sel:[0,0,0] op_sel_hi:[1,1,0]
	v_add_f32_dpp v20, v20, v20 row_half_mirror row_mask:0xf bank_mask:0xf bound_ctrl:1
	v_fma_mix_f32 v17, v82, v78, v17 op_sel:[0,1,0] op_sel_hi:[1,1,0]
	v_fma_mix_f32 v18, v82, v79, v18 op_sel:[0,0,0] op_sel_hi:[1,1,0]
	v_add_f32_dpp v20, v20, v20 row_mirror row_mask:0xf bank_mask:0xf bound_ctrl:1
	v_fma_mix_f32 v19, v82, v79, v19 op_sel:[0,1,0] op_sel_hi:[1,1,0]
	v_fma_mix_f32 v10, v20, v76, v16 op_sel:[0,0,0] op_sel_hi:[0,1,0]
	v_fma_mix_f32 v11, v20, v76, v17 op_sel:[0,1,0] op_sel_hi:[0,1,0]
	v_fma_mix_f32 v12, v20, v77, v18 op_sel:[0,0,0] op_sel_hi:[0,1,0]
	v_fma_mix_f32 v13, v20, v77, v19 op_sel:[0,1,0] op_sel_hi:[0,1,0]
	ds_read_b64 v[36:37], v6 offset:5136
	ds_read_b128 v[38:41], v6 offset:5392
	ds_read_b128 v[42:45], v6 offset:5648
	ds_read_u16 v46, v7 offset:5136
	v_fma_mix_f32 v14, v10, v86, 0 op_sel:[0,0,0] op_sel_hi:[0,1,0]
	v_fma_mix_f32 v50, v10, v80, 0 op_sel:[0,0,0] op_sel_hi:[0,1,0]
	v_fma_mix_f32 v14, v11, v86, v14 op_sel:[0,1,0] op_sel_hi:[0,1,0]
	v_fma_mix_f32 v50, v11, v80, v50 op_sel:[0,1,0] op_sel_hi:[0,1,0]
	v_fma_mix_f32 v14, v12, v87, v14 op_sel:[0,0,0] op_sel_hi:[0,1,0]
	v_fma_mix_f32 v50, v12, v81, v50 op_sel:[0,0,0] op_sel_hi:[0,1,0]
	v_fma_mix_f32 v14, v13, v87, v14 op_sel:[0,1,0] op_sel_hi:[0,1,0]
	v_fma_mix_f32 v16, v10, v84, 0 op_sel:[0,0,0] op_sel_hi:[0,1,0]
	v_fma_mix_f32 v17, v11, v84, 0 op_sel:[0,1,0] op_sel_hi:[0,1,0]
	v_add_f32_dpp v20, v14, v14 quad_perm:[1,0,3,2] row_mask:0xf bank_mask:0xf bound_ctrl:1
	v_fma_mix_f32 v50, v13, v81, v50 op_sel:[0,1,0] op_sel_hi:[0,1,0]
	v_fma_mix_f32 v18, v12, v85, 0 op_sel:[0,0,0] op_sel_hi:[0,1,0]
	v_add_f32_dpp v20, v20, v20 quad_perm:[2,3,0,1] row_mask:0xf bank_mask:0xf bound_ctrl:1
	v_fma_mix_f32 v19, v13, v85, 0 op_sel:[0,1,0] op_sel_hi:[0,1,0]
	v_fma_mix_f32 v16, v94, v90, v16 op_sel:[0,0,0] op_sel_hi:[1,1,0]
	v_add_f32_dpp v20, v20, v20 row_half_mirror row_mask:0xf bank_mask:0xf bound_ctrl:1
	v_fma_mix_f32 v17, v94, v90, v17 op_sel:[0,1,0] op_sel_hi:[1,1,0]
	v_fma_mix_f32 v18, v94, v91, v18 op_sel:[0,0,0] op_sel_hi:[1,1,0]
	v_add_f32_dpp v20, v20, v20 row_mirror row_mask:0xf bank_mask:0xf bound_ctrl:1
	v_fma_mix_f32 v19, v94, v91, v19 op_sel:[0,1,0] op_sel_hi:[1,1,0]
	v_fma_mix_f32 v10, v20, v88, v16 op_sel:[0,0,0] op_sel_hi:[0,1,0]
	v_fma_mix_f32 v11, v20, v88, v17 op_sel:[0,1,0] op_sel_hi:[0,1,0]
	v_fma_mix_f32 v12, v20, v89, v18 op_sel:[0,0,0] op_sel_hi:[0,1,0]
	v_fma_mix_f32 v13, v20, v89, v19 op_sel:[0,1,0] op_sel_hi:[0,1,0]
	s_waitcnt lgkmcnt(0)
	ds_read_b64 v[72:73], v6 offset:6160
	ds_read_b128 v[74:77], v6 offset:6416
	ds_read_b128 v[78:81], v6 offset:6672
	ds_read_u16 v82, v7 offset:6160
	v_fma_mix_f32 v14, v10, v26, 0 op_sel:[0,0,0] op_sel_hi:[0,1,0]
	v_fma_mix_f32 v51, v10, v92, 0 op_sel:[0,0,0] op_sel_hi:[0,1,0]
	v_fma_mix_f32 v14, v11, v26, v14 op_sel:[0,1,0] op_sel_hi:[0,1,0]
	v_fma_mix_f32 v51, v11, v92, v51 op_sel:[0,1,0] op_sel_hi:[0,1,0]
	v_fma_mix_f32 v14, v12, v27, v14 op_sel:[0,0,0] op_sel_hi:[0,1,0]
	v_fma_mix_f32 v51, v12, v93, v51 op_sel:[0,0,0] op_sel_hi:[0,1,0]
	v_fma_mix_f32 v14, v13, v27, v14 op_sel:[0,1,0] op_sel_hi:[0,1,0]
	v_fma_mix_f32 v16, v10, v24, 0 op_sel:[0,0,0] op_sel_hi:[0,1,0]
	v_fma_mix_f32 v17, v11, v24, 0 op_sel:[0,1,0] op_sel_hi:[0,1,0]
	v_add_f32_dpp v20, v14, v14 quad_perm:[1,0,3,2] row_mask:0xf bank_mask:0xf bound_ctrl:1
	v_fma_mix_f32 v51, v13, v93, v51 op_sel:[0,1,0] op_sel_hi:[0,1,0]
	v_fma_mix_f32 v18, v12, v25, 0 op_sel:[0,0,0] op_sel_hi:[0,1,0]
	v_add_f32_dpp v20, v20, v20 quad_perm:[2,3,0,1] row_mask:0xf bank_mask:0xf bound_ctrl:1
	v_fma_mix_f32 v19, v13, v25, 0 op_sel:[0,1,0] op_sel_hi:[0,1,0]
	v_fma_mix_f32 v16, v34, v30, v16 op_sel:[0,0,0] op_sel_hi:[1,1,0]
	v_add_f32_dpp v20, v20, v20 row_half_mirror row_mask:0xf bank_mask:0xf bound_ctrl:1
	v_fma_mix_f32 v17, v34, v30, v17 op_sel:[0,1,0] op_sel_hi:[1,1,0]
	v_fma_mix_f32 v18, v34, v31, v18 op_sel:[0,0,0] op_sel_hi:[1,1,0]
	v_add_f32_dpp v20, v20, v20 row_mirror row_mask:0xf bank_mask:0xf bound_ctrl:1
	v_fma_mix_f32 v19, v34, v31, v19 op_sel:[0,1,0] op_sel_hi:[1,1,0]
	v_fma_mix_f32 v10, v20, v28, v16 op_sel:[0,0,0] op_sel_hi:[0,1,0]
	v_fma_mix_f32 v11, v20, v28, v17 op_sel:[0,1,0] op_sel_hi:[0,1,0]
	v_fma_mix_f32 v12, v20, v29, v18 op_sel:[0,0,0] op_sel_hi:[0,1,0]
	v_fma_mix_f32 v13, v20, v29, v19 op_sel:[0,1,0] op_sel_hi:[0,1,0]
	ds_read_b64 v[84:85], v6 offset:7184
	ds_read_b128 v[86:89], v6 offset:7440
	ds_read_b128 v[90:93], v6 offset:7696
	ds_read_u16 v94, v7 offset:7184
	v_fma_mix_f32 v14, v10, v38, 0 op_sel:[0,0,0] op_sel_hi:[0,1,0]
	v_fma_mix_f32 v52, v10, v32, 0 op_sel:[0,0,0] op_sel_hi:[0,1,0]
	v_fma_mix_f32 v14, v11, v38, v14 op_sel:[0,1,0] op_sel_hi:[0,1,0]
	v_fma_mix_f32 v52, v11, v32, v52 op_sel:[0,1,0] op_sel_hi:[0,1,0]
	v_fma_mix_f32 v14, v12, v39, v14 op_sel:[0,0,0] op_sel_hi:[0,1,0]
	v_fma_mix_f32 v52, v12, v33, v52 op_sel:[0,0,0] op_sel_hi:[0,1,0]
	v_fma_mix_f32 v14, v13, v39, v14 op_sel:[0,1,0] op_sel_hi:[0,1,0]
	v_fma_mix_f32 v16, v10, v36, 0 op_sel:[0,0,0] op_sel_hi:[0,1,0]
	v_fma_mix_f32 v17, v11, v36, 0 op_sel:[0,1,0] op_sel_hi:[0,1,0]
	v_add_f32_dpp v20, v14, v14 quad_perm:[1,0,3,2] row_mask:0xf bank_mask:0xf bound_ctrl:1
	v_fma_mix_f32 v52, v13, v33, v52 op_sel:[0,1,0] op_sel_hi:[0,1,0]
	v_fma_mix_f32 v18, v12, v37, 0 op_sel:[0,0,0] op_sel_hi:[0,1,0]
	v_add_f32_dpp v20, v20, v20 quad_perm:[2,3,0,1] row_mask:0xf bank_mask:0xf bound_ctrl:1
	v_fma_mix_f32 v19, v13, v37, 0 op_sel:[0,1,0] op_sel_hi:[0,1,0]
	v_fma_mix_f32 v16, v46, v42, v16 op_sel:[0,0,0] op_sel_hi:[1,1,0]
	v_add_f32_dpp v20, v20, v20 row_half_mirror row_mask:0xf bank_mask:0xf bound_ctrl:1
	v_fma_mix_f32 v17, v46, v42, v17 op_sel:[0,1,0] op_sel_hi:[1,1,0]
	v_fma_mix_f32 v18, v46, v43, v18 op_sel:[0,0,0] op_sel_hi:[1,1,0]
	v_add_f32_dpp v20, v20, v20 row_mirror row_mask:0xf bank_mask:0xf bound_ctrl:1
	v_fma_mix_f32 v19, v46, v43, v19 op_sel:[0,1,0] op_sel_hi:[1,1,0]
	v_fma_mix_f32 v10, v20, v40, v16 op_sel:[0,0,0] op_sel_hi:[0,1,0]
	v_fma_mix_f32 v11, v20, v40, v17 op_sel:[0,1,0] op_sel_hi:[0,1,0]
	v_fma_mix_f32 v12, v20, v41, v18 op_sel:[0,0,0] op_sel_hi:[0,1,0]
	v_fma_mix_f32 v13, v20, v41, v19 op_sel:[0,1,0] op_sel_hi:[0,1,0]
	s_waitcnt lgkmcnt(0)
	ds_read_b64 v[24:25], v6 offset:8208
	ds_read_b128 v[26:29], v6 offset:8464
	ds_read_b128 v[30:33], v6 offset:8720
	ds_read_u16 v34, v7 offset:8208
	v_fma_mix_f32 v14, v10, v74, 0 op_sel:[0,0,0] op_sel_hi:[0,1,0]
	v_fma_mix_f32 v53, v10, v44, 0 op_sel:[0,0,0] op_sel_hi:[0,1,0]
	v_fma_mix_f32 v14, v11, v74, v14 op_sel:[0,1,0] op_sel_hi:[0,1,0]
	v_fma_mix_f32 v53, v11, v44, v53 op_sel:[0,1,0] op_sel_hi:[0,1,0]
	v_fma_mix_f32 v14, v12, v75, v14 op_sel:[0,0,0] op_sel_hi:[0,1,0]
	v_fma_mix_f32 v53, v12, v45, v53 op_sel:[0,0,0] op_sel_hi:[0,1,0]
	v_fma_mix_f32 v14, v13, v75, v14 op_sel:[0,1,0] op_sel_hi:[0,1,0]
	v_fma_mix_f32 v16, v10, v72, 0 op_sel:[0,0,0] op_sel_hi:[0,1,0]
	v_fma_mix_f32 v17, v11, v72, 0 op_sel:[0,1,0] op_sel_hi:[0,1,0]
	v_add_f32_dpp v20, v14, v14 quad_perm:[1,0,3,2] row_mask:0xf bank_mask:0xf bound_ctrl:1
	v_fma_mix_f32 v53, v13, v45, v53 op_sel:[0,1,0] op_sel_hi:[0,1,0]
	v_fma_mix_f32 v18, v12, v73, 0 op_sel:[0,0,0] op_sel_hi:[0,1,0]
	v_add_f32_dpp v20, v20, v20 quad_perm:[2,3,0,1] row_mask:0xf bank_mask:0xf bound_ctrl:1
	v_fma_mix_f32 v19, v13, v73, 0 op_sel:[0,1,0] op_sel_hi:[0,1,0]
	v_fma_mix_f32 v16, v82, v78, v16 op_sel:[0,0,0] op_sel_hi:[1,1,0]
	v_add_f32_dpp v20, v20, v20 row_half_mirror row_mask:0xf bank_mask:0xf bound_ctrl:1
	v_fma_mix_f32 v17, v82, v78, v17 op_sel:[0,1,0] op_sel_hi:[1,1,0]
	v_fma_mix_f32 v18, v82, v79, v18 op_sel:[0,0,0] op_sel_hi:[1,1,0]
	v_add_f32_dpp v20, v20, v20 row_mirror row_mask:0xf bank_mask:0xf bound_ctrl:1
	v_fma_mix_f32 v19, v82, v79, v19 op_sel:[0,1,0] op_sel_hi:[1,1,0]
	v_fma_mix_f32 v10, v20, v76, v16 op_sel:[0,0,0] op_sel_hi:[0,1,0]
	v_fma_mix_f32 v11, v20, v76, v17 op_sel:[0,1,0] op_sel_hi:[0,1,0]
	v_fma_mix_f32 v12, v20, v77, v18 op_sel:[0,0,0] op_sel_hi:[0,1,0]
	v_fma_mix_f32 v13, v20, v77, v19 op_sel:[0,1,0] op_sel_hi:[0,1,0]
	ds_read_b64 v[36:37], v6 offset:9232
	ds_read_b128 v[38:41], v6 offset:9488
	ds_read_b128 v[42:45], v6 offset:9744
	ds_read_u16 v46, v7 offset:9232
	v_fma_mix_f32 v14, v10, v86, 0 op_sel:[0,0,0] op_sel_hi:[0,1,0]
	v_fma_mix_f32 v54, v10, v80, 0 op_sel:[0,0,0] op_sel_hi:[0,1,0]
	v_fma_mix_f32 v14, v11, v86, v14 op_sel:[0,1,0] op_sel_hi:[0,1,0]
	v_fma_mix_f32 v54, v11, v80, v54 op_sel:[0,1,0] op_sel_hi:[0,1,0]
	v_fma_mix_f32 v14, v12, v87, v14 op_sel:[0,0,0] op_sel_hi:[0,1,0]
	v_fma_mix_f32 v54, v12, v81, v54 op_sel:[0,0,0] op_sel_hi:[0,1,0]
	v_fma_mix_f32 v14, v13, v87, v14 op_sel:[0,1,0] op_sel_hi:[0,1,0]
	v_fma_mix_f32 v16, v10, v84, 0 op_sel:[0,0,0] op_sel_hi:[0,1,0]
	v_fma_mix_f32 v17, v11, v84, 0 op_sel:[0,1,0] op_sel_hi:[0,1,0]
	v_add_f32_dpp v20, v14, v14 quad_perm:[1,0,3,2] row_mask:0xf bank_mask:0xf bound_ctrl:1
	v_fma_mix_f32 v54, v13, v81, v54 op_sel:[0,1,0] op_sel_hi:[0,1,0]
	v_fma_mix_f32 v18, v12, v85, 0 op_sel:[0,0,0] op_sel_hi:[0,1,0]
	v_add_f32_dpp v20, v20, v20 quad_perm:[2,3,0,1] row_mask:0xf bank_mask:0xf bound_ctrl:1
	v_fma_mix_f32 v19, v13, v85, 0 op_sel:[0,1,0] op_sel_hi:[0,1,0]
	v_fma_mix_f32 v16, v94, v90, v16 op_sel:[0,0,0] op_sel_hi:[1,1,0]
	v_add_f32_dpp v20, v20, v20 row_half_mirror row_mask:0xf bank_mask:0xf bound_ctrl:1
	v_fma_mix_f32 v17, v94, v90, v17 op_sel:[0,1,0] op_sel_hi:[1,1,0]
	v_fma_mix_f32 v18, v94, v91, v18 op_sel:[0,0,0] op_sel_hi:[1,1,0]
	v_add_f32_dpp v20, v20, v20 row_mirror row_mask:0xf bank_mask:0xf bound_ctrl:1
	v_fma_mix_f32 v19, v94, v91, v19 op_sel:[0,1,0] op_sel_hi:[1,1,0]
	v_fma_mix_f32 v10, v20, v88, v16 op_sel:[0,0,0] op_sel_hi:[0,1,0]
	v_fma_mix_f32 v11, v20, v88, v17 op_sel:[0,1,0] op_sel_hi:[0,1,0]
	v_fma_mix_f32 v12, v20, v89, v18 op_sel:[0,0,0] op_sel_hi:[0,1,0]
	v_fma_mix_f32 v13, v20, v89, v19 op_sel:[0,1,0] op_sel_hi:[0,1,0]
	s_waitcnt lgkmcnt(0)
	ds_read_b64 v[72:73], v6 offset:10256
	ds_read_b128 v[74:77], v6 offset:10512
	ds_read_b128 v[78:81], v6 offset:10768
	ds_read_u16 v82, v7 offset:10256
	v_fma_mix_f32 v14, v10, v26, 0 op_sel:[0,0,0] op_sel_hi:[0,1,0]
	v_fma_mix_f32 v55, v10, v92, 0 op_sel:[0,0,0] op_sel_hi:[0,1,0]
	v_fma_mix_f32 v14, v11, v26, v14 op_sel:[0,1,0] op_sel_hi:[0,1,0]
	v_fma_mix_f32 v55, v11, v92, v55 op_sel:[0,1,0] op_sel_hi:[0,1,0]
	v_fma_mix_f32 v14, v12, v27, v14 op_sel:[0,0,0] op_sel_hi:[0,1,0]
	v_fma_mix_f32 v55, v12, v93, v55 op_sel:[0,0,0] op_sel_hi:[0,1,0]
	v_fma_mix_f32 v14, v13, v27, v14 op_sel:[0,1,0] op_sel_hi:[0,1,0]
	v_fma_mix_f32 v16, v10, v24, 0 op_sel:[0,0,0] op_sel_hi:[0,1,0]
	v_fma_mix_f32 v17, v11, v24, 0 op_sel:[0,1,0] op_sel_hi:[0,1,0]
	v_add_f32_dpp v20, v14, v14 quad_perm:[1,0,3,2] row_mask:0xf bank_mask:0xf bound_ctrl:1
	v_fma_mix_f32 v55, v13, v93, v55 op_sel:[0,1,0] op_sel_hi:[0,1,0]
	v_fma_mix_f32 v18, v12, v25, 0 op_sel:[0,0,0] op_sel_hi:[0,1,0]
	v_add_f32_dpp v20, v20, v20 quad_perm:[2,3,0,1] row_mask:0xf bank_mask:0xf bound_ctrl:1
	v_fma_mix_f32 v19, v13, v25, 0 op_sel:[0,1,0] op_sel_hi:[0,1,0]
	v_fma_mix_f32 v16, v34, v30, v16 op_sel:[0,0,0] op_sel_hi:[1,1,0]
	v_add_f32_dpp v20, v20, v20 row_half_mirror row_mask:0xf bank_mask:0xf bound_ctrl:1
	v_fma_mix_f32 v17, v34, v30, v17 op_sel:[0,1,0] op_sel_hi:[1,1,0]
	v_fma_mix_f32 v18, v34, v31, v18 op_sel:[0,0,0] op_sel_hi:[1,1,0]
	v_add_f32_dpp v20, v20, v20 row_mirror row_mask:0xf bank_mask:0xf bound_ctrl:1
	v_fma_mix_f32 v19, v34, v31, v19 op_sel:[0,1,0] op_sel_hi:[1,1,0]
	v_fma_mix_f32 v10, v20, v28, v16 op_sel:[0,0,0] op_sel_hi:[0,1,0]
	v_fma_mix_f32 v11, v20, v28, v17 op_sel:[0,1,0] op_sel_hi:[0,1,0]
	v_fma_mix_f32 v12, v20, v29, v18 op_sel:[0,0,0] op_sel_hi:[0,1,0]
	v_fma_mix_f32 v13, v20, v29, v19 op_sel:[0,1,0] op_sel_hi:[0,1,0]
	ds_read_b64 v[84:85], v6 offset:11280
	ds_read_b128 v[86:89], v6 offset:11536
	ds_read_b128 v[90:93], v6 offset:11792
	ds_read_u16 v94, v7 offset:11280
	v_fma_mix_f32 v14, v10, v38, 0 op_sel:[0,0,0] op_sel_hi:[0,1,0]
	v_fma_mix_f32 v56, v10, v32, 0 op_sel:[0,0,0] op_sel_hi:[0,1,0]
	v_fma_mix_f32 v14, v11, v38, v14 op_sel:[0,1,0] op_sel_hi:[0,1,0]
	v_fma_mix_f32 v56, v11, v32, v56 op_sel:[0,1,0] op_sel_hi:[0,1,0]
	v_fma_mix_f32 v14, v12, v39, v14 op_sel:[0,0,0] op_sel_hi:[0,1,0]
	v_fma_mix_f32 v56, v12, v33, v56 op_sel:[0,0,0] op_sel_hi:[0,1,0]
	v_fma_mix_f32 v14, v13, v39, v14 op_sel:[0,1,0] op_sel_hi:[0,1,0]
	v_fma_mix_f32 v16, v10, v36, 0 op_sel:[0,0,0] op_sel_hi:[0,1,0]
	v_fma_mix_f32 v17, v11, v36, 0 op_sel:[0,1,0] op_sel_hi:[0,1,0]
	v_add_f32_dpp v20, v14, v14 quad_perm:[1,0,3,2] row_mask:0xf bank_mask:0xf bound_ctrl:1
	v_fma_mix_f32 v56, v13, v33, v56 op_sel:[0,1,0] op_sel_hi:[0,1,0]
	v_fma_mix_f32 v18, v12, v37, 0 op_sel:[0,0,0] op_sel_hi:[0,1,0]
	v_add_f32_dpp v20, v20, v20 quad_perm:[2,3,0,1] row_mask:0xf bank_mask:0xf bound_ctrl:1
	v_fma_mix_f32 v19, v13, v37, 0 op_sel:[0,1,0] op_sel_hi:[0,1,0]
	v_fma_mix_f32 v16, v46, v42, v16 op_sel:[0,0,0] op_sel_hi:[1,1,0]
	v_add_f32_dpp v20, v20, v20 row_half_mirror row_mask:0xf bank_mask:0xf bound_ctrl:1
	v_fma_mix_f32 v17, v46, v42, v17 op_sel:[0,1,0] op_sel_hi:[1,1,0]
	v_fma_mix_f32 v18, v46, v43, v18 op_sel:[0,0,0] op_sel_hi:[1,1,0]
	v_add_f32_dpp v20, v20, v20 row_mirror row_mask:0xf bank_mask:0xf bound_ctrl:1
	v_fma_mix_f32 v19, v46, v43, v19 op_sel:[0,1,0] op_sel_hi:[1,1,0]
	v_fma_mix_f32 v10, v20, v40, v16 op_sel:[0,0,0] op_sel_hi:[0,1,0]
	v_fma_mix_f32 v11, v20, v40, v17 op_sel:[0,1,0] op_sel_hi:[0,1,0]
	v_fma_mix_f32 v12, v20, v41, v18 op_sel:[0,0,0] op_sel_hi:[0,1,0]
	v_fma_mix_f32 v13, v20, v41, v19 op_sel:[0,1,0] op_sel_hi:[0,1,0]
	s_waitcnt lgkmcnt(0)
	ds_read_b64 v[24:25], v6 offset:12304
	ds_read_b128 v[26:29], v6 offset:12560
	ds_read_b128 v[30:33], v6 offset:12816
	ds_read_u16 v34, v7 offset:12304
	v_fma_mix_f32 v14, v10, v74, 0 op_sel:[0,0,0] op_sel_hi:[0,1,0]
	v_fma_mix_f32 v57, v10, v44, 0 op_sel:[0,0,0] op_sel_hi:[0,1,0]
	v_fma_mix_f32 v14, v11, v74, v14 op_sel:[0,1,0] op_sel_hi:[0,1,0]
	v_fma_mix_f32 v57, v11, v44, v57 op_sel:[0,1,0] op_sel_hi:[0,1,0]
	v_fma_mix_f32 v14, v12, v75, v14 op_sel:[0,0,0] op_sel_hi:[0,1,0]
	v_fma_mix_f32 v57, v12, v45, v57 op_sel:[0,0,0] op_sel_hi:[0,1,0]
	v_fma_mix_f32 v14, v13, v75, v14 op_sel:[0,1,0] op_sel_hi:[0,1,0]
	v_fma_mix_f32 v16, v10, v72, 0 op_sel:[0,0,0] op_sel_hi:[0,1,0]
	v_fma_mix_f32 v17, v11, v72, 0 op_sel:[0,1,0] op_sel_hi:[0,1,0]
	v_add_f32_dpp v20, v14, v14 quad_perm:[1,0,3,2] row_mask:0xf bank_mask:0xf bound_ctrl:1
	v_fma_mix_f32 v57, v13, v45, v57 op_sel:[0,1,0] op_sel_hi:[0,1,0]
	v_fma_mix_f32 v18, v12, v73, 0 op_sel:[0,0,0] op_sel_hi:[0,1,0]
	v_add_f32_dpp v20, v20, v20 quad_perm:[2,3,0,1] row_mask:0xf bank_mask:0xf bound_ctrl:1
	v_fma_mix_f32 v19, v13, v73, 0 op_sel:[0,1,0] op_sel_hi:[0,1,0]
	v_fma_mix_f32 v16, v82, v78, v16 op_sel:[0,0,0] op_sel_hi:[1,1,0]
	v_add_f32_dpp v20, v20, v20 row_half_mirror row_mask:0xf bank_mask:0xf bound_ctrl:1
	v_fma_mix_f32 v17, v82, v78, v17 op_sel:[0,1,0] op_sel_hi:[1,1,0]
	v_fma_mix_f32 v18, v82, v79, v18 op_sel:[0,0,0] op_sel_hi:[1,1,0]
	v_add_f32_dpp v20, v20, v20 row_mirror row_mask:0xf bank_mask:0xf bound_ctrl:1
	v_fma_mix_f32 v19, v82, v79, v19 op_sel:[0,1,0] op_sel_hi:[1,1,0]
	v_fma_mix_f32 v10, v20, v76, v16 op_sel:[0,0,0] op_sel_hi:[0,1,0]
	v_fma_mix_f32 v11, v20, v76, v17 op_sel:[0,1,0] op_sel_hi:[0,1,0]
	v_fma_mix_f32 v12, v20, v77, v18 op_sel:[0,0,0] op_sel_hi:[0,1,0]
	v_fma_mix_f32 v13, v20, v77, v19 op_sel:[0,1,0] op_sel_hi:[0,1,0]
	ds_read_b64 v[36:37], v6 offset:13328
	ds_read_b128 v[38:41], v6 offset:13584
	ds_read_b128 v[42:45], v6 offset:13840
	ds_read_u16 v46, v7 offset:13328
	v_fma_mix_f32 v14, v10, v86, 0 op_sel:[0,0,0] op_sel_hi:[0,1,0]
	v_fma_mix_f32 v58, v10, v80, 0 op_sel:[0,0,0] op_sel_hi:[0,1,0]
	v_fma_mix_f32 v14, v11, v86, v14 op_sel:[0,1,0] op_sel_hi:[0,1,0]
	v_fma_mix_f32 v58, v11, v80, v58 op_sel:[0,1,0] op_sel_hi:[0,1,0]
	v_fma_mix_f32 v14, v12, v87, v14 op_sel:[0,0,0] op_sel_hi:[0,1,0]
	v_fma_mix_f32 v58, v12, v81, v58 op_sel:[0,0,0] op_sel_hi:[0,1,0]
	v_fma_mix_f32 v14, v13, v87, v14 op_sel:[0,1,0] op_sel_hi:[0,1,0]
	v_fma_mix_f32 v16, v10, v84, 0 op_sel:[0,0,0] op_sel_hi:[0,1,0]
	v_fma_mix_f32 v17, v11, v84, 0 op_sel:[0,1,0] op_sel_hi:[0,1,0]
	v_add_f32_dpp v20, v14, v14 quad_perm:[1,0,3,2] row_mask:0xf bank_mask:0xf bound_ctrl:1
	v_fma_mix_f32 v58, v13, v81, v58 op_sel:[0,1,0] op_sel_hi:[0,1,0]
	v_fma_mix_f32 v18, v12, v85, 0 op_sel:[0,0,0] op_sel_hi:[0,1,0]
	v_add_f32_dpp v20, v20, v20 quad_perm:[2,3,0,1] row_mask:0xf bank_mask:0xf bound_ctrl:1
	v_fma_mix_f32 v19, v13, v85, 0 op_sel:[0,1,0] op_sel_hi:[0,1,0]
	v_fma_mix_f32 v16, v94, v90, v16 op_sel:[0,0,0] op_sel_hi:[1,1,0]
	v_add_f32_dpp v20, v20, v20 row_half_mirror row_mask:0xf bank_mask:0xf bound_ctrl:1
	v_fma_mix_f32 v17, v94, v90, v17 op_sel:[0,1,0] op_sel_hi:[1,1,0]
	v_fma_mix_f32 v18, v94, v91, v18 op_sel:[0,0,0] op_sel_hi:[1,1,0]
	v_add_f32_dpp v20, v20, v20 row_mirror row_mask:0xf bank_mask:0xf bound_ctrl:1
	v_fma_mix_f32 v19, v94, v91, v19 op_sel:[0,1,0] op_sel_hi:[1,1,0]
	v_fma_mix_f32 v10, v20, v88, v16 op_sel:[0,0,0] op_sel_hi:[0,1,0]
	v_fma_mix_f32 v11, v20, v88, v17 op_sel:[0,1,0] op_sel_hi:[0,1,0]
	v_fma_mix_f32 v12, v20, v89, v18 op_sel:[0,0,0] op_sel_hi:[0,1,0]
	v_fma_mix_f32 v13, v20, v89, v19 op_sel:[0,1,0] op_sel_hi:[0,1,0]
	s_waitcnt lgkmcnt(0)
	ds_read_b64 v[72:73], v6 offset:14352
	ds_read_b128 v[74:77], v6 offset:14608
	ds_read_b128 v[78:81], v6 offset:14864
	ds_read_u16 v82, v7 offset:14352
	v_fma_mix_f32 v14, v10, v26, 0 op_sel:[0,0,0] op_sel_hi:[0,1,0]
	v_fma_mix_f32 v59, v10, v92, 0 op_sel:[0,0,0] op_sel_hi:[0,1,0]
	v_fma_mix_f32 v14, v11, v26, v14 op_sel:[0,1,0] op_sel_hi:[0,1,0]
	v_fma_mix_f32 v59, v11, v92, v59 op_sel:[0,1,0] op_sel_hi:[0,1,0]
	v_fma_mix_f32 v14, v12, v27, v14 op_sel:[0,0,0] op_sel_hi:[0,1,0]
	v_fma_mix_f32 v59, v12, v93, v59 op_sel:[0,0,0] op_sel_hi:[0,1,0]
	v_fma_mix_f32 v14, v13, v27, v14 op_sel:[0,1,0] op_sel_hi:[0,1,0]
	v_fma_mix_f32 v16, v10, v24, 0 op_sel:[0,0,0] op_sel_hi:[0,1,0]
	v_fma_mix_f32 v17, v11, v24, 0 op_sel:[0,1,0] op_sel_hi:[0,1,0]
	v_add_f32_dpp v20, v14, v14 quad_perm:[1,0,3,2] row_mask:0xf bank_mask:0xf bound_ctrl:1
	v_fma_mix_f32 v59, v13, v93, v59 op_sel:[0,1,0] op_sel_hi:[0,1,0]
	v_fma_mix_f32 v18, v12, v25, 0 op_sel:[0,0,0] op_sel_hi:[0,1,0]
	v_add_f32_dpp v20, v20, v20 quad_perm:[2,3,0,1] row_mask:0xf bank_mask:0xf bound_ctrl:1
	v_fma_mix_f32 v19, v13, v25, 0 op_sel:[0,1,0] op_sel_hi:[0,1,0]
	v_fma_mix_f32 v16, v34, v30, v16 op_sel:[0,0,0] op_sel_hi:[1,1,0]
	v_add_f32_dpp v20, v20, v20 row_half_mirror row_mask:0xf bank_mask:0xf bound_ctrl:1
	v_fma_mix_f32 v17, v34, v30, v17 op_sel:[0,1,0] op_sel_hi:[1,1,0]
	v_fma_mix_f32 v18, v34, v31, v18 op_sel:[0,0,0] op_sel_hi:[1,1,0]
	v_add_f32_dpp v20, v20, v20 row_mirror row_mask:0xf bank_mask:0xf bound_ctrl:1
	v_fma_mix_f32 v19, v34, v31, v19 op_sel:[0,1,0] op_sel_hi:[1,1,0]
	v_fma_mix_f32 v10, v20, v28, v16 op_sel:[0,0,0] op_sel_hi:[0,1,0]
	v_fma_mix_f32 v11, v20, v28, v17 op_sel:[0,1,0] op_sel_hi:[0,1,0]
	v_fma_mix_f32 v12, v20, v29, v18 op_sel:[0,0,0] op_sel_hi:[0,1,0]
	v_fma_mix_f32 v13, v20, v29, v19 op_sel:[0,1,0] op_sel_hi:[0,1,0]
	ds_read_b128 v[100:103], v9
	ds_read_b64 v[84:85], v6 offset:15376
	ds_read_b128 v[86:89], v6 offset:15632
	ds_read_b128 v[90:93], v6 offset:15888
	ds_read_u16 v94, v7 offset:15376
	v_fma_mix_f32 v14, v10, v38, 0 op_sel:[0,0,0] op_sel_hi:[0,1,0]
	v_fma_mix_f32 v60, v10, v32, 0 op_sel:[0,0,0] op_sel_hi:[0,1,0]
	v_fma_mix_f32 v14, v11, v38, v14 op_sel:[0,1,0] op_sel_hi:[0,1,0]
	v_fma_mix_f32 v60, v11, v32, v60 op_sel:[0,1,0] op_sel_hi:[0,1,0]
	v_fma_mix_f32 v14, v12, v39, v14 op_sel:[0,0,0] op_sel_hi:[0,1,0]
	v_fma_mix_f32 v60, v12, v33, v60 op_sel:[0,0,0] op_sel_hi:[0,1,0]
	v_fma_mix_f32 v14, v13, v39, v14 op_sel:[0,1,0] op_sel_hi:[0,1,0]
	v_fma_mix_f32 v16, v10, v36, 0 op_sel:[0,0,0] op_sel_hi:[0,1,0]
	v_fma_mix_f32 v17, v11, v36, 0 op_sel:[0,1,0] op_sel_hi:[0,1,0]
	v_add_f32_dpp v20, v14, v14 quad_perm:[1,0,3,2] row_mask:0xf bank_mask:0xf bound_ctrl:1
	v_fma_mix_f32 v60, v13, v33, v60 op_sel:[0,1,0] op_sel_hi:[0,1,0]
	v_fma_mix_f32 v18, v12, v37, 0 op_sel:[0,0,0] op_sel_hi:[0,1,0]
	v_add_f32_dpp v20, v20, v20 quad_perm:[2,3,0,1] row_mask:0xf bank_mask:0xf bound_ctrl:1
	v_fma_mix_f32 v19, v13, v37, 0 op_sel:[0,1,0] op_sel_hi:[0,1,0]
	v_fma_mix_f32 v16, v46, v42, v16 op_sel:[0,0,0] op_sel_hi:[1,1,0]
	v_add_f32_dpp v20, v20, v20 row_half_mirror row_mask:0xf bank_mask:0xf bound_ctrl:1
	v_fma_mix_f32 v17, v46, v42, v17 op_sel:[0,1,0] op_sel_hi:[1,1,0]
	v_fma_mix_f32 v18, v46, v43, v18 op_sel:[0,0,0] op_sel_hi:[1,1,0]
	v_add_f32_dpp v20, v20, v20 row_mirror row_mask:0xf bank_mask:0xf bound_ctrl:1
	v_fma_mix_f32 v19, v46, v43, v19 op_sel:[0,1,0] op_sel_hi:[1,1,0]
	v_fma_mix_f32 v10, v20, v40, v16 op_sel:[0,0,0] op_sel_hi:[0,1,0]
	v_fma_mix_f32 v11, v20, v40, v17 op_sel:[0,1,0] op_sel_hi:[0,1,0]
	v_fma_mix_f32 v12, v20, v41, v18 op_sel:[0,0,0] op_sel_hi:[0,1,0]
	v_fma_mix_f32 v13, v20, v41, v19 op_sel:[0,1,0] op_sel_hi:[0,1,0]
	s_waitcnt lgkmcnt(0)
	v_add_u32_e32 v6, 0x4000, v6
	v_add_u32_e32 v7, 0x4000, v7
	v_and_b32_e32 v6, 0x1ffff, v6
	v_and_b32_e32 v7, 0x1ffff, v7
	ds_read_b64 v[24:25], v6 offset:16
	ds_read_b128 v[26:29], v6 offset:272
	ds_read_b128 v[30:33], v6 offset:528
	ds_read_u16 v34, v7 offset:16
	v_fma_mix_f32 v14, v10, v74, 0 op_sel:[0,0,0] op_sel_hi:[0,1,0]
	v_fma_mix_f32 v61, v10, v44, 0 op_sel:[0,0,0] op_sel_hi:[0,1,0]
	v_fma_mix_f32 v14, v11, v74, v14 op_sel:[0,1,0] op_sel_hi:[0,1,0]
	v_fma_mix_f32 v61, v11, v44, v61 op_sel:[0,1,0] op_sel_hi:[0,1,0]
	v_fma_mix_f32 v14, v12, v75, v14 op_sel:[0,0,0] op_sel_hi:[0,1,0]
	v_fma_mix_f32 v61, v12, v45, v61 op_sel:[0,0,0] op_sel_hi:[0,1,0]
	v_fma_mix_f32 v14, v13, v75, v14 op_sel:[0,1,0] op_sel_hi:[0,1,0]
	v_fma_mix_f32 v16, v10, v72, 0 op_sel:[0,0,0] op_sel_hi:[0,1,0]
	v_fma_mix_f32 v17, v11, v72, 0 op_sel:[0,1,0] op_sel_hi:[0,1,0]
	v_add_f32_dpp v20, v14, v14 quad_perm:[1,0,3,2] row_mask:0xf bank_mask:0xf bound_ctrl:1
	v_fma_mix_f32 v61, v13, v45, v61 op_sel:[0,1,0] op_sel_hi:[0,1,0]
	v_fma_mix_f32 v18, v12, v73, 0 op_sel:[0,0,0] op_sel_hi:[0,1,0]
	v_add_f32_dpp v20, v20, v20 quad_perm:[2,3,0,1] row_mask:0xf bank_mask:0xf bound_ctrl:1
	v_fma_mix_f32 v19, v13, v73, 0 op_sel:[0,1,0] op_sel_hi:[0,1,0]
	v_fma_mix_f32 v16, v82, v78, v16 op_sel:[0,0,0] op_sel_hi:[1,1,0]
	v_add_f32_dpp v20, v20, v20 row_half_mirror row_mask:0xf bank_mask:0xf bound_ctrl:1
	v_fma_mix_f32 v17, v82, v78, v17 op_sel:[0,1,0] op_sel_hi:[1,1,0]
	v_fma_mix_f32 v18, v82, v79, v18 op_sel:[0,0,0] op_sel_hi:[1,1,0]
	v_add_f32_dpp v20, v20, v20 row_mirror row_mask:0xf bank_mask:0xf bound_ctrl:1
	v_fma_mix_f32 v19, v82, v79, v19 op_sel:[0,1,0] op_sel_hi:[1,1,0]
	v_fma_mix_f32 v10, v20, v76, v16 op_sel:[0,0,0] op_sel_hi:[0,1,0]
	v_fma_mix_f32 v11, v20, v76, v17 op_sel:[0,1,0] op_sel_hi:[0,1,0]
	v_fma_mix_f32 v12, v20, v77, v18 op_sel:[0,0,0] op_sel_hi:[0,1,0]
	v_fma_mix_f32 v13, v20, v77, v19 op_sel:[0,1,0] op_sel_hi:[0,1,0]
; DEVINL u16 f2bf(float a) { return (u16)(pk2(a, 0.f) & 0xffffu); }
; #define RW_STEP2(B) RW_STEP(B, WvA, XA, KrA, vhA, WvB, XB, KrB, vhB); RW_STEP((B) + 1, WvB, XB, KrB, vhB, WvA, XA, KrA, vhA)
; #define RW_STEP4(B) RW_STEP2(B); RW_STEP2((B) + 2)
; template <int DIR>
; DEVINL void rwkv_scan_dir(const Params& p, int task, int lane, int wave) {
;     ...
;   for (int st = 0; st < 4096; st += 32) {
;     RW_STEP(0, WvA, XA, KrA, vhA, WvB, XB, KrB, vhB);
;     if (st > 0) { const int q0 = st - 16 + seg; yo[(long)(DIR ? (4095 - q0) : q0) * 1024] = f2bf(ykeep); }
;     RW_STEP(1, WvB, XB, KrB, vhB, WvA, XA, KrA, vhA);
;     RW_STEP2(2); RW_STEP4(4); RW_STEP4(8); RW_STEP4(12);
	ds_read_b64 v[36:37], v6 offset:1040
	ds_read_b128 v[38:41], v6 offset:1296
	ds_read_b128 v[42:45], v6 offset:1552
	ds_read_u16 v46, v7 offset:1040
	v_fma_mix_f32 v14, v10, v86, 0 op_sel:[0,0,0] op_sel_hi:[0,1,0]
	v_fma_mix_f32 v62, v10, v80, 0 op_sel:[0,0,0] op_sel_hi:[0,1,0]
	v_fma_mix_f32 v14, v11, v86, v14 op_sel:[0,1,0] op_sel_hi:[0,1,0]
	v_fma_mix_f32 v62, v11, v80, v62 op_sel:[0,1,0] op_sel_hi:[0,1,0]
	v_fma_mix_f32 v14, v12, v87, v14 op_sel:[0,0,0] op_sel_hi:[0,1,0]
	v_fma_mix_f32 v62, v12, v81, v62 op_sel:[0,0,0] op_sel_hi:[0,1,0]
	v_fma_mix_f32 v14, v13, v87, v14 op_sel:[0,1,0] op_sel_hi:[0,1,0]
	v_fma_mix_f32 v16, v10, v84, 0 op_sel:[0,0,0] op_sel_hi:[0,1,0]
	v_fma_mix_f32 v17, v11, v84, 0 op_sel:[0,1,0] op_sel_hi:[0,1,0]
	v_add_f32_dpp v20, v14, v14 quad_perm:[1,0,3,2] row_mask:0xf bank_mask:0xf bound_ctrl:1
	v_fma_mix_f32 v62, v13, v81, v62 op_sel:[0,1,0] op_sel_hi:[0,1,0]
	v_fma_mix_f32 v18, v12, v85, 0 op_sel:[0,0,0] op_sel_hi:[0,1,0]
	v_add_f32_dpp v20, v20, v20 quad_perm:[2,3,0,1] row_mask:0xf bank_mask:0xf bound_ctrl:1
	v_fma_mix_f32 v19, v13, v85, 0 op_sel:[0,1,0] op_sel_hi:[0,1,0]
	v_fma_mix_f32 v16, v94, v90, v16 op_sel:[0,0,0] op_sel_hi:[1,1,0]
	v_add_f32_dpp v20, v20, v20 row_half_mirror row_mask:0xf bank_mask:0xf bound_ctrl:1
	v_fma_mix_f32 v17, v94, v90, v17 op_sel:[0,1,0] op_sel_hi:[1,1,0]
	v_fma_mix_f32 v18, v94, v91, v18 op_sel:[0,0,0] op_sel_hi:[1,1,0]
	v_add_f32_dpp v20, v20, v20 row_mirror row_mask:0xf bank_mask:0xf bound_ctrl:1
	v_fma_mix_f32 v19, v94, v91, v19 op_sel:[0,1,0] op_sel_hi:[1,1,0]
	v_fma_mix_f32 v10, v20, v88, v16 op_sel:[0,0,0] op_sel_hi:[0,1,0]
	v_fma_mix_f32 v11, v20, v88, v17 op_sel:[0,1,0] op_sel_hi:[0,1,0]
	v_fma_mix_f32 v12, v20, v89, v18 op_sel:[0,0,0] op_sel_hi:[0,1,0]
	v_fma_mix_f32 v13, v20, v89, v19 op_sel:[0,1,0] op_sel_hi:[0,1,0]
	s_waitcnt lgkmcnt(0)
	s_add_u32 s43, s43, 1
	s_waitcnt vmcnt(0)
	v_add_u32_e32 v69, 1, v69
	ds_write_b32 v23, v69
	v_min3_u32 v100, v100, v101, v102
	v_min_u32_e32 v100, v100, v103
	s_nop 0
	v_readfirstlane_b32 s24, v100
	s_nop 0
	s_cmp_ge_u32 s24, s43
	s_cbranch_scc0 .Lrw_slow_d0b1
.Lrw_ready_d0b1:
	s_add_u32 m0, s41, 16
	s_nop 0
	global_load_lds_dwordx4 v5, s[10:11] offset:0
	global_load_lds_dwordx4 v5, s[10:11] offset:1024
	global_load_lds_dwordx4 v5, s[10:11] offset:2048
	global_load_lds_dwordx4 v5, s[10:11] offset:3072
	s_add_u32 s10, s10, 0x4000
	s_addc_u32 s11, s11, 0
	s_add_u32 s41, s41, 0x4000
	s_and_b32 s41, s41, 0x1ffff
	ds_read_b64 v[72:73], v6 offset:2064
	ds_read_b128 v[74:77], v6 offset:2320
	ds_read_b128 v[78:81], v6 offset:2576
	ds_read_u16 v82, v7 offset:2064
	v_fma_mix_f32 v14, v10, v26, 0 op_sel:[0,0,0] op_sel_hi:[0,1,0]
	v_fma_mix_f32 v63, v10, v92, 0 op_sel:[0,0,0] op_sel_hi:[0,1,0]
	v_fma_mix_f32 v14, v11, v26, v14 op_sel:[0,1,0] op_sel_hi:[0,1,0]
	v_fma_mix_f32 v63, v11, v92, v63 op_sel:[0,1,0] op_sel_hi:[0,1,0]
	v_fma_mix_f32 v14, v12, v27, v14 op_sel:[0,0,0] op_sel_hi:[0,1,0]
	v_fma_mix_f32 v63, v12, v93, v63 op_sel:[0,0,0] op_sel_hi:[0,1,0]
	v_fma_mix_f32 v14, v13, v27, v14 op_sel:[0,1,0] op_sel_hi:[0,1,0]
	v_fma_mix_f32 v16, v10, v24, 0 op_sel:[0,0,0] op_sel_hi:[0,1,0]
	v_fma_mix_f32 v17, v11, v24, 0 op_sel:[0,1,0] op_sel_hi:[0,1,0]
	v_add_f32_dpp v20, v14, v14 quad_perm:[1,0,3,2] row_mask:0xf bank_mask:0xf bound_ctrl:1
	v_fma_mix_f32 v63, v13, v93, v63 op_sel:[0,1,0] op_sel_hi:[0,1,0]
	v_fma_mix_f32 v18, v12, v25, 0 op_sel:[0,0,0] op_sel_hi:[0,1,0]
	v_add_f32_dpp v20, v20, v20 quad_perm:[2,3,0,1] row_mask:0xf bank_mask:0xf bound_ctrl:1
	v_fma_mix_f32 v19, v13, v25, 0 op_sel:[0,1,0] op_sel_hi:[0,1,0]
	v_fma_mix_f32 v16, v34, v30, v16 op_sel:[0,0,0] op_sel_hi:[1,1,0]
	v_add_f32_dpp v20, v20, v20 row_half_mirror row_mask:0xf bank_mask:0xf bound_ctrl:1
	v_fma_mix_f32 v17, v34, v30, v17 op_sel:[0,1,0] op_sel_hi:[1,1,0]
	v_fma_mix_f32 v18, v34, v31, v18 op_sel:[0,0,0] op_sel_hi:[1,1,0]
	v_add_f32_dpp v20, v20, v20 row_mirror row_mask:0xf bank_mask:0xf bound_ctrl:1
	v_fma_mix_f32 v19, v34, v31, v19 op_sel:[0,1,0] op_sel_hi:[1,1,0]
	v_fma_mix_f32 v10, v20, v28, v16 op_sel:[0,0,0] op_sel_hi:[0,1,0]
	v_fma_mix_f32 v11, v20, v28, v17 op_sel:[0,1,0] op_sel_hi:[0,1,0]
	v_fma_mix_f32 v12, v20, v29, v18 op_sel:[0,0,0] op_sel_hi:[0,1,0]
	v_fma_mix_f32 v13, v20, v29, v19 op_sel:[0,1,0] op_sel_hi:[0,1,0]
	v_add_f32_dpp v48, v48, v48 row_ror:8 row_mask:0xf bank_mask:0x3
	v_add_f32_dpp v49, v49, v49 row_ror:8 row_mask:0xf bank_mask:0x3
	v_add_f32_dpp v50, v50, v50 row_ror:8 row_mask:0xf bank_mask:0x3
	v_add_f32_dpp v51, v51, v51 row_ror:8 row_mask:0xf bank_mask:0x3
	v_add_f32_dpp v52, v52, v52 row_ror:8 row_mask:0xf bank_mask:0x3
	v_add_f32_dpp v53, v53, v53 row_ror:8 row_mask:0xf bank_mask:0x3
	v_add_f32_dpp v54, v54, v54 row_ror:8 row_mask:0xf bank_mask:0x3
	v_add_f32_dpp v55, v55, v55 row_ror:8 row_mask:0xf bank_mask:0x3
	v_add_f32_dpp v48, v56, v56 row_ror:8 row_mask:0xf bank_mask:0xc
	v_add_f32_dpp v49, v57, v57 row_ror:8 row_mask:0xf bank_mask:0xc
	v_add_f32_dpp v50, v58, v58 row_ror:8 row_mask:0xf bank_mask:0xc
	v_add_f32_dpp v51, v59, v59 row_ror:8 row_mask:0xf bank_mask:0xc
	v_add_f32_dpp v52, v60, v60 row_ror:8 row_mask:0xf bank_mask:0xc
	v_add_f32_dpp v53, v61, v61 row_ror:8 row_mask:0xf bank_mask:0xc
	v_add_f32_dpp v54, v62, v62 row_ror:8 row_mask:0xf bank_mask:0xc
	v_add_f32_dpp v55, v63, v63 row_ror:8 row_mask:0xf bank_mask:0xc
	v_add_f32_dpp v48, v48, v48 row_ror:12 row_mask:0xf bank_mask:0x5
	v_add_f32_dpp v49, v49, v49 row_ror:12 row_mask:0xf bank_mask:0x5
	v_add_f32_dpp v50, v50, v50 row_ror:12 row_mask:0xf bank_mask:0x5
	v_add_f32_dpp v51, v51, v51 row_ror:12 row_mask:0xf bank_mask:0x5
	v_add_f32_dpp v48, v52, v52 row_ror:4 row_mask:0xf bank_mask:0xa
; DEVINL u16 f2bf(float a) { return (u16)(pk2(a, 0.f) & 0xffffu); }
; template <int DIR>
; DEVINL void rwkv_scan_dir(const Params& p, int task, int lane, int wave) {
;     ...
;   for (int st = 0; st < 4096; st += 32) {
;     RW_STEP(0, WvA, XA, KrA, vhA, WvB, XB, KrB, vhB);
;     if (st > 0) { const int q0 = st - 16 + seg; yo[(long)(DIR ? (4095 - q0) : q0) * 1024] = f2bf(ykeep); }
;     RW_STEP(1, WvB, XB, KrB, vhB, WvA, XA, KrA, vhA);
	v_add_f32_dpp v49, v53, v53 row_ror:4 row_mask:0xf bank_mask:0xa
	v_add_f32_dpp v50, v54, v54 row_ror:4 row_mask:0xf bank_mask:0xa
	v_add_f32_dpp v51, v55, v55 row_ror:4 row_mask:0xf bank_mask:0xa
	v_add_f32_dpp v64, v48, v48 quad_perm:[2,3,0,1] row_mask:0xf bank_mask:0xf bound_ctrl:1
	v_add_f32_dpp v65, v50, v50 quad_perm:[2,3,0,1] row_mask:0xf bank_mask:0xf bound_ctrl:1
	v_cndmask_b32_e64 v56, v64, v65, s[50:51]
	v_add_f32_dpp v64, v49, v49 quad_perm:[2,3,0,1] row_mask:0xf bank_mask:0xf bound_ctrl:1
	v_add_f32_dpp v65, v51, v51 quad_perm:[2,3,0,1] row_mask:0xf bank_mask:0xf bound_ctrl:1
	v_cndmask_b32_e64 v57, v64, v65, s[50:51]
	v_add_f32_dpp v64, v56, v56 quad_perm:[1,0,3,2] row_mask:0xf bank_mask:0xf bound_ctrl:1
	s_nop 0
	v_add_f32_dpp v65, v57, v57 quad_perm:[1,0,3,2] row_mask:0xf bank_mask:0xf bound_ctrl:1
	v_cndmask_b32_e64 v66, v64, v65, s[48:49]
	v_cvt_pk_bf16_f32 v66, v66, v66
	global_store_short v8, v66, s[12:13]
	s_add_u32 s12, s12, 0x8000
	s_addc_u32 s13, s13, 0
	ds_read_b64 v[84:85], v6 offset:3088
	ds_read_b128 v[86:89], v6 offset:3344
	ds_read_b128 v[90:93], v6 offset:3600
	ds_read_u16 v94, v7 offset:3088
	v_fma_mix_f32 v14, v10, v38, 0 op_sel:[0,0,0] op_sel_hi:[0,1,0]
	v_fma_mix_f32 v48, v10, v32, 0 op_sel:[0,0,0] op_sel_hi:[0,1,0]
	v_fma_mix_f32 v14, v11, v38, v14 op_sel:[0,1,0] op_sel_hi:[0,1,0]
	v_fma_mix_f32 v48, v11, v32, v48 op_sel:[0,1,0] op_sel_hi:[0,1,0]
	v_fma_mix_f32 v14, v12, v39, v14 op_sel:[0,0,0] op_sel_hi:[0,1,0]
	v_fma_mix_f32 v48, v12, v33, v48 op_sel:[0,0,0] op_sel_hi:[0,1,0]
	v_fma_mix_f32 v14, v13, v39, v14 op_sel:[0,1,0] op_sel_hi:[0,1,0]
	v_fma_mix_f32 v16, v10, v36, 0 op_sel:[0,0,0] op_sel_hi:[0,1,0]
	v_fma_mix_f32 v17, v11, v36, 0 op_sel:[0,1,0] op_sel_hi:[0,1,0]
	v_add_f32_dpp v20, v14, v14 quad_perm:[1,0,3,2] row_mask:0xf bank_mask:0xf bound_ctrl:1
	v_fma_mix_f32 v48, v13, v33, v48 op_sel:[0,1,0] op_sel_hi:[0,1,0]
	v_fma_mix_f32 v18, v12, v37, 0 op_sel:[0,0,0] op_sel_hi:[0,1,0]
	v_add_f32_dpp v20, v20, v20 quad_perm:[2,3,0,1] row_mask:0xf bank_mask:0xf bound_ctrl:1
	v_fma_mix_f32 v19, v13, v37, 0 op_sel:[0,1,0] op_sel_hi:[0,1,0]
	v_fma_mix_f32 v16, v46, v42, v16 op_sel:[0,0,0] op_sel_hi:[1,1,0]
	v_add_f32_dpp v20, v20, v20 row_half_mirror row_mask:0xf bank_mask:0xf bound_ctrl:1
	v_fma_mix_f32 v17, v46, v42, v17 op_sel:[0,1,0] op_sel_hi:[1,1,0]
	v_fma_mix_f32 v18, v46, v43, v18 op_sel:[0,0,0] op_sel_hi:[1,1,0]
	v_add_f32_dpp v20, v20, v20 row_mirror row_mask:0xf bank_mask:0xf bound_ctrl:1
	v_fma_mix_f32 v19, v46, v43, v19 op_sel:[0,1,0] op_sel_hi:[1,1,0]
	v_fma_mix_f32 v10, v20, v40, v16 op_sel:[0,0,0] op_sel_hi:[0,1,0]
	v_fma_mix_f32 v11, v20, v40, v17 op_sel:[0,1,0] op_sel_hi:[0,1,0]
	v_fma_mix_f32 v12, v20, v41, v18 op_sel:[0,0,0] op_sel_hi:[0,1,0]
	v_fma_mix_f32 v13, v20, v41, v19 op_sel:[0,1,0] op_sel_hi:[0,1,0]
	s_waitcnt lgkmcnt(0)
	ds_read_b64 v[24:25], v6 offset:4112
	ds_read_b128 v[26:29], v6 offset:4368
	ds_read_b128 v[30:33], v6 offset:4624
	ds_read_u16 v34, v7 offset:4112
	v_fma_mix_f32 v14, v10, v74, 0 op_sel:[0,0,0] op_sel_hi:[0,1,0]
	v_fma_mix_f32 v49, v10, v44, 0 op_sel:[0,0,0] op_sel_hi:[0,1,0]
	v_fma_mix_f32 v14, v11, v74, v14 op_sel:[0,1,0] op_sel_hi:[0,1,0]
	v_fma_mix_f32 v49, v11, v44, v49 op_sel:[0,1,0] op_sel_hi:[0,1,0]
	v_fma_mix_f32 v14, v12, v75, v14 op_sel:[0,0,0] op_sel_hi:[0,1,0]
	v_fma_mix_f32 v49, v12, v45, v49 op_sel:[0,0,0] op_sel_hi:[0,1,0]
	v_fma_mix_f32 v14, v13, v75, v14 op_sel:[0,1,0] op_sel_hi:[0,1,0]
	v_fma_mix_f32 v16, v10, v72, 0 op_sel:[0,0,0] op_sel_hi:[0,1,0]
	v_fma_mix_f32 v17, v11, v72, 0 op_sel:[0,1,0] op_sel_hi:[0,1,0]
	v_add_f32_dpp v20, v14, v14 quad_perm:[1,0,3,2] row_mask:0xf bank_mask:0xf bound_ctrl:1
	v_fma_mix_f32 v49, v13, v45, v49 op_sel:[0,1,0] op_sel_hi:[0,1,0]
	v_fma_mix_f32 v18, v12, v73, 0 op_sel:[0,0,0] op_sel_hi:[0,1,0]
	v_add_f32_dpp v20, v20, v20 quad_perm:[2,3,0,1] row_mask:0xf bank_mask:0xf bound_ctrl:1
	v_fma_mix_f32 v19, v13, v73, 0 op_sel:[0,1,0] op_sel_hi:[0,1,0]
	v_fma_mix_f32 v16, v82, v78, v16 op_sel:[0,0,0] op_sel_hi:[1,1,0]
	v_add_f32_dpp v20, v20, v20 row_half_mirror row_mask:0xf bank_mask:0xf bound_ctrl:1
	v_fma_mix_f32 v17, v82, v78, v17 op_sel:[0,1,0] op_sel_hi:[1,1,0]
	v_fma_mix_f32 v18, v82, v79, v18 op_sel:[0,0,0] op_sel_hi:[1,1,0]
	v_add_f32_dpp v20, v20, v20 row_mirror row_mask:0xf bank_mask:0xf bound_ctrl:1
	v_fma_mix_f32 v19, v82, v79, v19 op_sel:[0,1,0] op_sel_hi:[1,1,0]
	v_fma_mix_f32 v10, v20, v76, v16 op_sel:[0,0,0] op_sel_hi:[0,1,0]
	v_fma_mix_f32 v11, v20, v76, v17 op_sel:[0,1,0] op_sel_hi:[0,1,0]
	v_fma_mix_f32 v12, v20, v77, v18 op_sel:[0,0,0] op_sel_hi:[0,1,0]
	v_fma_mix_f32 v13, v20, v77, v19 op_sel:[0,1,0] op_sel_hi:[0,1,0]
	ds_read_b64 v[36:37], v6 offset:5136
	ds_read_b128 v[38:41], v6 offset:5392
	ds_read_b128 v[42:45], v6 offset:5648
	ds_read_u16 v46, v7 offset:5136
	v_fma_mix_f32 v14, v10, v86, 0 op_sel:[0,0,0] op_sel_hi:[0,1,0]
	v_fma_mix_f32 v50, v10, v80, 0 op_sel:[0,0,0] op_sel_hi:[0,1,0]
	v_fma_mix_f32 v14, v11, v86, v14 op_sel:[0,1,0] op_sel_hi:[0,1,0]
	v_fma_mix_f32 v50, v11, v80, v50 op_sel:[0,1,0] op_sel_hi:[0,1,0]
	v_fma_mix_f32 v14, v12, v87, v14 op_sel:[0,0,0] op_sel_hi:[0,1,0]
	v_fma_mix_f32 v50, v12, v81, v50 op_sel:[0,0,0] op_sel_hi:[0,1,0]
	v_fma_mix_f32 v14, v13, v87, v14 op_sel:[0,1,0] op_sel_hi:[0,1,0]
	v_fma_mix_f32 v16, v10, v84, 0 op_sel:[0,0,0] op_sel_hi:[0,1,0]
	v_fma_mix_f32 v17, v11, v84, 0 op_sel:[0,1,0] op_sel_hi:[0,1,0]
	v_add_f32_dpp v20, v14, v14 quad_perm:[1,0,3,2] row_mask:0xf bank_mask:0xf bound_ctrl:1
	v_fma_mix_f32 v50, v13, v81, v50 op_sel:[0,1,0] op_sel_hi:[0,1,0]
	v_fma_mix_f32 v18, v12, v85, 0 op_sel:[0,0,0] op_sel_hi:[0,1,0]
	v_add_f32_dpp v20, v20, v20 quad_perm:[2,3,0,1] row_mask:0xf bank_mask:0xf bound_ctrl:1
	v_fma_mix_f32 v19, v13, v85, 0 op_sel:[0,1,0] op_sel_hi:[0,1,0]
	v_fma_mix_f32 v16, v94, v90, v16 op_sel:[0,0,0] op_sel_hi:[1,1,0]
	v_add_f32_dpp v20, v20, v20 row_half_mirror row_mask:0xf bank_mask:0xf bound_ctrl:1
	v_fma_mix_f32 v17, v94, v90, v17 op_sel:[0,1,0] op_sel_hi:[1,1,0]
	v_fma_mix_f32 v18, v94, v91, v18 op_sel:[0,0,0] op_sel_hi:[1,1,0]
	v_add_f32_dpp v20, v20, v20 row_mirror row_mask:0xf bank_mask:0xf bound_ctrl:1
	v_fma_mix_f32 v19, v94, v91, v19 op_sel:[0,1,0] op_sel_hi:[1,1,0]
	v_fma_mix_f32 v10, v20, v88, v16 op_sel:[0,0,0] op_sel_hi:[0,1,0]
	v_fma_mix_f32 v11, v20, v88, v17 op_sel:[0,1,0] op_sel_hi:[0,1,0]
	v_fma_mix_f32 v12, v20, v89, v18 op_sel:[0,0,0] op_sel_hi:[0,1,0]
	v_fma_mix_f32 v13, v20, v89, v19 op_sel:[0,1,0] op_sel_hi:[0,1,0]
	s_waitcnt lgkmcnt(0)
	ds_read_b64 v[72:73], v6 offset:6160
	ds_read_b128 v[74:77], v6 offset:6416
	ds_read_b128 v[78:81], v6 offset:6672
	ds_read_u16 v82, v7 offset:6160
	v_fma_mix_f32 v14, v10, v26, 0 op_sel:[0,0,0] op_sel_hi:[0,1,0]
	v_fma_mix_f32 v51, v10, v92, 0 op_sel:[0,0,0] op_sel_hi:[0,1,0]
	v_fma_mix_f32 v14, v11, v26, v14 op_sel:[0,1,0] op_sel_hi:[0,1,0]
	v_fma_mix_f32 v51, v11, v92, v51 op_sel:[0,1,0] op_sel_hi:[0,1,0]
	v_fma_mix_f32 v14, v12, v27, v14 op_sel:[0,0,0] op_sel_hi:[0,1,0]
	v_fma_mix_f32 v51, v12, v93, v51 op_sel:[0,0,0] op_sel_hi:[0,1,0]
	v_fma_mix_f32 v14, v13, v27, v14 op_sel:[0,1,0] op_sel_hi:[0,1,0]
	v_fma_mix_f32 v16, v10, v24, 0 op_sel:[0,0,0] op_sel_hi:[0,1,0]
	v_fma_mix_f32 v17, v11, v24, 0 op_sel:[0,1,0] op_sel_hi:[0,1,0]
	v_add_f32_dpp v20, v14, v14 quad_perm:[1,0,3,2] row_mask:0xf bank_mask:0xf bound_ctrl:1
	v_fma_mix_f32 v51, v13, v93, v51 op_sel:[0,1,0] op_sel_hi:[0,1,0]
	v_fma_mix_f32 v18, v12, v25, 0 op_sel:[0,0,0] op_sel_hi:[0,1,0]
	v_add_f32_dpp v20, v20, v20 quad_perm:[2,3,0,1] row_mask:0xf bank_mask:0xf bound_ctrl:1
	v_fma_mix_f32 v19, v13, v25, 0 op_sel:[0,1,0] op_sel_hi:[0,1,0]
	v_fma_mix_f32 v16, v34, v30, v16 op_sel:[0,0,0] op_sel_hi:[1,1,0]
	v_add_f32_dpp v20, v20, v20 row_half_mirror row_mask:0xf bank_mask:0xf bound_ctrl:1
	v_fma_mix_f32 v17, v34, v30, v17 op_sel:[0,1,0] op_sel_hi:[1,1,0]
	v_fma_mix_f32 v18, v34, v31, v18 op_sel:[0,0,0] op_sel_hi:[1,1,0]
	v_add_f32_dpp v20, v20, v20 row_mirror row_mask:0xf bank_mask:0xf bound_ctrl:1
	v_fma_mix_f32 v19, v34, v31, v19 op_sel:[0,1,0] op_sel_hi:[1,1,0]
	v_fma_mix_f32 v10, v20, v28, v16 op_sel:[0,0,0] op_sel_hi:[0,1,0]
	v_fma_mix_f32 v11, v20, v28, v17 op_sel:[0,1,0] op_sel_hi:[0,1,0]
	v_fma_mix_f32 v12, v20, v29, v18 op_sel:[0,0,0] op_sel_hi:[0,1,0]
	v_fma_mix_f32 v13, v20, v29, v19 op_sel:[0,1,0] op_sel_hi:[0,1,0]
	ds_read_b64 v[84:85], v6 offset:7184
	ds_read_b128 v[86:89], v6 offset:7440
	ds_read_b128 v[90:93], v6 offset:7696
	ds_read_u16 v94, v7 offset:7184
	v_fma_mix_f32 v14, v10, v38, 0 op_sel:[0,0,0] op_sel_hi:[0,1,0]
	v_fma_mix_f32 v52, v10, v32, 0 op_sel:[0,0,0] op_sel_hi:[0,1,0]
	v_fma_mix_f32 v14, v11, v38, v14 op_sel:[0,1,0] op_sel_hi:[0,1,0]
	v_fma_mix_f32 v52, v11, v32, v52 op_sel:[0,1,0] op_sel_hi:[0,1,0]
	v_fma_mix_f32 v14, v12, v39, v14 op_sel:[0,0,0] op_sel_hi:[0,1,0]
	v_fma_mix_f32 v52, v12, v33, v52 op_sel:[0,0,0] op_sel_hi:[0,1,0]
	v_fma_mix_f32 v14, v13, v39, v14 op_sel:[0,1,0] op_sel_hi:[0,1,0]
	v_fma_mix_f32 v16, v10, v36, 0 op_sel:[0,0,0] op_sel_hi:[0,1,0]
	v_fma_mix_f32 v17, v11, v36, 0 op_sel:[0,1,0] op_sel_hi:[0,1,0]
	v_add_f32_dpp v20, v14, v14 quad_perm:[1,0,3,2] row_mask:0xf bank_mask:0xf bound_ctrl:1
	v_fma_mix_f32 v52, v13, v33, v52 op_sel:[0,1,0] op_sel_hi:[0,1,0]
	v_fma_mix_f32 v18, v12, v37, 0 op_sel:[0,0,0] op_sel_hi:[0,1,0]
	v_add_f32_dpp v20, v20, v20 quad_perm:[2,3,0,1] row_mask:0xf bank_mask:0xf bound_ctrl:1
	v_fma_mix_f32 v19, v13, v37, 0 op_sel:[0,1,0] op_sel_hi:[0,1,0]
	v_fma_mix_f32 v16, v46, v42, v16 op_sel:[0,0,0] op_sel_hi:[1,1,0]
	v_add_f32_dpp v20, v20, v20 row_half_mirror row_mask:0xf bank_mask:0xf bound_ctrl:1
	v_fma_mix_f32 v17, v46, v42, v17 op_sel:[0,1,0] op_sel_hi:[1,1,0]
	v_fma_mix_f32 v18, v46, v43, v18 op_sel:[0,0,0] op_sel_hi:[1,1,0]
	v_add_f32_dpp v20, v20, v20 row_mirror row_mask:0xf bank_mask:0xf bound_ctrl:1
	v_fma_mix_f32 v19, v46, v43, v19 op_sel:[0,1,0] op_sel_hi:[1,1,0]
	v_fma_mix_f32 v10, v20, v40, v16 op_sel:[0,0,0] op_sel_hi:[0,1,0]
	v_fma_mix_f32 v11, v20, v40, v17 op_sel:[0,1,0] op_sel_hi:[0,1,0]
	v_fma_mix_f32 v12, v20, v41, v18 op_sel:[0,0,0] op_sel_hi:[0,1,0]
	v_fma_mix_f32 v13, v20, v41, v19 op_sel:[0,1,0] op_sel_hi:[0,1,0]
	s_waitcnt lgkmcnt(0)
	ds_read_b64 v[24:25], v6 offset:8208
	ds_read_b128 v[26:29], v6 offset:8464
	ds_read_b128 v[30:33], v6 offset:8720
	ds_read_u16 v34, v7 offset:8208
	v_fma_mix_f32 v14, v10, v74, 0 op_sel:[0,0,0] op_sel_hi:[0,1,0]
	v_fma_mix_f32 v53, v10, v44, 0 op_sel:[0,0,0] op_sel_hi:[0,1,0]
	v_fma_mix_f32 v14, v11, v74, v14 op_sel:[0,1,0] op_sel_hi:[0,1,0]
	v_fma_mix_f32 v53, v11, v44, v53 op_sel:[0,1,0] op_sel_hi:[0,1,0]
	v_fma_mix_f32 v14, v12, v75, v14 op_sel:[0,0,0] op_sel_hi:[0,1,0]
	v_fma_mix_f32 v53, v12, v45, v53 op_sel:[0,0,0] op_sel_hi:[0,1,0]
	v_fma_mix_f32 v14, v13, v75, v14 op_sel:[0,1,0] op_sel_hi:[0,1,0]
	v_fma_mix_f32 v16, v10, v72, 0 op_sel:[0,0,0] op_sel_hi:[0,1,0]
	v_fma_mix_f32 v17, v11, v72, 0 op_sel:[0,1,0] op_sel_hi:[0,1,0]
	v_add_f32_dpp v20, v14, v14 quad_perm:[1,0,3,2] row_mask:0xf bank_mask:0xf bound_ctrl:1
	v_fma_mix_f32 v53, v13, v45, v53 op_sel:[0,1,0] op_sel_hi:[0,1,0]
	v_fma_mix_f32 v18, v12, v73, 0 op_sel:[0,0,0] op_sel_hi:[0,1,0]
	v_add_f32_dpp v20, v20, v20 quad_perm:[2,3,0,1] row_mask:0xf bank_mask:0xf bound_ctrl:1
	v_fma_mix_f32 v19, v13, v73, 0 op_sel:[0,1,0] op_sel_hi:[0,1,0]
	v_fma_mix_f32 v16, v82, v78, v16 op_sel:[0,0,0] op_sel_hi:[1,1,0]
	v_add_f32_dpp v20, v20, v20 row_half_mirror row_mask:0xf bank_mask:0xf bound_ctrl:1
	v_fma_mix_f32 v17, v82, v78, v17 op_sel:[0,1,0] op_sel_hi:[1,1,0]
	v_fma_mix_f32 v18, v82, v79, v18 op_sel:[0,0,0] op_sel_hi:[1,1,0]
	v_add_f32_dpp v20, v20, v20 row_mirror row_mask:0xf bank_mask:0xf bound_ctrl:1
	v_fma_mix_f32 v19, v82, v79, v19 op_sel:[0,1,0] op_sel_hi:[1,1,0]
	v_fma_mix_f32 v10, v20, v76, v16 op_sel:[0,0,0] op_sel_hi:[0,1,0]
	v_fma_mix_f32 v11, v20, v76, v17 op_sel:[0,1,0] op_sel_hi:[0,1,0]
	v_fma_mix_f32 v12, v20, v77, v18 op_sel:[0,0,0] op_sel_hi:[0,1,0]
	v_fma_mix_f32 v13, v20, v77, v19 op_sel:[0,1,0] op_sel_hi:[0,1,0]
	ds_read_b64 v[36:37], v6 offset:9232
	ds_read_b128 v[38:41], v6 offset:9488
	ds_read_b128 v[42:45], v6 offset:9744
	ds_read_u16 v46, v7 offset:9232
	v_fma_mix_f32 v14, v10, v86, 0 op_sel:[0,0,0] op_sel_hi:[0,1,0]
	v_fma_mix_f32 v54, v10, v80, 0 op_sel:[0,0,0] op_sel_hi:[0,1,0]
	v_fma_mix_f32 v14, v11, v86, v14 op_sel:[0,1,0] op_sel_hi:[0,1,0]
	v_fma_mix_f32 v54, v11, v80, v54 op_sel:[0,1,0] op_sel_hi:[0,1,0]
	v_fma_mix_f32 v14, v12, v87, v14 op_sel:[0,0,0] op_sel_hi:[0,1,0]
	v_fma_mix_f32 v54, v12, v81, v54 op_sel:[0,0,0] op_sel_hi:[0,1,0]
	v_fma_mix_f32 v14, v13, v87, v14 op_sel:[0,1,0] op_sel_hi:[0,1,0]
	v_fma_mix_f32 v16, v10, v84, 0 op_sel:[0,0,0] op_sel_hi:[0,1,0]
	v_fma_mix_f32 v17, v11, v84, 0 op_sel:[0,1,0] op_sel_hi:[0,1,0]
	v_add_f32_dpp v20, v14, v14 quad_perm:[1,0,3,2] row_mask:0xf bank_mask:0xf bound_ctrl:1
	v_fma_mix_f32 v54, v13, v81, v54 op_sel:[0,1,0] op_sel_hi:[0,1,0]
	v_fma_mix_f32 v18, v12, v85, 0 op_sel:[0,0,0] op_sel_hi:[0,1,0]
	v_add_f32_dpp v20, v20, v20 quad_perm:[2,3,0,1] row_mask:0xf bank_mask:0xf bound_ctrl:1
	v_fma_mix_f32 v19, v13, v85, 0 op_sel:[0,1,0] op_sel_hi:[0,1,0]
	v_fma_mix_f32 v16, v94, v90, v16 op_sel:[0,0,0] op_sel_hi:[1,1,0]
	v_add_f32_dpp v20, v20, v20 row_half_mirror row_mask:0xf bank_mask:0xf bound_ctrl:1
	v_fma_mix_f32 v17, v94, v90, v17 op_sel:[0,1,0] op_sel_hi:[1,1,0]
	v_fma_mix_f32 v18, v94, v91, v18 op_sel:[0,0,0] op_sel_hi:[1,1,0]
	v_add_f32_dpp v20, v20, v20 row_mirror row_mask:0xf bank_mask:0xf bound_ctrl:1
	v_fma_mix_f32 v19, v94, v91, v19 op_sel:[0,1,0] op_sel_hi:[1,1,0]
	v_fma_mix_f32 v10, v20, v88, v16 op_sel:[0,0,0] op_sel_hi:[0,1,0]
	v_fma_mix_f32 v11, v20, v88, v17 op_sel:[0,1,0] op_sel_hi:[0,1,0]
	v_fma_mix_f32 v12, v20, v89, v18 op_sel:[0,0,0] op_sel_hi:[0,1,0]
	v_fma_mix_f32 v13, v20, v89, v19 op_sel:[0,1,0] op_sel_hi:[0,1,0]
	s_waitcnt lgkmcnt(0)
	ds_read_b64 v[72:73], v6 offset:10256
	ds_read_b128 v[74:77], v6 offset:10512
	ds_read_b128 v[78:81], v6 offset:10768
	ds_read_u16 v82, v7 offset:10256
	v_fma_mix_f32 v14, v10, v26, 0 op_sel:[0,0,0] op_sel_hi:[0,1,0]
	v_fma_mix_f32 v55, v10, v92, 0 op_sel:[0,0,0] op_sel_hi:[0,1,0]
	v_fma_mix_f32 v14, v11, v26, v14 op_sel:[0,1,0] op_sel_hi:[0,1,0]
	v_fma_mix_f32 v55, v11, v92, v55 op_sel:[0,1,0] op_sel_hi:[0,1,0]
	v_fma_mix_f32 v14, v12, v27, v14 op_sel:[0,0,0] op_sel_hi:[0,1,0]
	v_fma_mix_f32 v55, v12, v93, v55 op_sel:[0,0,0] op_sel_hi:[0,1,0]
	v_fma_mix_f32 v14, v13, v27, v14 op_sel:[0,1,0] op_sel_hi:[0,1,0]
	v_fma_mix_f32 v16, v10, v24, 0 op_sel:[0,0,0] op_sel_hi:[0,1,0]
	v_fma_mix_f32 v17, v11, v24, 0 op_sel:[0,1,0] op_sel_hi:[0,1,0]
	v_add_f32_dpp v20, v14, v14 quad_perm:[1,0,3,2] row_mask:0xf bank_mask:0xf bound_ctrl:1
	v_fma_mix_f32 v55, v13, v93, v55 op_sel:[0,1,0] op_sel_hi:[0,1,0]
	v_fma_mix_f32 v18, v12, v25, 0 op_sel:[0,0,0] op_sel_hi:[0,1,0]
	v_add_f32_dpp v20, v20, v20 quad_perm:[2,3,0,1] row_mask:0xf bank_mask:0xf bound_ctrl:1
	v_fma_mix_f32 v19, v13, v25, 0 op_sel:[0,1,0] op_sel_hi:[0,1,0]
	v_fma_mix_f32 v16, v34, v30, v16 op_sel:[0,0,0] op_sel_hi:[1,1,0]
	v_add_f32_dpp v20, v20, v20 row_half_mirror row_mask:0xf bank_mask:0xf bound_ctrl:1
	v_fma_mix_f32 v17, v34, v30, v17 op_sel:[0,1,0] op_sel_hi:[1,1,0]
	v_fma_mix_f32 v18, v34, v31, v18 op_sel:[0,0,0] op_sel_hi:[1,1,0]
	v_add_f32_dpp v20, v20, v20 row_mirror row_mask:0xf bank_mask:0xf bound_ctrl:1
	v_fma_mix_f32 v19, v34, v31, v19 op_sel:[0,1,0] op_sel_hi:[1,1,0]
	v_fma_mix_f32 v10, v20, v28, v16 op_sel:[0,0,0] op_sel_hi:[0,1,0]
	v_fma_mix_f32 v11, v20, v28, v17 op_sel:[0,1,0] op_sel_hi:[0,1,0]
	v_fma_mix_f32 v12, v20, v29, v18 op_sel:[0,0,0] op_sel_hi:[0,1,0]
	v_fma_mix_f32 v13, v20, v29, v19 op_sel:[0,1,0] op_sel_hi:[0,1,0]
	ds_read_b64 v[84:85], v6 offset:11280
	ds_read_b128 v[86:89], v6 offset:11536
	ds_read_b128 v[90:93], v6 offset:11792
	ds_read_u16 v94, v7 offset:11280
	v_fma_mix_f32 v14, v10, v38, 0 op_sel:[0,0,0] op_sel_hi:[0,1,0]
	v_fma_mix_f32 v56, v10, v32, 0 op_sel:[0,0,0] op_sel_hi:[0,1,0]
	v_fma_mix_f32 v14, v11, v38, v14 op_sel:[0,1,0] op_sel_hi:[0,1,0]
	v_fma_mix_f32 v56, v11, v32, v56 op_sel:[0,1,0] op_sel_hi:[0,1,0]
	v_fma_mix_f32 v14, v12, v39, v14 op_sel:[0,0,0] op_sel_hi:[0,1,0]
	v_fma_mix_f32 v56, v12, v33, v56 op_sel:[0,0,0] op_sel_hi:[0,1,0]
	v_fma_mix_f32 v14, v13, v39, v14 op_sel:[0,1,0] op_sel_hi:[0,1,0]
	v_fma_mix_f32 v16, v10, v36, 0 op_sel:[0,0,0] op_sel_hi:[0,1,0]
	v_fma_mix_f32 v17, v11, v36, 0 op_sel:[0,1,0] op_sel_hi:[0,1,0]
	v_add_f32_dpp v20, v14, v14 quad_perm:[1,0,3,2] row_mask:0xf bank_mask:0xf bound_ctrl:1
	v_fma_mix_f32 v56, v13, v33, v56 op_sel:[0,1,0] op_sel_hi:[0,1,0]
	v_fma_mix_f32 v18, v12, v37, 0 op_sel:[0,0,0] op_sel_hi:[0,1,0]
	v_add_f32_dpp v20, v20, v20 quad_perm:[2,3,0,1] row_mask:0xf bank_mask:0xf bound_ctrl:1
	v_fma_mix_f32 v19, v13, v37, 0 op_sel:[0,1,0] op_sel_hi:[0,1,0]
	v_fma_mix_f32 v16, v46, v42, v16 op_sel:[0,0,0] op_sel_hi:[1,1,0]
	v_add_f32_dpp v20, v20, v20 row_half_mirror row_mask:0xf bank_mask:0xf bound_ctrl:1
	v_fma_mix_f32 v17, v46, v42, v17 op_sel:[0,1,0] op_sel_hi:[1,1,0]
	v_fma_mix_f32 v18, v46, v43, v18 op_sel:[0,0,0] op_sel_hi:[1,1,0]
	v_add_f32_dpp v20, v20, v20 row_mirror row_mask:0xf bank_mask:0xf bound_ctrl:1
	v_fma_mix_f32 v19, v46, v43, v19 op_sel:[0,1,0] op_sel_hi:[1,1,0]
	v_fma_mix_f32 v10, v20, v40, v16 op_sel:[0,0,0] op_sel_hi:[0,1,0]
	v_fma_mix_f32 v11, v20, v40, v17 op_sel:[0,1,0] op_sel_hi:[0,1,0]
	v_fma_mix_f32 v12, v20, v41, v18 op_sel:[0,0,0] op_sel_hi:[0,1,0]
	v_fma_mix_f32 v13, v20, v41, v19 op_sel:[0,1,0] op_sel_hi:[0,1,0]
	s_waitcnt lgkmcnt(0)
	ds_read_b64 v[24:25], v6 offset:12304
	ds_read_b128 v[26:29], v6 offset:12560
	ds_read_b128 v[30:33], v6 offset:12816
	ds_read_u16 v34, v7 offset:12304
	v_fma_mix_f32 v14, v10, v74, 0 op_sel:[0,0,0] op_sel_hi:[0,1,0]
	v_fma_mix_f32 v57, v10, v44, 0 op_sel:[0,0,0] op_sel_hi:[0,1,0]
	v_fma_mix_f32 v14, v11, v74, v14 op_sel:[0,1,0] op_sel_hi:[0,1,0]
	v_fma_mix_f32 v57, v11, v44, v57 op_sel:[0,1,0] op_sel_hi:[0,1,0]
	v_fma_mix_f32 v14, v12, v75, v14 op_sel:[0,0,0] op_sel_hi:[0,1,0]
	v_fma_mix_f32 v57, v12, v45, v57 op_sel:[0,0,0] op_sel_hi:[0,1,0]
	v_fma_mix_f32 v14, v13, v75, v14 op_sel:[0,1,0] op_sel_hi:[0,1,0]
	v_fma_mix_f32 v16, v10, v72, 0 op_sel:[0,0,0] op_sel_hi:[0,1,0]
	v_fma_mix_f32 v17, v11, v72, 0 op_sel:[0,1,0] op_sel_hi:[0,1,0]
	v_add_f32_dpp v20, v14, v14 quad_perm:[1,0,3,2] row_mask:0xf bank_mask:0xf bound_ctrl:1
	v_fma_mix_f32 v57, v13, v45, v57 op_sel:[0,1,0] op_sel_hi:[0,1,0]
	v_fma_mix_f32 v18, v12, v73, 0 op_sel:[0,0,0] op_sel_hi:[0,1,0]
	v_add_f32_dpp v20, v20, v20 quad_perm:[2,3,0,1] row_mask:0xf bank_mask:0xf bound_ctrl:1
	v_fma_mix_f32 v19, v13, v73, 0 op_sel:[0,1,0] op_sel_hi:[0,1,0]
	v_fma_mix_f32 v16, v82, v78, v16 op_sel:[0,0,0] op_sel_hi:[1,1,0]
	v_add_f32_dpp v20, v20, v20 row_half_mirror row_mask:0xf bank_mask:0xf bound_ctrl:1
	v_fma_mix_f32 v17, v82, v78, v17 op_sel:[0,1,0] op_sel_hi:[1,1,0]
	v_fma_mix_f32 v18, v82, v79, v18 op_sel:[0,0,0] op_sel_hi:[1,1,0]
	v_add_f32_dpp v20, v20, v20 row_mirror row_mask:0xf bank_mask:0xf bound_ctrl:1
	v_fma_mix_f32 v19, v82, v79, v19 op_sel:[0,1,0] op_sel_hi:[1,1,0]
	v_fma_mix_f32 v10, v20, v76, v16 op_sel:[0,0,0] op_sel_hi:[0,1,0]
	v_fma_mix_f32 v11, v20, v76, v17 op_sel:[0,1,0] op_sel_hi:[0,1,0]
	v_fma_mix_f32 v12, v20, v77, v18 op_sel:[0,0,0] op_sel_hi:[0,1,0]
	v_fma_mix_f32 v13, v20, v77, v19 op_sel:[0,1,0] op_sel_hi:[0,1,0]
	ds_read_b64 v[36:37], v6 offset:13328
	ds_read_b128 v[38:41], v6 offset:13584
	ds_read_b128 v[42:45], v6 offset:13840
	ds_read_u16 v46, v7 offset:13328
	v_fma_mix_f32 v14, v10, v86, 0 op_sel:[0,0,0] op_sel_hi:[0,1,0]
	v_fma_mix_f32 v58, v10, v80, 0 op_sel:[0,0,0] op_sel_hi:[0,1,0]
	v_fma_mix_f32 v14, v11, v86, v14 op_sel:[0,1,0] op_sel_hi:[0,1,0]
	v_fma_mix_f32 v58, v11, v80, v58 op_sel:[0,1,0] op_sel_hi:[0,1,0]
	v_fma_mix_f32 v14, v12, v87, v14 op_sel:[0,0,0] op_sel_hi:[0,1,0]
	v_fma_mix_f32 v58, v12, v81, v58 op_sel:[0,0,0] op_sel_hi:[0,1,0]
	v_fma_mix_f32 v14, v13, v87, v14 op_sel:[0,1,0] op_sel_hi:[0,1,0]
	v_fma_mix_f32 v16, v10, v84, 0 op_sel:[0,0,0] op_sel_hi:[0,1,0]
	v_fma_mix_f32 v17, v11, v84, 0 op_sel:[0,1,0] op_sel_hi:[0,1,0]
	v_add_f32_dpp v20, v14, v14 quad_perm:[1,0,3,2] row_mask:0xf bank_mask:0xf bound_ctrl:1
	v_fma_mix_f32 v58, v13, v81, v58 op_sel:[0,1,0] op_sel_hi:[0,1,0]
	v_fma_mix_f32 v18, v12, v85, 0 op_sel:[0,0,0] op_sel_hi:[0,1,0]
	v_add_f32_dpp v20, v20, v20 quad_perm:[2,3,0,1] row_mask:0xf bank_mask:0xf bound_ctrl:1
	v_fma_mix_f32 v19, v13, v85, 0 op_sel:[0,1,0] op_sel_hi:[0,1,0]
	v_fma_mix_f32 v16, v94, v90, v16 op_sel:[0,0,0] op_sel_hi:[1,1,0]
	v_add_f32_dpp v20, v20, v20 row_half_mirror row_mask:0xf bank_mask:0xf bound_ctrl:1
	v_fma_mix_f32 v17, v94, v90, v17 op_sel:[0,1,0] op_sel_hi:[1,1,0]
	v_fma_mix_f32 v18, v94, v91, v18 op_sel:[0,0,0] op_sel_hi:[1,1,0]
	v_add_f32_dpp v20, v20, v20 row_mirror row_mask:0xf bank_mask:0xf bound_ctrl:1
	v_fma_mix_f32 v19, v94, v91, v19 op_sel:[0,1,0] op_sel_hi:[1,1,0]
	v_fma_mix_f32 v10, v20, v88, v16 op_sel:[0,0,0] op_sel_hi:[0,1,0]
	v_fma_mix_f32 v11, v20, v88, v17 op_sel:[0,1,0] op_sel_hi:[0,1,0]
	v_fma_mix_f32 v12, v20, v89, v18 op_sel:[0,0,0] op_sel_hi:[0,1,0]
	v_fma_mix_f32 v13, v20, v89, v19 op_sel:[0,1,0] op_sel_hi:[0,1,0]
	s_waitcnt lgkmcnt(0)
	ds_read_b64 v[72:73], v6 offset:14352
	ds_read_b128 v[74:77], v6 offset:14608
	ds_read_b128 v[78:81], v6 offset:14864
	ds_read_u16 v82, v7 offset:14352
	v_fma_mix_f32 v14, v10, v26, 0 op_sel:[0,0,0] op_sel_hi:[0,1,0]
	v_fma_mix_f32 v59, v10, v92, 0 op_sel:[0,0,0] op_sel_hi:[0,1,0]
	v_fma_mix_f32 v14, v11, v26, v14 op_sel:[0,1,0] op_sel_hi:[0,1,0]
	v_fma_mix_f32 v59, v11, v92, v59 op_sel:[0,1,0] op_sel_hi:[0,1,0]
	v_fma_mix_f32 v14, v12, v27, v14 op_sel:[0,0,0] op_sel_hi:[0,1,0]
	v_fma_mix_f32 v59, v12, v93, v59 op_sel:[0,0,0] op_sel_hi:[0,1,0]
	v_fma_mix_f32 v14, v13, v27, v14 op_sel:[0,1,0] op_sel_hi:[0,1,0]
	v_fma_mix_f32 v16, v10, v24, 0 op_sel:[0,0,0] op_sel_hi:[0,1,0]
	v_fma_mix_f32 v17, v11, v24, 0 op_sel:[0,1,0] op_sel_hi:[0,1,0]
	v_add_f32_dpp v20, v14, v14 quad_perm:[1,0,3,2] row_mask:0xf bank_mask:0xf bound_ctrl:1
	v_fma_mix_f32 v59, v13, v93, v59 op_sel:[0,1,0] op_sel_hi:[0,1,0]
	v_fma_mix_f32 v18, v12, v25, 0 op_sel:[0,0,0] op_sel_hi:[0,1,0]
	v_add_f32_dpp v20, v20, v20 quad_perm:[2,3,0,1] row_mask:0xf bank_mask:0xf bound_ctrl:1
	v_fma_mix_f32 v19, v13, v25, 0 op_sel:[0,1,0] op_sel_hi:[0,1,0]
	v_fma_mix_f32 v16, v34, v30, v16 op_sel:[0,0,0] op_sel_hi:[1,1,0]
	v_add_f32_dpp v20, v20, v20 row_half_mirror row_mask:0xf bank_mask:0xf bound_ctrl:1
	v_fma_mix_f32 v17, v34, v30, v17 op_sel:[0,1,0] op_sel_hi:[1,1,0]
	v_fma_mix_f32 v18, v34, v31, v18 op_sel:[0,0,0] op_sel_hi:[1,1,0]
	v_add_f32_dpp v20, v20, v20 row_mirror row_mask:0xf bank_mask:0xf bound_ctrl:1
	v_fma_mix_f32 v19, v34, v31, v19 op_sel:[0,1,0] op_sel_hi:[1,1,0]
	v_fma_mix_f32 v10, v20, v28, v16 op_sel:[0,0,0] op_sel_hi:[0,1,0]
	v_fma_mix_f32 v11, v20, v28, v17 op_sel:[0,1,0] op_sel_hi:[0,1,0]
	v_fma_mix_f32 v12, v20, v29, v18 op_sel:[0,0,0] op_sel_hi:[0,1,0]
	v_fma_mix_f32 v13, v20, v29, v19 op_sel:[0,1,0] op_sel_hi:[0,1,0]
	ds_read_b128 v[100:103], v9
	ds_read_b64 v[84:85], v6 offset:15376
	ds_read_b128 v[86:89], v6 offset:15632
	ds_read_b128 v[90:93], v6 offset:15888
	ds_read_u16 v94, v7 offset:15376
	v_fma_mix_f32 v14, v10, v38, 0 op_sel:[0,0,0] op_sel_hi:[0,1,0]
	v_fma_mix_f32 v60, v10, v32, 0 op_sel:[0,0,0] op_sel_hi:[0,1,0]
	v_fma_mix_f32 v14, v11, v38, v14 op_sel:[0,1,0] op_sel_hi:[0,1,0]
	v_fma_mix_f32 v60, v11, v32, v60 op_sel:[0,1,0] op_sel_hi:[0,1,0]
	v_fma_mix_f32 v14, v12, v39, v14 op_sel:[0,0,0] op_sel_hi:[0,1,0]
	v_fma_mix_f32 v60, v12, v33, v60 op_sel:[0,0,0] op_sel_hi:[0,1,0]
	v_fma_mix_f32 v14, v13, v39, v14 op_sel:[0,1,0] op_sel_hi:[0,1,0]
	v_fma_mix_f32 v16, v10, v36, 0 op_sel:[0,0,0] op_sel_hi:[0,1,0]
	v_fma_mix_f32 v17, v11, v36, 0 op_sel:[0,1,0] op_sel_hi:[0,1,0]
	v_add_f32_dpp v20, v14, v14 quad_perm:[1,0,3,2] row_mask:0xf bank_mask:0xf bound_ctrl:1
	v_fma_mix_f32 v60, v13, v33, v60 op_sel:[0,1,0] op_sel_hi:[0,1,0]
	v_fma_mix_f32 v18, v12, v37, 0 op_sel:[0,0,0] op_sel_hi:[0,1,0]
	v_add_f32_dpp v20, v20, v20 quad_perm:[2,3,0,1] row_mask:0xf bank_mask:0xf bound_ctrl:1
	v_fma_mix_f32 v19, v13, v37, 0 op_sel:[0,1,0] op_sel_hi:[0,1,0]
	v_fma_mix_f32 v16, v46, v42, v16 op_sel:[0,0,0] op_sel_hi:[1,1,0]
	v_add_f32_dpp v20, v20, v20 row_half_mirror row_mask:0xf bank_mask:0xf bound_ctrl:1
	v_fma_mix_f32 v17, v46, v42, v17 op_sel:[0,1,0] op_sel_hi:[1,1,0]
	v_fma_mix_f32 v18, v46, v43, v18 op_sel:[0,0,0] op_sel_hi:[1,1,0]
	v_add_f32_dpp v20, v20, v20 row_mirror row_mask:0xf bank_mask:0xf bound_ctrl:1
	v_fma_mix_f32 v19, v46, v43, v19 op_sel:[0,1,0] op_sel_hi:[1,1,0]
	v_fma_mix_f32 v10, v20, v40, v16 op_sel:[0,0,0] op_sel_hi:[0,1,0]
	v_fma_mix_f32 v11, v20, v40, v17 op_sel:[0,1,0] op_sel_hi:[0,1,0]
	v_fma_mix_f32 v12, v20, v41, v18 op_sel:[0,0,0] op_sel_hi:[0,1,0]
	v_fma_mix_f32 v13, v20, v41, v19 op_sel:[0,1,0] op_sel_hi:[0,1,0]
	s_waitcnt lgkmcnt(0)
	v_add_u32_e32 v6, 0x4000, v6
	v_add_u32_e32 v7, 0x4000, v7
	v_and_b32_e32 v6, 0x1ffff, v6
	v_and_b32_e32 v7, 0x1ffff, v7
	ds_read_b64 v[24:25], v6 offset:16
	ds_read_b128 v[26:29], v6 offset:272
	ds_read_b128 v[30:33], v6 offset:528
	ds_read_u16 v34, v7 offset:16
	v_fma_mix_f32 v14, v10, v74, 0 op_sel:[0,0,0] op_sel_hi:[0,1,0]
	v_fma_mix_f32 v61, v10, v44, 0 op_sel:[0,0,0] op_sel_hi:[0,1,0]
	v_fma_mix_f32 v14, v11, v74, v14 op_sel:[0,1,0] op_sel_hi:[0,1,0]
	v_fma_mix_f32 v61, v11, v44, v61 op_sel:[0,1,0] op_sel_hi:[0,1,0]
	v_fma_mix_f32 v14, v12, v75, v14 op_sel:[0,0,0] op_sel_hi:[0,1,0]
	v_fma_mix_f32 v61, v12, v45, v61 op_sel:[0,0,0] op_sel_hi:[0,1,0]
	v_fma_mix_f32 v14, v13, v75, v14 op_sel:[0,1,0] op_sel_hi:[0,1,0]
	v_fma_mix_f32 v16, v10, v72, 0 op_sel:[0,0,0] op_sel_hi:[0,1,0]
	v_fma_mix_f32 v17, v11, v72, 0 op_sel:[0,1,0] op_sel_hi:[0,1,0]
	v_add_f32_dpp v20, v14, v14 quad_perm:[1,0,3,2] row_mask:0xf bank_mask:0xf bound_ctrl:1
	v_fma_mix_f32 v61, v13, v45, v61 op_sel:[0,1,0] op_sel_hi:[0,1,0]
	v_fma_mix_f32 v18, v12, v73, 0 op_sel:[0,0,0] op_sel_hi:[0,1,0]
	v_add_f32_dpp v20, v20, v20 quad_perm:[2,3,0,1] row_mask:0xf bank_mask:0xf bound_ctrl:1
	v_fma_mix_f32 v19, v13, v73, 0 op_sel:[0,1,0] op_sel_hi:[0,1,0]
	v_fma_mix_f32 v16, v82, v78, v16 op_sel:[0,0,0] op_sel_hi:[1,1,0]
	v_add_f32_dpp v20, v20, v20 row_half_mirror row_mask:0xf bank_mask:0xf bound_ctrl:1
	v_fma_mix_f32 v17, v82, v78, v17 op_sel:[0,1,0] op_sel_hi:[1,1,0]
	v_fma_mix_f32 v18, v82, v79, v18 op_sel:[0,0,0] op_sel_hi:[1,1,0]
	v_add_f32_dpp v20, v20, v20 row_mirror row_mask:0xf bank_mask:0xf bound_ctrl:1
	v_fma_mix_f32 v19, v82, v79, v19 op_sel:[0,1,0] op_sel_hi:[1,1,0]
	v_fma_mix_f32 v10, v20, v76, v16 op_sel:[0,0,0] op_sel_hi:[0,1,0]
	v_fma_mix_f32 v11, v20, v76, v17 op_sel:[0,1,0] op_sel_hi:[0,1,0]
	v_fma_mix_f32 v12, v20, v77, v18 op_sel:[0,0,0] op_sel_hi:[0,1,0]
	v_fma_mix_f32 v13, v20, v77, v19 op_sel:[0,1,0] op_sel_hi:[0,1,0]
	ds_read_b64 v[36:37], v6 offset:1040
	ds_read_b128 v[38:41], v6 offset:1296
	ds_read_b128 v[42:45], v6 offset:1552
	ds_read_u16 v46, v7 offset:1040
	v_fma_mix_f32 v14, v10, v86, 0 op_sel:[0,0,0] op_sel_hi:[0,1,0]
	v_fma_mix_f32 v62, v10, v80, 0 op_sel:[0,0,0] op_sel_hi:[0,1,0]
	v_fma_mix_f32 v14, v11, v86, v14 op_sel:[0,1,0] op_sel_hi:[0,1,0]
	v_fma_mix_f32 v62, v11, v80, v62 op_sel:[0,1,0] op_sel_hi:[0,1,0]
	v_fma_mix_f32 v14, v12, v87, v14 op_sel:[0,0,0] op_sel_hi:[0,1,0]
	v_fma_mix_f32 v62, v12, v81, v62 op_sel:[0,0,0] op_sel_hi:[0,1,0]
	v_fma_mix_f32 v14, v13, v87, v14 op_sel:[0,1,0] op_sel_hi:[0,1,0]
	v_fma_mix_f32 v16, v10, v84, 0 op_sel:[0,0,0] op_sel_hi:[0,1,0]
	v_fma_mix_f32 v17, v11, v84, 0 op_sel:[0,1,0] op_sel_hi:[0,1,0]
	v_add_f32_dpp v20, v14, v14 quad_perm:[1,0,3,2] row_mask:0xf bank_mask:0xf bound_ctrl:1
	v_fma_mix_f32 v62, v13, v81, v62 op_sel:[0,1,0] op_sel_hi:[0,1,0]
	v_fma_mix_f32 v18, v12, v85, 0 op_sel:[0,0,0] op_sel_hi:[0,1,0]
	v_add_f32_dpp v20, v20, v20 quad_perm:[2,3,0,1] row_mask:0xf bank_mask:0xf bound_ctrl:1
	v_fma_mix_f32 v19, v13, v85, 0 op_sel:[0,1,0] op_sel_hi:[0,1,0]
	v_fma_mix_f32 v16, v94, v90, v16 op_sel:[0,0,0] op_sel_hi:[1,1,0]
	v_add_f32_dpp v20, v20, v20 row_half_mirror row_mask:0xf bank_mask:0xf bound_ctrl:1
	v_fma_mix_f32 v17, v94, v90, v17 op_sel:[0,1,0] op_sel_hi:[1,1,0]
	v_fma_mix_f32 v18, v94, v91, v18 op_sel:[0,0,0] op_sel_hi:[1,1,0]
	v_add_f32_dpp v20, v20, v20 row_mirror row_mask:0xf bank_mask:0xf bound_ctrl:1
	v_fma_mix_f32 v19, v94, v91, v19 op_sel:[0,1,0] op_sel_hi:[1,1,0]
	v_fma_mix_f32 v10, v20, v88, v16 op_sel:[0,0,0] op_sel_hi:[0,1,0]
	v_fma_mix_f32 v11, v20, v88, v17 op_sel:[0,1,0] op_sel_hi:[0,1,0]
	v_fma_mix_f32 v12, v20, v89, v18 op_sel:[0,0,0] op_sel_hi:[0,1,0]
	v_fma_mix_f32 v13, v20, v89, v19 op_sel:[0,1,0] op_sel_hi:[0,1,0]
	s_waitcnt lgkmcnt(0)
	s_add_u32 s43, s43, 1

; DEVINL u16 f2bf(float a) { return (u16)(pk2(a, 0.f) & 0xffffu); }
; #define RW_STEP2(B) RW_STEP(B, WvA, XA, KrA, vhA, WvB, XB, KrB, vhB); RW_STEP((B) + 1, WvB, XB, KrB, vhB, WvA, XA, KrA, vhA)
; #define RW_STEP4(B) RW_STEP2(B); RW_STEP2((B) + 2)
; template <int DIR>
; DEVINL void rwkv_scan_dir(const Params& p, int task, int lane, int wave) {
;     ...
;   for (int st = 0; st < 4096; st += 32) {
;     RW_STEP(0, WvA, XA, KrA, vhA, WvB, XB, KrB, vhB);
;     if (st > 0) { const int q0 = st - 16 + seg; yo[(long)(DIR ? (4095 - q0) : q0) * 1024] = f2bf(ykeep); }
;     RW_STEP(1, WvB, XB, KrB, vhB, WvA, XA, KrA, vhA);
;     RW_STEP2(2); RW_STEP4(4); RW_STEP4(8); RW_STEP4(12);
.Lrw_ready_d0:
	s_add_u32 m0, s41, 16
	s_nop 0
	global_load_lds_dwordx4 v5, s[10:11] offset:0
	global_load_lds_dwordx4 v5, s[10:11] offset:1024
	global_load_lds_dwordx4 v5, s[10:11] offset:2048
	global_load_lds_dwordx4 v5, s[10:11] offset:3072
	s_add_u32 s10, s10, 0x4000
	s_addc_u32 s11, s11, 0
	s_add_u32 s41, s41, 0x4000
	s_and_b32 s41, s41, 0x1ffff
	ds_read_b64 v[72:73], v6 offset:2064
	ds_read_b128 v[74:77], v6 offset:2320
	ds_read_b128 v[78:81], v6 offset:2576
	ds_read_u16 v82, v7 offset:2064
	v_fma_mix_f32 v14, v10, v26, 0 op_sel:[0,0,0] op_sel_hi:[0,1,0]
	v_fma_mix_f32 v63, v10, v92, 0 op_sel:[0,0,0] op_sel_hi:[0,1,0]
	v_fma_mix_f32 v14, v11, v26, v14 op_sel:[0,1,0] op_sel_hi:[0,1,0]
	v_fma_mix_f32 v63, v11, v92, v63 op_sel:[0,1,0] op_sel_hi:[0,1,0]
	v_fma_mix_f32 v14, v12, v27, v14 op_sel:[0,0,0] op_sel_hi:[0,1,0]
	v_fma_mix_f32 v63, v12, v93, v63 op_sel:[0,0,0] op_sel_hi:[0,1,0]
	v_fma_mix_f32 v14, v13, v27, v14 op_sel:[0,1,0] op_sel_hi:[0,1,0]
	v_fma_mix_f32 v16, v10, v24, 0 op_sel:[0,0,0] op_sel_hi:[0,1,0]
	v_fma_mix_f32 v17, v11, v24, 0 op_sel:[0,1,0] op_sel_hi:[0,1,0]
	v_add_f32_dpp v20, v14, v14 quad_perm:[1,0,3,2] row_mask:0xf bank_mask:0xf bound_ctrl:1
	v_fma_mix_f32 v63, v13, v93, v63 op_sel:[0,1,0] op_sel_hi:[0,1,0]
	v_fma_mix_f32 v18, v12, v25, 0 op_sel:[0,0,0] op_sel_hi:[0,1,0]
	v_add_f32_dpp v20, v20, v20 quad_perm:[2,3,0,1] row_mask:0xf bank_mask:0xf bound_ctrl:1
	v_fma_mix_f32 v19, v13, v25, 0 op_sel:[0,1,0] op_sel_hi:[0,1,0]
	v_fma_mix_f32 v16, v34, v30, v16 op_sel:[0,0,0] op_sel_hi:[1,1,0]
	v_add_f32_dpp v20, v20, v20 row_half_mirror row_mask:0xf bank_mask:0xf bound_ctrl:1
	v_fma_mix_f32 v17, v34, v30, v17 op_sel:[0,1,0] op_sel_hi:[1,1,0]
	v_fma_mix_f32 v18, v34, v31, v18 op_sel:[0,0,0] op_sel_hi:[1,1,0]
	v_add_f32_dpp v20, v20, v20 row_mirror row_mask:0xf bank_mask:0xf bound_ctrl:1
	v_fma_mix_f32 v19, v34, v31, v19 op_sel:[0,1,0] op_sel_hi:[1,1,0]
	v_fma_mix_f32 v10, v20, v28, v16 op_sel:[0,0,0] op_sel_hi:[0,1,0]
	v_fma_mix_f32 v11, v20, v28, v17 op_sel:[0,1,0] op_sel_hi:[0,1,0]
	v_fma_mix_f32 v12, v20, v29, v18 op_sel:[0,0,0] op_sel_hi:[0,1,0]
	v_fma_mix_f32 v13, v20, v29, v19 op_sel:[0,1,0] op_sel_hi:[0,1,0]
	v_add_f32_dpp v48, v48, v48 row_ror:8 row_mask:0xf bank_mask:0x3
	v_add_f32_dpp v49, v49, v49 row_ror:8 row_mask:0xf bank_mask:0x3
	v_add_f32_dpp v50, v50, v50 row_ror:8 row_mask:0xf bank_mask:0x3
	v_add_f32_dpp v51, v51, v51 row_ror:8 row_mask:0xf bank_mask:0x3
	v_add_f32_dpp v52, v52, v52 row_ror:8 row_mask:0xf bank_mask:0x3
	v_add_f32_dpp v53, v53, v53 row_ror:8 row_mask:0xf bank_mask:0x3
	v_add_f32_dpp v54, v54, v54 row_ror:8 row_mask:0xf bank_mask:0x3
	v_add_f32_dpp v55, v55, v55 row_ror:8 row_mask:0xf bank_mask:0x3
	v_add_f32_dpp v48, v56, v56 row_ror:8 row_mask:0xf bank_mask:0xc
	v_add_f32_dpp v49, v57, v57 row_ror:8 row_mask:0xf bank_mask:0xc
	v_add_f32_dpp v50, v58, v58 row_ror:8 row_mask:0xf bank_mask:0xc
	v_add_f32_dpp v51, v59, v59 row_ror:8 row_mask:0xf bank_mask:0xc
	v_add_f32_dpp v52, v60, v60 row_ror:8 row_mask:0xf bank_mask:0xc
	v_add_f32_dpp v53, v61, v61 row_ror:8 row_mask:0xf bank_mask:0xc
	v_add_f32_dpp v54, v62, v62 row_ror:8 row_mask:0xf bank_mask:0xc
	v_add_f32_dpp v55, v63, v63 row_ror:8 row_mask:0xf bank_mask:0xc
	v_add_f32_dpp v48, v48, v48 row_ror:12 row_mask:0xf bank_mask:0x5
	v_add_f32_dpp v49, v49, v49 row_ror:12 row_mask:0xf bank_mask:0x5
	v_add_f32_dpp v50, v50, v50 row_ror:12 row_mask:0xf bank_mask:0x5
	v_add_f32_dpp v51, v51, v51 row_ror:12 row_mask:0xf bank_mask:0x5
	v_add_f32_dpp v48, v52, v52 row_ror:4 row_mask:0xf bank_mask:0xa
	v_add_f32_dpp v49, v53, v53 row_ror:4 row_mask:0xf bank_mask:0xa
	v_add_f32_dpp v50, v54, v54 row_ror:4 row_mask:0xf bank_mask:0xa
	v_add_f32_dpp v51, v55, v55 row_ror:4 row_mask:0xf bank_mask:0xa
	v_add_f32_dpp v64, v48, v48 quad_perm:[2,3,0,1] row_mask:0xf bank_mask:0xf bound_ctrl:1
	v_add_f32_dpp v65, v50, v50 quad_perm:[2,3,0,1] row_mask:0xf bank_mask:0xf bound_ctrl:1
	v_cndmask_b32_e64 v56, v64, v65, s[50:51]
	v_add_f32_dpp v64, v49, v49 quad_perm:[2,3,0,1] row_mask:0xf bank_mask:0xf bound_ctrl:1
	v_add_f32_dpp v65, v51, v51 quad_perm:[2,3,0,1] row_mask:0xf bank_mask:0xf bound_ctrl:1
	v_cndmask_b32_e64 v57, v64, v65, s[50:51]
	v_add_f32_dpp v64, v56, v56 quad_perm:[1,0,3,2] row_mask:0xf bank_mask:0xf bound_ctrl:1
	s_nop 0
	v_add_f32_dpp v65, v57, v57 quad_perm:[1,0,3,2] row_mask:0xf bank_mask:0xf bound_ctrl:1
	v_cndmask_b32_e64 v66, v64, v65, s[48:49]
	v_cvt_pk_bf16_f32 v66, v66, v66
	global_store_short v8, v66, s[12:13]
	s_add_u32 s12, s12, 0x8000
	s_addc_u32 s13, s13, 0
	ds_read_b64 v[84:85], v6 offset:3088
	ds_read_b128 v[86:89], v6 offset:3344
	ds_read_b128 v[90:93], v6 offset:3600
	ds_read_u16 v94, v7 offset:3088
	v_fma_mix_f32 v14, v10, v38, 0 op_sel:[0,0,0] op_sel_hi:[0,1,0]
	v_fma_mix_f32 v48, v10, v32, 0 op_sel:[0,0,0] op_sel_hi:[0,1,0]
	v_fma_mix_f32 v14, v11, v38, v14 op_sel:[0,1,0] op_sel_hi:[0,1,0]
	v_fma_mix_f32 v48, v11, v32, v48 op_sel:[0,1,0] op_sel_hi:[0,1,0]
	v_fma_mix_f32 v14, v12, v39, v14 op_sel:[0,0,0] op_sel_hi:[0,1,0]
	v_fma_mix_f32 v48, v12, v33, v48 op_sel:[0,0,0] op_sel_hi:[0,1,0]
	v_fma_mix_f32 v14, v13, v39, v14 op_sel:[0,1,0] op_sel_hi:[0,1,0]
	v_fma_mix_f32 v16, v10, v36, 0 op_sel:[0,0,0] op_sel_hi:[0,1,0]
	v_fma_mix_f32 v17, v11, v36, 0 op_sel:[0,1,0] op_sel_hi:[0,1,0]
	v_add_f32_dpp v20, v14, v14 quad_perm:[1,0,3,2] row_mask:0xf bank_mask:0xf bound_ctrl:1
	v_fma_mix_f32 v48, v13, v33, v48 op_sel:[0,1,0] op_sel_hi:[0,1,0]
	v_fma_mix_f32 v18, v12, v37, 0 op_sel:[0,0,0] op_sel_hi:[0,1,0]
	v_add_f32_dpp v20, v20, v20 quad_perm:[2,3,0,1] row_mask:0xf bank_mask:0xf bound_ctrl:1
	v_fma_mix_f32 v19, v13, v37, 0 op_sel:[0,1,0] op_sel_hi:[0,1,0]
	v_fma_mix_f32 v16, v46, v42, v16 op_sel:[0,0,0] op_sel_hi:[1,1,0]
	v_add_f32_dpp v20, v20, v20 row_half_mirror row_mask:0xf bank_mask:0xf bound_ctrl:1
	v_fma_mix_f32 v17, v46, v42, v17 op_sel:[0,1,0] op_sel_hi:[1,1,0]
	v_fma_mix_f32 v18, v46, v43, v18 op_sel:[0,0,0] op_sel_hi:[1,1,0]
	v_add_f32_dpp v20, v20, v20 row_mirror row_mask:0xf bank_mask:0xf bound_ctrl:1
	v_fma_mix_f32 v19, v46, v43, v19 op_sel:[0,1,0] op_sel_hi:[1,1,0]
	v_fma_mix_f32 v10, v20, v40, v16 op_sel:[0,0,0] op_sel_hi:[0,1,0]
	v_fma_mix_f32 v11, v20, v40, v17 op_sel:[0,1,0] op_sel_hi:[0,1,0]
	v_fma_mix_f32 v12, v20, v41, v18 op_sel:[0,0,0] op_sel_hi:[0,1,0]
	v_fma_mix_f32 v13, v20, v41, v19 op_sel:[0,1,0] op_sel_hi:[0,1,0]
	s_waitcnt lgkmcnt(0)
	ds_read_b64 v[24:25], v6 offset:4112
	ds_read_b128 v[26:29], v6 offset:4368
	ds_read_b128 v[30:33], v6 offset:4624
	ds_read_u16 v34, v7 offset:4112
	v_fma_mix_f32 v14, v10, v74, 0 op_sel:[0,0,0] op_sel_hi:[0,1,0]
	v_fma_mix_f32 v49, v10, v44, 0 op_sel:[0,0,0] op_sel_hi:[0,1,0]
	v_fma_mix_f32 v14, v11, v74, v14 op_sel:[0,1,0] op_sel_hi:[0,1,0]
	v_fma_mix_f32 v49, v11, v44, v49 op_sel:[0,1,0] op_sel_hi:[0,1,0]
	v_fma_mix_f32 v14, v12, v75, v14 op_sel:[0,0,0] op_sel_hi:[0,1,0]
	v_fma_mix_f32 v49, v12, v45, v49 op_sel:[0,0,0] op_sel_hi:[0,1,0]
	v_fma_mix_f32 v14, v13, v75, v14 op_sel:[0,1,0] op_sel_hi:[0,1,0]
	v_fma_mix_f32 v16, v10, v72, 0 op_sel:[0,0,0] op_sel_hi:[0,1,0]
	v_fma_mix_f32 v17, v11, v72, 0 op_sel:[0,1,0] op_sel_hi:[0,1,0]
	v_add_f32_dpp v20, v14, v14 quad_perm:[1,0,3,2] row_mask:0xf bank_mask:0xf bound_ctrl:1
	v_fma_mix_f32 v49, v13, v45, v49 op_sel:[0,1,0] op_sel_hi:[0,1,0]
	v_fma_mix_f32 v18, v12, v73, 0 op_sel:[0,0,0] op_sel_hi:[0,1,0]
	v_add_f32_dpp v20, v20, v20 quad_perm:[2,3,0,1] row_mask:0xf bank_mask:0xf bound_ctrl:1
	v_fma_mix_f32 v19, v13, v73, 0 op_sel:[0,1,0] op_sel_hi:[0,1,0]
	v_fma_mix_f32 v16, v82, v78, v16 op_sel:[0,0,0] op_sel_hi:[1,1,0]
	v_add_f32_dpp v20, v20, v20 row_half_mirror row_mask:0xf bank_mask:0xf bound_ctrl:1
	v_fma_mix_f32 v17, v82, v78, v17 op_sel:[0,1,0] op_sel_hi:[1,1,0]
	v_fma_mix_f32 v18, v82, v79, v18 op_sel:[0,0,0] op_sel_hi:[1,1,0]
	v_add_f32_dpp v20, v20, v20 row_mirror row_mask:0xf bank_mask:0xf bound_ctrl:1
	v_fma_mix_f32 v19, v82, v79, v19 op_sel:[0,1,0] op_sel_hi:[1,1,0]
	v_fma_mix_f32 v10, v20, v76, v16 op_sel:[0,0,0] op_sel_hi:[0,1,0]
	v_fma_mix_f32 v11, v20, v76, v17 op_sel:[0,1,0] op_sel_hi:[0,1,0]
	v_fma_mix_f32 v12, v20, v77, v18 op_sel:[0,0,0] op_sel_hi:[0,1,0]
	v_fma_mix_f32 v13, v20, v77, v19 op_sel:[0,1,0] op_sel_hi:[0,1,0]
	ds_read_b64 v[36:37], v6 offset:5136
	ds_read_b128 v[38:41], v6 offset:5392
	ds_read_b128 v[42:45], v6 offset:5648
	ds_read_u16 v46, v7 offset:5136
	v_fma_mix_f32 v14, v10, v86, 0 op_sel:[0,0,0] op_sel_hi:[0,1,0]
	v_fma_mix_f32 v50, v10, v80, 0 op_sel:[0,0,0] op_sel_hi:[0,1,0]
	v_fma_mix_f32 v14, v11, v86, v14 op_sel:[0,1,0] op_sel_hi:[0,1,0]
	v_fma_mix_f32 v50, v11, v80, v50 op_sel:[0,1,0] op_sel_hi:[0,1,0]
	v_fma_mix_f32 v14, v12, v87, v14 op_sel:[0,0,0] op_sel_hi:[0,1,0]
	v_fma_mix_f32 v50, v12, v81, v50 op_sel:[0,0,0] op_sel_hi:[0,1,0]
	v_fma_mix_f32 v14, v13, v87, v14 op_sel:[0,1,0] op_sel_hi:[0,1,0]
	v_fma_mix_f32 v16, v10, v84, 0 op_sel:[0,0,0] op_sel_hi:[0,1,0]
	v_fma_mix_f32 v17, v11, v84, 0 op_sel:[0,1,0] op_sel_hi:[0,1,0]
	v_add_f32_dpp v20, v14, v14 quad_perm:[1,0,3,2] row_mask:0xf bank_mask:0xf bound_ctrl:1
	v_fma_mix_f32 v50, v13, v81, v50 op_sel:[0,1,0] op_sel_hi:[0,1,0]
	v_fma_mix_f32 v18, v12, v85, 0 op_sel:[0,0,0] op_sel_hi:[0,1,0]
	v_add_f32_dpp v20, v20, v20 quad_perm:[2,3,0,1] row_mask:0xf bank_mask:0xf bound_ctrl:1
	v_fma_mix_f32 v19, v13, v85, 0 op_sel:[0,1,0] op_sel_hi:[0,1,0]
	v_fma_mix_f32 v16, v94, v90, v16 op_sel:[0,0,0] op_sel_hi:[1,1,0]
	v_add_f32_dpp v20, v20, v20 row_half_mirror row_mask:0xf bank_mask:0xf bound_ctrl:1
	v_fma_mix_f32 v17, v94, v90, v17 op_sel:[0,1,0] op_sel_hi:[1,1,0]
	v_fma_mix_f32 v18, v94, v91, v18 op_sel:[0,0,0] op_sel_hi:[1,1,0]
	v_add_f32_dpp v20, v20, v20 row_mirror row_mask:0xf bank_mask:0xf bound_ctrl:1
	v_fma_mix_f32 v19, v94, v91, v19 op_sel:[0,1,0] op_sel_hi:[1,1,0]
	v_fma_mix_f32 v10, v20, v88, v16 op_sel:[0,0,0] op_sel_hi:[0,1,0]
	v_fma_mix_f32 v11, v20, v88, v17 op_sel:[0,1,0] op_sel_hi:[0,1,0]
	v_fma_mix_f32 v12, v20, v89, v18 op_sel:[0,0,0] op_sel_hi:[0,1,0]
	v_fma_mix_f32 v13, v20, v89, v19 op_sel:[0,1,0] op_sel_hi:[0,1,0]
	s_waitcnt lgkmcnt(0)
	ds_read_b64 v[72:73], v6 offset:6160
	ds_read_b128 v[74:77], v6 offset:6416
	ds_read_b128 v[78:81], v6 offset:6672
	ds_read_u16 v82, v7 offset:6160
	v_fma_mix_f32 v14, v10, v26, 0 op_sel:[0,0,0] op_sel_hi:[0,1,0]
	v_fma_mix_f32 v51, v10, v92, 0 op_sel:[0,0,0] op_sel_hi:[0,1,0]
	v_fma_mix_f32 v14, v11, v26, v14 op_sel:[0,1,0] op_sel_hi:[0,1,0]
	v_fma_mix_f32 v51, v11, v92, v51 op_sel:[0,1,0] op_sel_hi:[0,1,0]
	v_fma_mix_f32 v14, v12, v27, v14 op_sel:[0,0,0] op_sel_hi:[0,1,0]
	v_fma_mix_f32 v51, v12, v93, v51 op_sel:[0,0,0] op_sel_hi:[0,1,0]
	v_fma_mix_f32 v14, v13, v27, v14 op_sel:[0,1,0] op_sel_hi:[0,1,0]
	v_fma_mix_f32 v16, v10, v24, 0 op_sel:[0,0,0] op_sel_hi:[0,1,0]
	v_fma_mix_f32 v17, v11, v24, 0 op_sel:[0,1,0] op_sel_hi:[0,1,0]
	v_add_f32_dpp v20, v14, v14 quad_perm:[1,0,3,2] row_mask:0xf bank_mask:0xf bound_ctrl:1
	v_fma_mix_f32 v51, v13, v93, v51 op_sel:[0,1,0] op_sel_hi:[0,1,0]
	v_fma_mix_f32 v18, v12, v25, 0 op_sel:[0,0,0] op_sel_hi:[0,1,0]
	v_add_f32_dpp v20, v20, v20 quad_perm:[2,3,0,1] row_mask:0xf bank_mask:0xf bound_ctrl:1
	v_fma_mix_f32 v19, v13, v25, 0 op_sel:[0,1,0] op_sel_hi:[0,1,0]
	v_fma_mix_f32 v16, v34, v30, v16 op_sel:[0,0,0] op_sel_hi:[1,1,0]
	v_add_f32_dpp v20, v20, v20 row_half_mirror row_mask:0xf bank_mask:0xf bound_ctrl:1
	v_fma_mix_f32 v17, v34, v30, v17 op_sel:[0,1,0] op_sel_hi:[1,1,0]
	v_fma_mix_f32 v18, v34, v31, v18 op_sel:[0,0,0] op_sel_hi:[1,1,0]
	v_add_f32_dpp v20, v20, v20 row_mirror row_mask:0xf bank_mask:0xf bound_ctrl:1
	v_fma_mix_f32 v19, v34, v31, v19 op_sel:[0,1,0] op_sel_hi:[1,1,0]
	v_fma_mix_f32 v10, v20, v28, v16 op_sel:[0,0,0] op_sel_hi:[0,1,0]
	v_fma_mix_f32 v11, v20, v28, v17 op_sel:[0,1,0] op_sel_hi:[0,1,0]
	v_fma_mix_f32 v12, v20, v29, v18 op_sel:[0,0,0] op_sel_hi:[0,1,0]
	v_fma_mix_f32 v13, v20, v29, v19 op_sel:[0,1,0] op_sel_hi:[0,1,0]
	ds_read_b64 v[84:85], v6 offset:7184
	ds_read_b128 v[86:89], v6 offset:7440
	ds_read_b128 v[90:93], v6 offset:7696
	ds_read_u16 v94, v7 offset:7184
	v_fma_mix_f32 v14, v10, v38, 0 op_sel:[0,0,0] op_sel_hi:[0,1,0]
	v_fma_mix_f32 v52, v10, v32, 0 op_sel:[0,0,0] op_sel_hi:[0,1,0]
	v_fma_mix_f32 v14, v11, v38, v14 op_sel:[0,1,0] op_sel_hi:[0,1,0]
	v_fma_mix_f32 v52, v11, v32, v52 op_sel:[0,1,0] op_sel_hi:[0,1,0]
	v_fma_mix_f32 v14, v12, v39, v14 op_sel:[0,0,0] op_sel_hi:[0,1,0]
	v_fma_mix_f32 v52, v12, v33, v52 op_sel:[0,0,0] op_sel_hi:[0,1,0]
	v_fma_mix_f32 v14, v13, v39, v14 op_sel:[0,1,0] op_sel_hi:[0,1,0]
	v_fma_mix_f32 v16, v10, v36, 0 op_sel:[0,0,0] op_sel_hi:[0,1,0]
	v_fma_mix_f32 v17, v11, v36, 0 op_sel:[0,1,0] op_sel_hi:[0,1,0]
	v_add_f32_dpp v20, v14, v14 quad_perm:[1,0,3,2] row_mask:0xf bank_mask:0xf bound_ctrl:1
	v_fma_mix_f32 v52, v13, v33, v52 op_sel:[0,1,0] op_sel_hi:[0,1,0]
	v_fma_mix_f32 v18, v12, v37, 0 op_sel:[0,0,0] op_sel_hi:[0,1,0]
	v_add_f32_dpp v20, v20, v20 quad_perm:[2,3,0,1] row_mask:0xf bank_mask:0xf bound_ctrl:1
	v_fma_mix_f32 v19, v13, v37, 0 op_sel:[0,1,0] op_sel_hi:[0,1,0]
	v_fma_mix_f32 v16, v46, v42, v16 op_sel:[0,0,0] op_sel_hi:[1,1,0]
	v_add_f32_dpp v20, v20, v20 row_half_mirror row_mask:0xf bank_mask:0xf bound_ctrl:1
	v_fma_mix_f32 v17, v46, v42, v17 op_sel:[0,1,0] op_sel_hi:[1,1,0]
	v_fma_mix_f32 v18, v46, v43, v18 op_sel:[0,0,0] op_sel_hi:[1,1,0]
	v_add_f32_dpp v20, v20, v20 row_mirror row_mask:0xf bank_mask:0xf bound_ctrl:1
	v_fma_mix_f32 v19, v46, v43, v19 op_sel:[0,1,0] op_sel_hi:[1,1,0]
	v_fma_mix_f32 v10, v20, v40, v16 op_sel:[0,0,0] op_sel_hi:[0,1,0]
	v_fma_mix_f32 v11, v20, v40, v17 op_sel:[0,1,0] op_sel_hi:[0,1,0]
	v_fma_mix_f32 v12, v20, v41, v18 op_sel:[0,0,0] op_sel_hi:[0,1,0]
	v_fma_mix_f32 v13, v20, v41, v19 op_sel:[0,1,0] op_sel_hi:[0,1,0]
	s_waitcnt lgkmcnt(0)
	ds_read_b64 v[24:25], v6 offset:8208
	ds_read_b128 v[26:29], v6 offset:8464
	ds_read_b128 v[30:33], v6 offset:8720
	ds_read_u16 v34, v7 offset:8208
	v_fma_mix_f32 v14, v10, v74, 0 op_sel:[0,0,0] op_sel_hi:[0,1,0]
	v_fma_mix_f32 v53, v10, v44, 0 op_sel:[0,0,0] op_sel_hi:[0,1,0]
	v_fma_mix_f32 v14, v11, v74, v14 op_sel:[0,1,0] op_sel_hi:[0,1,0]
	v_fma_mix_f32 v53, v11, v44, v53 op_sel:[0,1,0] op_sel_hi:[0,1,0]
	v_fma_mix_f32 v14, v12, v75, v14 op_sel:[0,0,0] op_sel_hi:[0,1,0]
	v_fma_mix_f32 v53, v12, v45, v53 op_sel:[0,0,0] op_sel_hi:[0,1,0]
	v_fma_mix_f32 v14, v13, v75, v14 op_sel:[0,1,0] op_sel_hi:[0,1,0]
	v_fma_mix_f32 v16, v10, v72, 0 op_sel:[0,0,0] op_sel_hi:[0,1,0]
	v_fma_mix_f32 v17, v11, v72, 0 op_sel:[0,1,0] op_sel_hi:[0,1,0]
	v_add_f32_dpp v20, v14, v14 quad_perm:[1,0,3,2] row_mask:0xf bank_mask:0xf bound_ctrl:1
	v_fma_mix_f32 v53, v13, v45, v53 op_sel:[0,1,0] op_sel_hi:[0,1,0]
	v_fma_mix_f32 v18, v12, v73, 0 op_sel:[0,0,0] op_sel_hi:[0,1,0]
	v_add_f32_dpp v20, v20, v20 quad_perm:[2,3,0,1] row_mask:0xf bank_mask:0xf bound_ctrl:1
	v_fma_mix_f32 v19, v13, v73, 0 op_sel:[0,1,0] op_sel_hi:[0,1,0]
	v_fma_mix_f32 v16, v82, v78, v16 op_sel:[0,0,0] op_sel_hi:[1,1,0]
	v_add_f32_dpp v20, v20, v20 row_half_mirror row_mask:0xf bank_mask:0xf bound_ctrl:1
	v_fma_mix_f32 v17, v82, v78, v17 op_sel:[0,1,0] op_sel_hi:[1,1,0]
	v_fma_mix_f32 v18, v82, v79, v18 op_sel:[0,0,0] op_sel_hi:[1,1,0]
	v_add_f32_dpp v20, v20, v20 row_mirror row_mask:0xf bank_mask:0xf bound_ctrl:1
	v_fma_mix_f32 v19, v82, v79, v19 op_sel:[0,1,0] op_sel_hi:[1,1,0]
	v_fma_mix_f32 v10, v20, v76, v16 op_sel:[0,0,0] op_sel_hi:[0,1,0]
	v_fma_mix_f32 v11, v20, v76, v17 op_sel:[0,1,0] op_sel_hi:[0,1,0]
	v_fma_mix_f32 v12, v20, v77, v18 op_sel:[0,0,0] op_sel_hi:[0,1,0]
	v_fma_mix_f32 v13, v20, v77, v19 op_sel:[0,1,0] op_sel_hi:[0,1,0]
	ds_read_b64 v[36:37], v6 offset:9232
	ds_read_b128 v[38:41], v6 offset:9488
	ds_read_b128 v[42:45], v6 offset:9744
	ds_read_u16 v46, v7 offset:9232
	v_fma_mix_f32 v14, v10, v86, 0 op_sel:[0,0,0] op_sel_hi:[0,1,0]
	v_fma_mix_f32 v54, v10, v80, 0 op_sel:[0,0,0] op_sel_hi:[0,1,0]
	v_fma_mix_f32 v14, v11, v86, v14 op_sel:[0,1,0] op_sel_hi:[0,1,0]
	v_fma_mix_f32 v54, v11, v80, v54 op_sel:[0,1,0] op_sel_hi:[0,1,0]
	v_fma_mix_f32 v14, v12, v87, v14 op_sel:[0,0,0] op_sel_hi:[0,1,0]
	v_fma_mix_f32 v54, v12, v81, v54 op_sel:[0,0,0] op_sel_hi:[0,1,0]
	v_fma_mix_f32 v14, v13, v87, v14 op_sel:[0,1,0] op_sel_hi:[0,1,0]
	v_fma_mix_f32 v16, v10, v84, 0 op_sel:[0,0,0] op_sel_hi:[0,1,0]
	v_fma_mix_f32 v17, v11, v84, 0 op_sel:[0,1,0] op_sel_hi:[0,1,0]
	v_add_f32_dpp v20, v14, v14 quad_perm:[1,0,3,2] row_mask:0xf bank_mask:0xf bound_ctrl:1
	v_fma_mix_f32 v54, v13, v81, v54 op_sel:[0,1,0] op_sel_hi:[0,1,0]
	v_fma_mix_f32 v18, v12, v85, 0 op_sel:[0,0,0] op_sel_hi:[0,1,0]
	v_add_f32_dpp v20, v20, v20 quad_perm:[2,3,0,1] row_mask:0xf bank_mask:0xf bound_ctrl:1
	v_fma_mix_f32 v19, v13, v85, 0 op_sel:[0,1,0] op_sel_hi:[0,1,0]
	v_fma_mix_f32 v16, v94, v90, v16 op_sel:[0,0,0] op_sel_hi:[1,1,0]
	v_add_f32_dpp v20, v20, v20 row_half_mirror row_mask:0xf bank_mask:0xf bound_ctrl:1
	v_fma_mix_f32 v17, v94, v90, v17 op_sel:[0,1,0] op_sel_hi:[1,1,0]
	v_fma_mix_f32 v18, v94, v91, v18 op_sel:[0,0,0] op_sel_hi:[1,1,0]
	v_add_f32_dpp v20, v20, v20 row_mirror row_mask:0xf bank_mask:0xf bound_ctrl:1
	v_fma_mix_f32 v19, v94, v91, v19 op_sel:[0,1,0] op_sel_hi:[1,1,0]
	v_fma_mix_f32 v10, v20, v88, v16 op_sel:[0,0,0] op_sel_hi:[0,1,0]
	v_fma_mix_f32 v11, v20, v88, v17 op_sel:[0,1,0] op_sel_hi:[0,1,0]
	v_fma_mix_f32 v12, v20, v89, v18 op_sel:[0,0,0] op_sel_hi:[0,1,0]
	v_fma_mix_f32 v13, v20, v89, v19 op_sel:[0,1,0] op_sel_hi:[0,1,0]
	s_waitcnt lgkmcnt(0)
	ds_read_b64 v[72:73], v6 offset:10256
	ds_read_b128 v[74:77], v6 offset:10512
	ds_read_b128 v[78:81], v6 offset:10768
	ds_read_u16 v82, v7 offset:10256
	v_fma_mix_f32 v14, v10, v26, 0 op_sel:[0,0,0] op_sel_hi:[0,1,0]
	v_fma_mix_f32 v55, v10, v92, 0 op_sel:[0,0,0] op_sel_hi:[0,1,0]
	v_fma_mix_f32 v14, v11, v26, v14 op_sel:[0,1,0] op_sel_hi:[0,1,0]
	v_fma_mix_f32 v55, v11, v92, v55 op_sel:[0,1,0] op_sel_hi:[0,1,0]
	v_fma_mix_f32 v14, v12, v27, v14 op_sel:[0,0,0] op_sel_hi:[0,1,0]
	v_fma_mix_f32 v55, v12, v93, v55 op_sel:[0,0,0] op_sel_hi:[0,1,0]
	v_fma_mix_f32 v14, v13, v27, v14 op_sel:[0,1,0] op_sel_hi:[0,1,0]
	v_fma_mix_f32 v16, v10, v24, 0 op_sel:[0,0,0] op_sel_hi:[0,1,0]
	v_fma_mix_f32 v17, v11, v24, 0 op_sel:[0,1,0] op_sel_hi:[0,1,0]
	v_add_f32_dpp v20, v14, v14 quad_perm:[1,0,3,2] row_mask:0xf bank_mask:0xf bound_ctrl:1
	v_fma_mix_f32 v55, v13, v93, v55 op_sel:[0,1,0] op_sel_hi:[0,1,0]
	v_fma_mix_f32 v18, v12, v25, 0 op_sel:[0,0,0] op_sel_hi:[0,1,0]
	v_add_f32_dpp v20, v20, v20 quad_perm:[2,3,0,1] row_mask:0xf bank_mask:0xf bound_ctrl:1
	v_fma_mix_f32 v19, v13, v25, 0 op_sel:[0,1,0] op_sel_hi:[0,1,0]
	v_fma_mix_f32 v16, v34, v30, v16 op_sel:[0,0,0] op_sel_hi:[1,1,0]
	v_add_f32_dpp v20, v20, v20 row_half_mirror row_mask:0xf bank_mask:0xf bound_ctrl:1
	v_fma_mix_f32 v17, v34, v30, v17 op_sel:[0,1,0] op_sel_hi:[1,1,0]
	v_fma_mix_f32 v18, v34, v31, v18 op_sel:[0,0,0] op_sel_hi:[1,1,0]
	v_add_f32_dpp v20, v20, v20 row_mirror row_mask:0xf bank_mask:0xf bound_ctrl:1
	v_fma_mix_f32 v19, v34, v31, v19 op_sel:[0,1,0] op_sel_hi:[1,1,0]
	v_fma_mix_f32 v10, v20, v28, v16 op_sel:[0,0,0] op_sel_hi:[0,1,0]
	v_fma_mix_f32 v11, v20, v28, v17 op_sel:[0,1,0] op_sel_hi:[0,1,0]
	v_fma_mix_f32 v12, v20, v29, v18 op_sel:[0,0,0] op_sel_hi:[0,1,0]
	v_fma_mix_f32 v13, v20, v29, v19 op_sel:[0,1,0] op_sel_hi:[0,1,0]
	ds_read_b64 v[84:85], v6 offset:11280
	ds_read_b128 v[86:89], v6 offset:11536
	ds_read_b128 v[90:93], v6 offset:11792
	ds_read_u16 v94, v7 offset:11280
	v_fma_mix_f32 v14, v10, v38, 0 op_sel:[0,0,0] op_sel_hi:[0,1,0]
	v_fma_mix_f32 v56, v10, v32, 0 op_sel:[0,0,0] op_sel_hi:[0,1,0]
	v_fma_mix_f32 v14, v11, v38, v14 op_sel:[0,1,0] op_sel_hi:[0,1,0]
	v_fma_mix_f32 v56, v11, v32, v56 op_sel:[0,1,0] op_sel_hi:[0,1,0]
	v_fma_mix_f32 v14, v12, v39, v14 op_sel:[0,0,0] op_sel_hi:[0,1,0]
	v_fma_mix_f32 v56, v12, v33, v56 op_sel:[0,0,0] op_sel_hi:[0,1,0]
	v_fma_mix_f32 v14, v13, v39, v14 op_sel:[0,1,0] op_sel_hi:[0,1,0]
	v_fma_mix_f32 v16, v10, v36, 0 op_sel:[0,0,0] op_sel_hi:[0,1,0]
	v_fma_mix_f32 v17, v11, v36, 0 op_sel:[0,1,0] op_sel_hi:[0,1,0]
	v_add_f32_dpp v20, v14, v14 quad_perm:[1,0,3,2] row_mask:0xf bank_mask:0xf bound_ctrl:1
	v_fma_mix_f32 v56, v13, v33, v56 op_sel:[0,1,0] op_sel_hi:[0,1,0]
	v_fma_mix_f32 v18, v12, v37, 0 op_sel:[0,0,0] op_sel_hi:[0,1,0]
	v_add_f32_dpp v20, v20, v20 quad_perm:[2,3,0,1] row_mask:0xf bank_mask:0xf bound_ctrl:1
	v_fma_mix_f32 v19, v13, v37, 0 op_sel:[0,1,0] op_sel_hi:[0,1,0]
	v_fma_mix_f32 v16, v46, v42, v16 op_sel:[0,0,0] op_sel_hi:[1,1,0]
	v_add_f32_dpp v20, v20, v20 row_half_mirror row_mask:0xf bank_mask:0xf bound_ctrl:1
	v_fma_mix_f32 v17, v46, v42, v17 op_sel:[0,1,0] op_sel_hi:[1,1,0]
	v_fma_mix_f32 v18, v46, v43, v18 op_sel:[0,0,0] op_sel_hi:[1,1,0]
	v_add_f32_dpp v20, v20, v20 row_mirror row_mask:0xf bank_mask:0xf bound_ctrl:1
	v_fma_mix_f32 v19, v46, v43, v19 op_sel:[0,1,0] op_sel_hi:[1,1,0]
	v_fma_mix_f32 v10, v20, v40, v16 op_sel:[0,0,0] op_sel_hi:[0,1,0]
	v_fma_mix_f32 v11, v20, v40, v17 op_sel:[0,1,0] op_sel_hi:[0,1,0]
	v_fma_mix_f32 v12, v20, v41, v18 op_sel:[0,0,0] op_sel_hi:[0,1,0]
	v_fma_mix_f32 v13, v20, v41, v19 op_sel:[0,1,0] op_sel_hi:[0,1,0]
	s_waitcnt lgkmcnt(0)
	ds_read_b64 v[24:25], v6 offset:12304
	ds_read_b128 v[26:29], v6 offset:12560
	ds_read_b128 v[30:33], v6 offset:12816
	ds_read_u16 v34, v7 offset:12304
	v_fma_mix_f32 v14, v10, v74, 0 op_sel:[0,0,0] op_sel_hi:[0,1,0]
	v_fma_mix_f32 v57, v10, v44, 0 op_sel:[0,0,0] op_sel_hi:[0,1,0]
	v_fma_mix_f32 v14, v11, v74, v14 op_sel:[0,1,0] op_sel_hi:[0,1,0]
	v_fma_mix_f32 v57, v11, v44, v57 op_sel:[0,1,0] op_sel_hi:[0,1,0]
	v_fma_mix_f32 v14, v12, v75, v14 op_sel:[0,0,0] op_sel_hi:[0,1,0]
	v_fma_mix_f32 v57, v12, v45, v57 op_sel:[0,0,0] op_sel_hi:[0,1,0]
	v_fma_mix_f32 v14, v13, v75, v14 op_sel:[0,1,0] op_sel_hi:[0,1,0]
	v_fma_mix_f32 v16, v10, v72, 0 op_sel:[0,0,0] op_sel_hi:[0,1,0]
	v_fma_mix_f32 v17, v11, v72, 0 op_sel:[0,1,0] op_sel_hi:[0,1,0]
	v_add_f32_dpp v20, v14, v14 quad_perm:[1,0,3,2] row_mask:0xf bank_mask:0xf bound_ctrl:1
	v_fma_mix_f32 v57, v13, v45, v57 op_sel:[0,1,0] op_sel_hi:[0,1,0]
	v_fma_mix_f32 v18, v12, v73, 0 op_sel:[0,0,0] op_sel_hi:[0,1,0]
	v_add_f32_dpp v20, v20, v20 quad_perm:[2,3,0,1] row_mask:0xf bank_mask:0xf bound_ctrl:1
	v_fma_mix_f32 v19, v13, v73, 0 op_sel:[0,1,0] op_sel_hi:[0,1,0]
	v_fma_mix_f32 v16, v82, v78, v16 op_sel:[0,0,0] op_sel_hi:[1,1,0]
	v_add_f32_dpp v20, v20, v20 row_half_mirror row_mask:0xf bank_mask:0xf bound_ctrl:1
	v_fma_mix_f32 v17, v82, v78, v17 op_sel:[0,1,0] op_sel_hi:[1,1,0]
	v_fma_mix_f32 v18, v82, v79, v18 op_sel:[0,0,0] op_sel_hi:[1,1,0]
	v_add_f32_dpp v20, v20, v20 row_mirror row_mask:0xf bank_mask:0xf bound_ctrl:1
	v_fma_mix_f32 v19, v82, v79, v19 op_sel:[0,1,0] op_sel_hi:[1,1,0]
	v_fma_mix_f32 v10, v20, v76, v16 op_sel:[0,0,0] op_sel_hi:[0,1,0]
	v_fma_mix_f32 v11, v20, v76, v17 op_sel:[0,1,0] op_sel_hi:[0,1,0]
	v_fma_mix_f32 v12, v20, v77, v18 op_sel:[0,0,0] op_sel_hi:[0,1,0]
	v_fma_mix_f32 v13, v20, v77, v19 op_sel:[0,1,0] op_sel_hi:[0,1,0]
	ds_read_b64 v[36:37], v6 offset:13328
	ds_read_b128 v[38:41], v6 offset:13584
	ds_read_b128 v[42:45], v6 offset:13840
	ds_read_u16 v46, v7 offset:13328
	v_fma_mix_f32 v14, v10, v86, 0 op_sel:[0,0,0] op_sel_hi:[0,1,0]
	v_fma_mix_f32 v58, v10, v80, 0 op_sel:[0,0,0] op_sel_hi:[0,1,0]
	v_fma_mix_f32 v14, v11, v86, v14 op_sel:[0,1,0] op_sel_hi:[0,1,0]
	v_fma_mix_f32 v58, v11, v80, v58 op_sel:[0,1,0] op_sel_hi:[0,1,0]
	v_fma_mix_f32 v14, v12, v87, v14 op_sel:[0,0,0] op_sel_hi:[0,1,0]
	v_fma_mix_f32 v58, v12, v81, v58 op_sel:[0,0,0] op_sel_hi:[0,1,0]
	v_fma_mix_f32 v14, v13, v87, v14 op_sel:[0,1,0] op_sel_hi:[0,1,0]
	v_fma_mix_f32 v16, v10, v84, 0 op_sel:[0,0,0] op_sel_hi:[0,1,0]
	v_fma_mix_f32 v17, v11, v84, 0 op_sel:[0,1,0] op_sel_hi:[0,1,0]
	v_add_f32_dpp v20, v14, v14 quad_perm:[1,0,3,2] row_mask:0xf bank_mask:0xf bound_ctrl:1
	v_fma_mix_f32 v58, v13, v81, v58 op_sel:[0,1,0] op_sel_hi:[0,1,0]
	v_fma_mix_f32 v18, v12, v85, 0 op_sel:[0,0,0] op_sel_hi:[0,1,0]
	v_add_f32_dpp v20, v20, v20 quad_perm:[2,3,0,1] row_mask:0xf bank_mask:0xf bound_ctrl:1
	v_fma_mix_f32 v19, v13, v85, 0 op_sel:[0,1,0] op_sel_hi:[0,1,0]
	v_fma_mix_f32 v16, v94, v90, v16 op_sel:[0,0,0] op_sel_hi:[1,1,0]
	v_add_f32_dpp v20, v20, v20 row_half_mirror row_mask:0xf bank_mask:0xf bound_ctrl:1
	v_fma_mix_f32 v17, v94, v90, v17 op_sel:[0,1,0] op_sel_hi:[1,1,0]
	v_fma_mix_f32 v18, v94, v91, v18 op_sel:[0,0,0] op_sel_hi:[1,1,0]
	v_add_f32_dpp v20, v20, v20 row_mirror row_mask:0xf bank_mask:0xf bound_ctrl:1
	v_fma_mix_f32 v19, v94, v91, v19 op_sel:[0,1,0] op_sel_hi:[1,1,0]
	v_fma_mix_f32 v10, v20, v88, v16 op_sel:[0,0,0] op_sel_hi:[0,1,0]
	v_fma_mix_f32 v11, v20, v88, v17 op_sel:[0,1,0] op_sel_hi:[0,1,0]
	v_fma_mix_f32 v12, v20, v89, v18 op_sel:[0,0,0] op_sel_hi:[0,1,0]
	v_fma_mix_f32 v13, v20, v89, v19 op_sel:[0,1,0] op_sel_hi:[0,1,0]
	s_waitcnt lgkmcnt(0)
	ds_read_b64 v[72:73], v6 offset:14352
	ds_read_b128 v[74:77], v6 offset:14608
	ds_read_b128 v[78:81], v6 offset:14864
	ds_read_u16 v82, v7 offset:14352
	v_fma_mix_f32 v14, v10, v26, 0 op_sel:[0,0,0] op_sel_hi:[0,1,0]
	v_fma_mix_f32 v59, v10, v92, 0 op_sel:[0,0,0] op_sel_hi:[0,1,0]
	v_fma_mix_f32 v14, v11, v26, v14 op_sel:[0,1,0] op_sel_hi:[0,1,0]
	v_fma_mix_f32 v59, v11, v92, v59 op_sel:[0,1,0] op_sel_hi:[0,1,0]
	v_fma_mix_f32 v14, v12, v27, v14 op_sel:[0,0,0] op_sel_hi:[0,1,0]
	v_fma_mix_f32 v59, v12, v93, v59 op_sel:[0,0,0] op_sel_hi:[0,1,0]
	v_fma_mix_f32 v14, v13, v27, v14 op_sel:[0,1,0] op_sel_hi:[0,1,0]
	v_fma_mix_f32 v16, v10, v24, 0 op_sel:[0,0,0] op_sel_hi:[0,1,0]
	v_fma_mix_f32 v17, v11, v24, 0 op_sel:[0,1,0] op_sel_hi:[0,1,0]
	v_add_f32_dpp v20, v14, v14 quad_perm:[1,0,3,2] row_mask:0xf bank_mask:0xf bound_ctrl:1
	v_fma_mix_f32 v59, v13, v93, v59 op_sel:[0,1,0] op_sel_hi:[0,1,0]
	v_fma_mix_f32 v18, v12, v25, 0 op_sel:[0,0,0] op_sel_hi:[0,1,0]
	v_add_f32_dpp v20, v20, v20 quad_perm:[2,3,0,1] row_mask:0xf bank_mask:0xf bound_ctrl:1
	v_fma_mix_f32 v19, v13, v25, 0 op_sel:[0,1,0] op_sel_hi:[0,1,0]
	v_fma_mix_f32 v16, v34, v30, v16 op_sel:[0,0,0] op_sel_hi:[1,1,0]
	v_add_f32_dpp v20, v20, v20 row_half_mirror row_mask:0xf bank_mask:0xf bound_ctrl:1
	v_fma_mix_f32 v17, v34, v30, v17 op_sel:[0,1,0] op_sel_hi:[1,1,0]
	v_fma_mix_f32 v18, v34, v31, v18 op_sel:[0,0,0] op_sel_hi:[1,1,0]
	v_add_f32_dpp v20, v20, v20 row_mirror row_mask:0xf bank_mask:0xf bound_ctrl:1
	v_fma_mix_f32 v19, v34, v31, v19 op_sel:[0,1,0] op_sel_hi:[1,1,0]
	v_fma_mix_f32 v10, v20, v28, v16 op_sel:[0,0,0] op_sel_hi:[0,1,0]
	v_fma_mix_f32 v11, v20, v28, v17 op_sel:[0,1,0] op_sel_hi:[0,1,0]
	v_fma_mix_f32 v12, v20, v29, v18 op_sel:[0,0,0] op_sel_hi:[0,1,0]
	v_fma_mix_f32 v13, v20, v29, v19 op_sel:[0,1,0] op_sel_hi:[0,1,0]
	ds_read_b128 v[100:103], v9
	ds_read_b64 v[84:85], v6 offset:15376
	ds_read_b128 v[86:89], v6 offset:15632
	ds_read_b128 v[90:93], v6 offset:15888
	ds_read_u16 v94, v7 offset:15376
	v_fma_mix_f32 v14, v10, v38, 0 op_sel:[0,0,0] op_sel_hi:[0,1,0]
	v_fma_mix_f32 v60, v10, v32, 0 op_sel:[0,0,0] op_sel_hi:[0,1,0]
	v_fma_mix_f32 v14, v11, v38, v14 op_sel:[0,1,0] op_sel_hi:[0,1,0]
	v_fma_mix_f32 v60, v11, v32, v60 op_sel:[0,1,0] op_sel_hi:[0,1,0]
	v_fma_mix_f32 v14, v12, v39, v14 op_sel:[0,0,0] op_sel_hi:[0,1,0]
	v_fma_mix_f32 v60, v12, v33, v60 op_sel:[0,0,0] op_sel_hi:[0,1,0]
	v_fma_mix_f32 v14, v13, v39, v14 op_sel:[0,1,0] op_sel_hi:[0,1,0]
	v_fma_mix_f32 v16, v10, v36, 0 op_sel:[0,0,0] op_sel_hi:[0,1,0]
	v_fma_mix_f32 v17, v11, v36, 0 op_sel:[0,1,0] op_sel_hi:[0,1,0]
	v_add_f32_dpp v20, v14, v14 quad_perm:[1,0,3,2] row_mask:0xf bank_mask:0xf bound_ctrl:1
	v_fma_mix_f32 v60, v13, v33, v60 op_sel:[0,1,0] op_sel_hi:[0,1,0]
	v_fma_mix_f32 v18, v12, v37, 0 op_sel:[0,0,0] op_sel_hi:[0,1,0]
	v_add_f32_dpp v20, v20, v20 quad_perm:[2,3,0,1] row_mask:0xf bank_mask:0xf bound_ctrl:1
	v_fma_mix_f32 v19, v13, v37, 0 op_sel:[0,1,0] op_sel_hi:[0,1,0]
	v_fma_mix_f32 v16, v46, v42, v16 op_sel:[0,0,0] op_sel_hi:[1,1,0]
	v_add_f32_dpp v20, v20, v20 row_half_mirror row_mask:0xf bank_mask:0xf bound_ctrl:1
	v_fma_mix_f32 v17, v46, v42, v17 op_sel:[0,1,0] op_sel_hi:[1,1,0]
	v_fma_mix_f32 v18, v46, v43, v18 op_sel:[0,0,0] op_sel_hi:[1,1,0]
	v_add_f32_dpp v20, v20, v20 row_mirror row_mask:0xf bank_mask:0xf bound_ctrl:1
	v_fma_mix_f32 v19, v46, v43, v19 op_sel:[0,1,0] op_sel_hi:[1,1,0]
	v_fma_mix_f32 v10, v20, v40, v16 op_sel:[0,0,0] op_sel_hi:[0,1,0]
	v_fma_mix_f32 v11, v20, v40, v17 op_sel:[0,1,0] op_sel_hi:[0,1,0]
	v_fma_mix_f32 v12, v20, v41, v18 op_sel:[0,0,0] op_sel_hi:[0,1,0]
	v_fma_mix_f32 v13, v20, v41, v19 op_sel:[0,1,0] op_sel_hi:[0,1,0]
	s_waitcnt lgkmcnt(0)
; DEVINL u16 f2bf(float a) { return (u16)(pk2(a, 0.f) & 0xffffu); }
; #define RW_STEP2(B) RW_STEP(B, WvA, XA, KrA, vhA, WvB, XB, KrB, vhB); RW_STEP((B) + 1, WvB, XB, KrB, vhB, WvA, XA, KrA, vhA)
; #define RW_STEP4(B) RW_STEP2(B); RW_STEP2((B) + 2)
; template <int DIR>
; DEVINL void rwkv_scan_dir(const Params& p, int task, int lane, int wave) {
;     ...
;   for (int st = 0; st < 4096; st += 32) {
;     RW_STEP(0, WvA, XA, KrA, vhA, WvB, XB, KrB, vhB);
;     if (st > 0) { const int q0 = st - 16 + seg; yo[(long)(DIR ? (4095 - q0) : q0) * 1024] = f2bf(ykeep); }
;     RW_STEP(1, WvB, XB, KrB, vhB, WvA, XA, KrA, vhA);
;     RW_STEP2(2); RW_STEP4(4); RW_STEP4(8); RW_STEP4(12);
;     RW_STEP(16, WvA, XA, KrA, vhA, WvB, XB, KrB, vhB);
;     { const int q0 = st + seg; yo[(long)(DIR ? (4095 - q0) : q0) * 1024] = f2bf(ykeep); }
;     RW_STEP(17, WvB, XB, KrB, vhB, WvA, XA, KrA, vhA);
;     RW_STEP2(18); RW_STEP4(20); RW_STEP4(24); RW_STEP4(28);
;   }
;   {
;     const float ylast = allred16(ypart);
;     ykeep = (seg == 15) ? ylast : ykeep;
;     const int q0 = 4096 - 16 + seg; yo[(long)(DIR ? (4095 - q0) : q0) * 1024] = f2bf(ykeep);
;   }
	v_add_u32_e32 v6, 0x4000, v6
	v_add_u32_e32 v7, 0x4000, v7
	v_and_b32_e32 v6, 0x1ffff, v6
	v_and_b32_e32 v7, 0x1ffff, v7
	ds_read_b64 v[24:25], v6 offset:16
	ds_read_b128 v[26:29], v6 offset:272
	ds_read_b128 v[30:33], v6 offset:528
	ds_read_u16 v34, v7 offset:16
	v_fma_mix_f32 v14, v10, v74, 0 op_sel:[0,0,0] op_sel_hi:[0,1,0]
	v_fma_mix_f32 v61, v10, v44, 0 op_sel:[0,0,0] op_sel_hi:[0,1,0]
	v_fma_mix_f32 v14, v11, v74, v14 op_sel:[0,1,0] op_sel_hi:[0,1,0]
	v_fma_mix_f32 v61, v11, v44, v61 op_sel:[0,1,0] op_sel_hi:[0,1,0]
	v_fma_mix_f32 v14, v12, v75, v14 op_sel:[0,0,0] op_sel_hi:[0,1,0]
	v_fma_mix_f32 v61, v12, v45, v61 op_sel:[0,0,0] op_sel_hi:[0,1,0]
	v_fma_mix_f32 v14, v13, v75, v14 op_sel:[0,1,0] op_sel_hi:[0,1,0]
	v_fma_mix_f32 v16, v10, v72, 0 op_sel:[0,0,0] op_sel_hi:[0,1,0]
	v_fma_mix_f32 v17, v11, v72, 0 op_sel:[0,1,0] op_sel_hi:[0,1,0]
	v_add_f32_dpp v20, v14, v14 quad_perm:[1,0,3,2] row_mask:0xf bank_mask:0xf bound_ctrl:1
	v_fma_mix_f32 v61, v13, v45, v61 op_sel:[0,1,0] op_sel_hi:[0,1,0]
	v_fma_mix_f32 v18, v12, v73, 0 op_sel:[0,0,0] op_sel_hi:[0,1,0]
	v_add_f32_dpp v20, v20, v20 quad_perm:[2,3,0,1] row_mask:0xf bank_mask:0xf bound_ctrl:1
	v_fma_mix_f32 v19, v13, v73, 0 op_sel:[0,1,0] op_sel_hi:[0,1,0]
	v_fma_mix_f32 v16, v82, v78, v16 op_sel:[0,0,0] op_sel_hi:[1,1,0]
	v_add_f32_dpp v20, v20, v20 row_half_mirror row_mask:0xf bank_mask:0xf bound_ctrl:1
	v_fma_mix_f32 v17, v82, v78, v17 op_sel:[0,1,0] op_sel_hi:[1,1,0]
	v_fma_mix_f32 v18, v82, v79, v18 op_sel:[0,0,0] op_sel_hi:[1,1,0]
	v_add_f32_dpp v20, v20, v20 row_mirror row_mask:0xf bank_mask:0xf bound_ctrl:1
	v_fma_mix_f32 v19, v82, v79, v19 op_sel:[0,1,0] op_sel_hi:[1,1,0]
	v_fma_mix_f32 v10, v20, v76, v16 op_sel:[0,0,0] op_sel_hi:[0,1,0]
	v_fma_mix_f32 v11, v20, v76, v17 op_sel:[0,1,0] op_sel_hi:[0,1,0]
	v_fma_mix_f32 v12, v20, v77, v18 op_sel:[0,0,0] op_sel_hi:[0,1,0]
	v_fma_mix_f32 v13, v20, v77, v19 op_sel:[0,1,0] op_sel_hi:[0,1,0]
	ds_read_b64 v[36:37], v6 offset:1040
	ds_read_b128 v[38:41], v6 offset:1296
	ds_read_b128 v[42:45], v6 offset:1552
	ds_read_u16 v46, v7 offset:1040
	v_fma_mix_f32 v14, v10, v86, 0 op_sel:[0,0,0] op_sel_hi:[0,1,0]
	v_fma_mix_f32 v62, v10, v80, 0 op_sel:[0,0,0] op_sel_hi:[0,1,0]
	v_fma_mix_f32 v14, v11, v86, v14 op_sel:[0,1,0] op_sel_hi:[0,1,0]
	v_fma_mix_f32 v62, v11, v80, v62 op_sel:[0,1,0] op_sel_hi:[0,1,0]
	v_fma_mix_f32 v14, v12, v87, v14 op_sel:[0,0,0] op_sel_hi:[0,1,0]
	v_fma_mix_f32 v62, v12, v81, v62 op_sel:[0,0,0] op_sel_hi:[0,1,0]
	v_fma_mix_f32 v14, v13, v87, v14 op_sel:[0,1,0] op_sel_hi:[0,1,0]
	v_fma_mix_f32 v16, v10, v84, 0 op_sel:[0,0,0] op_sel_hi:[0,1,0]
	v_fma_mix_f32 v17, v11, v84, 0 op_sel:[0,1,0] op_sel_hi:[0,1,0]
	v_add_f32_dpp v20, v14, v14 quad_perm:[1,0,3,2] row_mask:0xf bank_mask:0xf bound_ctrl:1
	v_fma_mix_f32 v62, v13, v81, v62 op_sel:[0,1,0] op_sel_hi:[0,1,0]
	v_fma_mix_f32 v18, v12, v85, 0 op_sel:[0,0,0] op_sel_hi:[0,1,0]
	v_add_f32_dpp v20, v20, v20 quad_perm:[2,3,0,1] row_mask:0xf bank_mask:0xf bound_ctrl:1
	v_fma_mix_f32 v19, v13, v85, 0 op_sel:[0,1,0] op_sel_hi:[0,1,0]
	v_fma_mix_f32 v16, v94, v90, v16 op_sel:[0,0,0] op_sel_hi:[1,1,0]
	v_add_f32_dpp v20, v20, v20 row_half_mirror row_mask:0xf bank_mask:0xf bound_ctrl:1
	v_fma_mix_f32 v17, v94, v90, v17 op_sel:[0,1,0] op_sel_hi:[1,1,0]
	v_fma_mix_f32 v18, v94, v91, v18 op_sel:[0,0,0] op_sel_hi:[1,1,0]
	v_add_f32_dpp v20, v20, v20 row_mirror row_mask:0xf bank_mask:0xf bound_ctrl:1
	v_fma_mix_f32 v19, v94, v91, v19 op_sel:[0,1,0] op_sel_hi:[1,1,0]
	v_fma_mix_f32 v10, v20, v88, v16 op_sel:[0,0,0] op_sel_hi:[0,1,0]
	v_fma_mix_f32 v11, v20, v88, v17 op_sel:[0,1,0] op_sel_hi:[0,1,0]
	v_fma_mix_f32 v12, v20, v89, v18 op_sel:[0,0,0] op_sel_hi:[0,1,0]
	v_fma_mix_f32 v13, v20, v89, v19 op_sel:[0,1,0] op_sel_hi:[0,1,0]
	s_waitcnt lgkmcnt(0)
	s_add_u32 s43, s43, 1
	s_cmp_lg_u32 s43, s45
	s_cbranch_scc1 .Lrw_blk_d0
	s_sub_u32 s15, s43, 2
	v_fma_mix_f32 v21, v10, v92, 0 op_sel:[0,0,0] op_sel_hi:[0,1,0]
	v_fma_mix_f32 v22, v12, v93, 0 op_sel:[0,0,0] op_sel_hi:[0,1,0]
	v_fma_mix_f32 v21, v11, v92, v21 op_sel:[0,1,0] op_sel_hi:[0,1,0]
	v_fma_mix_f32 v22, v13, v93, v22 op_sel:[0,1,0] op_sel_hi:[0,1,0]
	v_add_f32_e32 v63, v21, v22
	s_nop 1
	v_add_f32_dpp v48, v48, v48 row_ror:8 row_mask:0xf bank_mask:0x3
	v_add_f32_dpp v49, v49, v49 row_ror:8 row_mask:0xf bank_mask:0x3
	v_add_f32_dpp v50, v50, v50 row_ror:8 row_mask:0xf bank_mask:0x3
	v_add_f32_dpp v51, v51, v51 row_ror:8 row_mask:0xf bank_mask:0x3
	v_add_f32_dpp v52, v52, v52 row_ror:8 row_mask:0xf bank_mask:0x3
	v_add_f32_dpp v53, v53, v53 row_ror:8 row_mask:0xf bank_mask:0x3
	v_add_f32_dpp v54, v54, v54 row_ror:8 row_mask:0xf bank_mask:0x3
	v_add_f32_dpp v55, v55, v55 row_ror:8 row_mask:0xf bank_mask:0x3
	v_add_f32_dpp v48, v56, v56 row_ror:8 row_mask:0xf bank_mask:0xc
	v_add_f32_dpp v49, v57, v57 row_ror:8 row_mask:0xf bank_mask:0xc
	v_add_f32_dpp v50, v58, v58 row_ror:8 row_mask:0xf bank_mask:0xc
	v_add_f32_dpp v51, v59, v59 row_ror:8 row_mask:0xf bank_mask:0xc
	v_add_f32_dpp v52, v60, v60 row_ror:8 row_mask:0xf bank_mask:0xc
	v_add_f32_dpp v53, v61, v61 row_ror:8 row_mask:0xf bank_mask:0xc
	v_add_f32_dpp v54, v62, v62 row_ror:8 row_mask:0xf bank_mask:0xc
	v_add_f32_dpp v55, v63, v63 row_ror:8 row_mask:0xf bank_mask:0xc
	v_add_f32_dpp v48, v48, v48 row_ror:12 row_mask:0xf bank_mask:0x5
	v_add_f32_dpp v49, v49, v49 row_ror:12 row_mask:0xf bank_mask:0x5
	v_add_f32_dpp v50, v50, v50 row_ror:12 row_mask:0xf bank_mask:0x5
	v_add_f32_dpp v51, v51, v51 row_ror:12 row_mask:0xf bank_mask:0x5
	v_add_f32_dpp v48, v52, v52 row_ror:4 row_mask:0xf bank_mask:0xa
	v_add_f32_dpp v49, v53, v53 row_ror:4 row_mask:0xf bank_mask:0xa
	v_add_f32_dpp v50, v54, v54 row_ror:4 row_mask:0xf bank_mask:0xa
	v_add_f32_dpp v51, v55, v55 row_ror:4 row_mask:0xf bank_mask:0xa
	v_add_f32_dpp v64, v48, v48 quad_perm:[2,3,0,1] row_mask:0xf bank_mask:0xf bound_ctrl:1
	v_add_f32_dpp v65, v50, v50 quad_perm:[2,3,0,1] row_mask:0xf bank_mask:0xf bound_ctrl:1
	v_cndmask_b32_e64 v56, v64, v65, s[50:51]
	v_add_f32_dpp v64, v49, v49 quad_perm:[2,3,0,1] row_mask:0xf bank_mask:0xf bound_ctrl:1
	v_add_f32_dpp v65, v51, v51 quad_perm:[2,3,0,1] row_mask:0xf bank_mask:0xf bound_ctrl:1
	v_cndmask_b32_e64 v57, v64, v65, s[50:51]
	v_add_f32_dpp v64, v56, v56 quad_perm:[1,0,3,2] row_mask:0xf bank_mask:0xf bound_ctrl:1
	s_nop 0
	v_add_f32_dpp v65, v57, v57 quad_perm:[1,0,3,2] row_mask:0xf bank_mask:0xf bound_ctrl:1
	v_cndmask_b32_e64 v66, v64, v65, s[48:49]
	v_cvt_pk_bf16_f32 v66, v66, v66
	global_store_short v8, v66, s[12:13]
	s_add_u32 s12, s12, 0x8000
	s_addc_u32 s13, s13, 0
	s_branch .Lrw_next

; DEVINL u16 f2bf(float a) { return (u16)(pk2(a, 0.f) & 0xffffu); }
; #define RW_STEP2(B) RW_STEP(B, WvA, XA, KrA, vhA, WvB, XB, KrB, vhB); RW_STEP((B) + 1, WvB, XB, KrB, vhB, WvA, XA, KrA, vhA)
; #define RW_STEP4(B) RW_STEP2(B); RW_STEP2((B) + 2)
; template <int DIR>
; DEVINL void rwkv_scan_dir(const Params& p, int task, int lane, int wave) {
;     ...
;   for (int st = 0; st < 4096; st += 32) {
;     RW_STEP(0, WvA, XA, KrA, vhA, WvB, XB, KrB, vhB);
;     if (st > 0) { const int q0 = st - 16 + seg; yo[(long)(DIR ? (4095 - q0) : q0) * 1024] = f2bf(ykeep); }
;     RW_STEP(1, WvB, XB, KrB, vhB, WvA, XA, KrA, vhA);
;     RW_STEP2(2); RW_STEP4(4); RW_STEP4(8); RW_STEP4(12);
.Lrw_ready_d1b0:
	s_add_u32 m0, s41, 16
	s_nop 0
	global_load_lds_dwordx4 v5, s[10:11] offset:0
	global_load_lds_dwordx4 v5, s[10:11] offset:1024
	global_load_lds_dwordx4 v5, s[10:11] offset:2048
	global_load_lds_dwordx4 v5, s[10:11] offset:3072
	s_sub_u32 s10, s10, 0x4000
	s_subb_u32 s11, s11, 0
	s_sub_u32 s41, s41, 0x4000
	s_and_b32 s41, s41, 0x1ffff
	ds_read_b64 v[72:73], v6 offset:13336
	ds_read_b128 v[74:77], v6 offset:13584
	ds_read_b128 v[78:81], v6 offset:13840
	ds_read_u16 v82, v7 offset:13328
	v_fma_mix_f32 v14, v10, v26, 0 op_sel:[0,0,0] op_sel_hi:[0,1,0]
	v_fma_mix_f32 v63, v10, v92, 0 op_sel:[0,0,0] op_sel_hi:[0,1,0]
	v_fma_mix_f32 v14, v11, v26, v14 op_sel:[0,1,0] op_sel_hi:[0,1,0]
	v_fma_mix_f32 v63, v11, v92, v63 op_sel:[0,1,0] op_sel_hi:[0,1,0]
	v_fma_mix_f32 v14, v12, v27, v14 op_sel:[0,0,0] op_sel_hi:[0,1,0]
	v_fma_mix_f32 v63, v12, v93, v63 op_sel:[0,0,0] op_sel_hi:[0,1,0]
	v_fma_mix_f32 v14, v13, v27, v14 op_sel:[0,1,0] op_sel_hi:[0,1,0]
	v_fma_mix_f32 v16, v10, v24, 0 op_sel:[0,0,0] op_sel_hi:[0,1,0]
	v_fma_mix_f32 v17, v11, v24, 0 op_sel:[0,1,0] op_sel_hi:[0,1,0]
	v_add_f32_dpp v20, v14, v14 quad_perm:[1,0,3,2] row_mask:0xf bank_mask:0xf bound_ctrl:1
	v_fma_mix_f32 v63, v13, v93, v63 op_sel:[0,1,0] op_sel_hi:[0,1,0]
	v_fma_mix_f32 v18, v12, v25, 0 op_sel:[0,0,0] op_sel_hi:[0,1,0]
	v_add_f32_dpp v20, v20, v20 quad_perm:[2,3,0,1] row_mask:0xf bank_mask:0xf bound_ctrl:1
	v_fma_mix_f32 v19, v13, v25, 0 op_sel:[0,1,0] op_sel_hi:[0,1,0]
	v_fma_mix_f32 v16, v34, v30, v16 op_sel:[0,0,0] op_sel_hi:[1,1,0]
	v_add_f32_dpp v20, v20, v20 row_half_mirror row_mask:0xf bank_mask:0xf bound_ctrl:1
	v_fma_mix_f32 v17, v34, v30, v17 op_sel:[0,1,0] op_sel_hi:[1,1,0]
	v_fma_mix_f32 v18, v34, v31, v18 op_sel:[0,0,0] op_sel_hi:[1,1,0]
	v_add_f32_dpp v20, v20, v20 row_mirror row_mask:0xf bank_mask:0xf bound_ctrl:1
	v_fma_mix_f32 v19, v34, v31, v19 op_sel:[0,1,0] op_sel_hi:[1,1,0]
	v_fma_mix_f32 v10, v20, v28, v16 op_sel:[0,0,0] op_sel_hi:[0,1,0]
	v_fma_mix_f32 v11, v20, v28, v17 op_sel:[0,1,0] op_sel_hi:[0,1,0]
	v_fma_mix_f32 v12, v20, v29, v18 op_sel:[0,0,0] op_sel_hi:[0,1,0]
	v_fma_mix_f32 v13, v20, v29, v19 op_sel:[0,1,0] op_sel_hi:[0,1,0]
	ds_read_b64 v[84:85], v6 offset:12312
	ds_read_b128 v[86:89], v6 offset:12560
	ds_read_b128 v[90:93], v6 offset:12816
	ds_read_u16 v94, v7 offset:12304
	v_fma_mix_f32 v14, v10, v38, 0 op_sel:[0,0,0] op_sel_hi:[0,1,0]
	v_fma_mix_f32 v48, v10, v32, 0 op_sel:[0,0,0] op_sel_hi:[0,1,0]
	v_fma_mix_f32 v14, v11, v38, v14 op_sel:[0,1,0] op_sel_hi:[0,1,0]
	v_fma_mix_f32 v48, v11, v32, v48 op_sel:[0,1,0] op_sel_hi:[0,1,0]
	v_fma_mix_f32 v14, v12, v39, v14 op_sel:[0,0,0] op_sel_hi:[0,1,0]
	v_fma_mix_f32 v48, v12, v33, v48 op_sel:[0,0,0] op_sel_hi:[0,1,0]
	v_fma_mix_f32 v14, v13, v39, v14 op_sel:[0,1,0] op_sel_hi:[0,1,0]
	v_fma_mix_f32 v16, v10, v36, 0 op_sel:[0,0,0] op_sel_hi:[0,1,0]
	v_fma_mix_f32 v17, v11, v36, 0 op_sel:[0,1,0] op_sel_hi:[0,1,0]
	v_add_f32_dpp v20, v14, v14 quad_perm:[1,0,3,2] row_mask:0xf bank_mask:0xf bound_ctrl:1
	v_fma_mix_f32 v48, v13, v33, v48 op_sel:[0,1,0] op_sel_hi:[0,1,0]
	v_fma_mix_f32 v18, v12, v37, 0 op_sel:[0,0,0] op_sel_hi:[0,1,0]
	v_add_f32_dpp v20, v20, v20 quad_perm:[2,3,0,1] row_mask:0xf bank_mask:0xf bound_ctrl:1
	v_fma_mix_f32 v19, v13, v37, 0 op_sel:[0,1,0] op_sel_hi:[0,1,0]
	v_fma_mix_f32 v16, v46, v42, v16 op_sel:[0,0,0] op_sel_hi:[1,1,0]
	v_add_f32_dpp v20, v20, v20 row_half_mirror row_mask:0xf bank_mask:0xf bound_ctrl:1
	v_fma_mix_f32 v17, v46, v42, v17 op_sel:[0,1,0] op_sel_hi:[1,1,0]
	v_fma_mix_f32 v18, v46, v43, v18 op_sel:[0,0,0] op_sel_hi:[1,1,0]
	v_add_f32_dpp v20, v20, v20 row_mirror row_mask:0xf bank_mask:0xf bound_ctrl:1
	v_fma_mix_f32 v19, v46, v43, v19 op_sel:[0,1,0] op_sel_hi:[1,1,0]
	v_fma_mix_f32 v10, v20, v40, v16 op_sel:[0,0,0] op_sel_hi:[0,1,0]
	v_fma_mix_f32 v11, v20, v40, v17 op_sel:[0,1,0] op_sel_hi:[0,1,0]
	v_fma_mix_f32 v12, v20, v41, v18 op_sel:[0,0,0] op_sel_hi:[0,1,0]
	v_fma_mix_f32 v13, v20, v41, v19 op_sel:[0,1,0] op_sel_hi:[0,1,0]
	s_waitcnt lgkmcnt(0)
	ds_read_b64 v[24:25], v6 offset:11288
	ds_read_b128 v[26:29], v6 offset:11536
	ds_read_b128 v[30:33], v6 offset:11792
	ds_read_u16 v34, v7 offset:11280
	v_fma_mix_f32 v14, v10, v74, 0 op_sel:[0,0,0] op_sel_hi:[0,1,0]
	v_fma_mix_f32 v49, v10, v44, 0 op_sel:[0,0,0] op_sel_hi:[0,1,0]
	v_fma_mix_f32 v14, v11, v74, v14 op_sel:[0,1,0] op_sel_hi:[0,1,0]
	v_fma_mix_f32 v49, v11, v44, v49 op_sel:[0,1,0] op_sel_hi:[0,1,0]
	v_fma_mix_f32 v14, v12, v75, v14 op_sel:[0,0,0] op_sel_hi:[0,1,0]
	v_fma_mix_f32 v49, v12, v45, v49 op_sel:[0,0,0] op_sel_hi:[0,1,0]
	v_fma_mix_f32 v14, v13, v75, v14 op_sel:[0,1,0] op_sel_hi:[0,1,0]
	v_fma_mix_f32 v16, v10, v72, 0 op_sel:[0,0,0] op_sel_hi:[0,1,0]
	v_fma_mix_f32 v17, v11, v72, 0 op_sel:[0,1,0] op_sel_hi:[0,1,0]
	v_add_f32_dpp v20, v14, v14 quad_perm:[1,0,3,2] row_mask:0xf bank_mask:0xf bound_ctrl:1
	v_fma_mix_f32 v49, v13, v45, v49 op_sel:[0,1,0] op_sel_hi:[0,1,0]
	v_fma_mix_f32 v18, v12, v73, 0 op_sel:[0,0,0] op_sel_hi:[0,1,0]
	v_add_f32_dpp v20, v20, v20 quad_perm:[2,3,0,1] row_mask:0xf bank_mask:0xf bound_ctrl:1
	v_fma_mix_f32 v19, v13, v73, 0 op_sel:[0,1,0] op_sel_hi:[0,1,0]
	v_fma_mix_f32 v16, v82, v78, v16 op_sel:[0,0,0] op_sel_hi:[1,1,0]
	v_add_f32_dpp v20, v20, v20 row_half_mirror row_mask:0xf bank_mask:0xf bound_ctrl:1
	v_fma_mix_f32 v17, v82, v78, v17 op_sel:[0,1,0] op_sel_hi:[1,1,0]
	v_fma_mix_f32 v18, v82, v79, v18 op_sel:[0,0,0] op_sel_hi:[1,1,0]
	v_add_f32_dpp v20, v20, v20 row_mirror row_mask:0xf bank_mask:0xf bound_ctrl:1
	v_fma_mix_f32 v19, v82, v79, v19 op_sel:[0,1,0] op_sel_hi:[1,1,0]
	v_fma_mix_f32 v10, v20, v76, v16 op_sel:[0,0,0] op_sel_hi:[0,1,0]
	v_fma_mix_f32 v11, v20, v76, v17 op_sel:[0,1,0] op_sel_hi:[0,1,0]
	v_fma_mix_f32 v12, v20, v77, v18 op_sel:[0,0,0] op_sel_hi:[0,1,0]
	v_fma_mix_f32 v13, v20, v77, v19 op_sel:[0,1,0] op_sel_hi:[0,1,0]
	ds_read_b64 v[36:37], v6 offset:10264
	ds_read_b128 v[38:41], v6 offset:10512
	ds_read_b128 v[42:45], v6 offset:10768
	ds_read_u16 v46, v7 offset:10256
	v_fma_mix_f32 v14, v10, v86, 0 op_sel:[0,0,0] op_sel_hi:[0,1,0]
	v_fma_mix_f32 v50, v10, v80, 0 op_sel:[0,0,0] op_sel_hi:[0,1,0]
	v_fma_mix_f32 v14, v11, v86, v14 op_sel:[0,1,0] op_sel_hi:[0,1,0]
	v_fma_mix_f32 v50, v11, v80, v50 op_sel:[0,1,0] op_sel_hi:[0,1,0]
	v_fma_mix_f32 v14, v12, v87, v14 op_sel:[0,0,0] op_sel_hi:[0,1,0]
	v_fma_mix_f32 v50, v12, v81, v50 op_sel:[0,0,0] op_sel_hi:[0,1,0]
	v_fma_mix_f32 v14, v13, v87, v14 op_sel:[0,1,0] op_sel_hi:[0,1,0]
	v_fma_mix_f32 v16, v10, v84, 0 op_sel:[0,0,0] op_sel_hi:[0,1,0]
	v_fma_mix_f32 v17, v11, v84, 0 op_sel:[0,1,0] op_sel_hi:[0,1,0]
	v_add_f32_dpp v20, v14, v14 quad_perm:[1,0,3,2] row_mask:0xf bank_mask:0xf bound_ctrl:1
	v_fma_mix_f32 v50, v13, v81, v50 op_sel:[0,1,0] op_sel_hi:[0,1,0]
	v_fma_mix_f32 v18, v12, v85, 0 op_sel:[0,0,0] op_sel_hi:[0,1,0]
	v_add_f32_dpp v20, v20, v20 quad_perm:[2,3,0,1] row_mask:0xf bank_mask:0xf bound_ctrl:1
	v_fma_mix_f32 v19, v13, v85, 0 op_sel:[0,1,0] op_sel_hi:[0,1,0]
	v_fma_mix_f32 v16, v94, v90, v16 op_sel:[0,0,0] op_sel_hi:[1,1,0]
	v_add_f32_dpp v20, v20, v20 row_half_mirror row_mask:0xf bank_mask:0xf bound_ctrl:1
	v_fma_mix_f32 v17, v94, v90, v17 op_sel:[0,1,0] op_sel_hi:[1,1,0]
	v_fma_mix_f32 v18, v94, v91, v18 op_sel:[0,0,0] op_sel_hi:[1,1,0]
	v_add_f32_dpp v20, v20, v20 row_mirror row_mask:0xf bank_mask:0xf bound_ctrl:1
	v_fma_mix_f32 v19, v94, v91, v19 op_sel:[0,1,0] op_sel_hi:[1,1,0]
	v_fma_mix_f32 v10, v20, v88, v16 op_sel:[0,0,0] op_sel_hi:[0,1,0]
	v_fma_mix_f32 v11, v20, v88, v17 op_sel:[0,1,0] op_sel_hi:[0,1,0]
	v_fma_mix_f32 v12, v20, v89, v18 op_sel:[0,0,0] op_sel_hi:[0,1,0]
	v_fma_mix_f32 v13, v20, v89, v19 op_sel:[0,1,0] op_sel_hi:[0,1,0]
	s_waitcnt lgkmcnt(0)
	ds_read_b64 v[72:73], v6 offset:9240
	ds_read_b128 v[74:77], v6 offset:9488
	ds_read_b128 v[78:81], v6 offset:9744
	ds_read_u16 v82, v7 offset:9232
	v_fma_mix_f32 v14, v10, v26, 0 op_sel:[0,0,0] op_sel_hi:[0,1,0]
	v_fma_mix_f32 v51, v10, v92, 0 op_sel:[0,0,0] op_sel_hi:[0,1,0]
	v_fma_mix_f32 v14, v11, v26, v14 op_sel:[0,1,0] op_sel_hi:[0,1,0]
	v_fma_mix_f32 v51, v11, v92, v51 op_sel:[0,1,0] op_sel_hi:[0,1,0]
	v_fma_mix_f32 v14, v12, v27, v14 op_sel:[0,0,0] op_sel_hi:[0,1,0]
	v_fma_mix_f32 v51, v12, v93, v51 op_sel:[0,0,0] op_sel_hi:[0,1,0]
	v_fma_mix_f32 v14, v13, v27, v14 op_sel:[0,1,0] op_sel_hi:[0,1,0]
	v_fma_mix_f32 v16, v10, v24, 0 op_sel:[0,0,0] op_sel_hi:[0,1,0]
	v_fma_mix_f32 v17, v11, v24, 0 op_sel:[0,1,0] op_sel_hi:[0,1,0]
	v_add_f32_dpp v20, v14, v14 quad_perm:[1,0,3,2] row_mask:0xf bank_mask:0xf bound_ctrl:1
	v_fma_mix_f32 v51, v13, v93, v51 op_sel:[0,1,0] op_sel_hi:[0,1,0]
	v_fma_mix_f32 v18, v12, v25, 0 op_sel:[0,0,0] op_sel_hi:[0,1,0]
	v_add_f32_dpp v20, v20, v20 quad_perm:[2,3,0,1] row_mask:0xf bank_mask:0xf bound_ctrl:1
	v_fma_mix_f32 v19, v13, v25, 0 op_sel:[0,1,0] op_sel_hi:[0,1,0]
	v_fma_mix_f32 v16, v34, v30, v16 op_sel:[0,0,0] op_sel_hi:[1,1,0]
	v_add_f32_dpp v20, v20, v20 row_half_mirror row_mask:0xf bank_mask:0xf bound_ctrl:1
	v_fma_mix_f32 v17, v34, v30, v17 op_sel:[0,1,0] op_sel_hi:[1,1,0]
	v_fma_mix_f32 v18, v34, v31, v18 op_sel:[0,0,0] op_sel_hi:[1,1,0]
	v_add_f32_dpp v20, v20, v20 row_mirror row_mask:0xf bank_mask:0xf bound_ctrl:1
	v_fma_mix_f32 v19, v34, v31, v19 op_sel:[0,1,0] op_sel_hi:[1,1,0]
	v_fma_mix_f32 v10, v20, v28, v16 op_sel:[0,0,0] op_sel_hi:[0,1,0]
	v_fma_mix_f32 v11, v20, v28, v17 op_sel:[0,1,0] op_sel_hi:[0,1,0]
	v_fma_mix_f32 v12, v20, v29, v18 op_sel:[0,0,0] op_sel_hi:[0,1,0]
	v_fma_mix_f32 v13, v20, v29, v19 op_sel:[0,1,0] op_sel_hi:[0,1,0]
	ds_read_b64 v[84:85], v6 offset:8216
	ds_read_b128 v[86:89], v6 offset:8464
	ds_read_b128 v[90:93], v6 offset:8720
	ds_read_u16 v94, v7 offset:8208
	v_fma_mix_f32 v14, v10, v38, 0 op_sel:[0,0,0] op_sel_hi:[0,1,0]
	v_fma_mix_f32 v52, v10, v32, 0 op_sel:[0,0,0] op_sel_hi:[0,1,0]
	v_fma_mix_f32 v14, v11, v38, v14 op_sel:[0,1,0] op_sel_hi:[0,1,0]
	v_fma_mix_f32 v52, v11, v32, v52 op_sel:[0,1,0] op_sel_hi:[0,1,0]
	v_fma_mix_f32 v14, v12, v39, v14 op_sel:[0,0,0] op_sel_hi:[0,1,0]
	v_fma_mix_f32 v52, v12, v33, v52 op_sel:[0,0,0] op_sel_hi:[0,1,0]
	v_fma_mix_f32 v14, v13, v39, v14 op_sel:[0,1,0] op_sel_hi:[0,1,0]
	v_fma_mix_f32 v16, v10, v36, 0 op_sel:[0,0,0] op_sel_hi:[0,1,0]
	v_fma_mix_f32 v17, v11, v36, 0 op_sel:[0,1,0] op_sel_hi:[0,1,0]
	v_add_f32_dpp v20, v14, v14 quad_perm:[1,0,3,2] row_mask:0xf bank_mask:0xf bound_ctrl:1
	v_fma_mix_f32 v52, v13, v33, v52 op_sel:[0,1,0] op_sel_hi:[0,1,0]
	v_fma_mix_f32 v18, v12, v37, 0 op_sel:[0,0,0] op_sel_hi:[0,1,0]
	v_add_f32_dpp v20, v20, v20 quad_perm:[2,3,0,1] row_mask:0xf bank_mask:0xf bound_ctrl:1
	v_fma_mix_f32 v19, v13, v37, 0 op_sel:[0,1,0] op_sel_hi:[0,1,0]
	v_fma_mix_f32 v16, v46, v42, v16 op_sel:[0,0,0] op_sel_hi:[1,1,0]
	v_add_f32_dpp v20, v20, v20 row_half_mirror row_mask:0xf bank_mask:0xf bound_ctrl:1
	v_fma_mix_f32 v17, v46, v42, v17 op_sel:[0,1,0] op_sel_hi:[1,1,0]
	v_fma_mix_f32 v18, v46, v43, v18 op_sel:[0,0,0] op_sel_hi:[1,1,0]
	v_add_f32_dpp v20, v20, v20 row_mirror row_mask:0xf bank_mask:0xf bound_ctrl:1
	v_fma_mix_f32 v19, v46, v43, v19 op_sel:[0,1,0] op_sel_hi:[1,1,0]
	v_fma_mix_f32 v10, v20, v40, v16 op_sel:[0,0,0] op_sel_hi:[0,1,0]
	v_fma_mix_f32 v11, v20, v40, v17 op_sel:[0,1,0] op_sel_hi:[0,1,0]
	v_fma_mix_f32 v12, v20, v41, v18 op_sel:[0,0,0] op_sel_hi:[0,1,0]
	v_fma_mix_f32 v13, v20, v41, v19 op_sel:[0,1,0] op_sel_hi:[0,1,0]
	s_waitcnt lgkmcnt(0)
	ds_read_b64 v[24:25], v6 offset:7192
	ds_read_b128 v[26:29], v6 offset:7440
	ds_read_b128 v[30:33], v6 offset:7696
	ds_read_u16 v34, v7 offset:7184
	v_fma_mix_f32 v14, v10, v74, 0 op_sel:[0,0,0] op_sel_hi:[0,1,0]
	v_fma_mix_f32 v53, v10, v44, 0 op_sel:[0,0,0] op_sel_hi:[0,1,0]
	v_fma_mix_f32 v14, v11, v74, v14 op_sel:[0,1,0] op_sel_hi:[0,1,0]
	v_fma_mix_f32 v53, v11, v44, v53 op_sel:[0,1,0] op_sel_hi:[0,1,0]
	v_fma_mix_f32 v14, v12, v75, v14 op_sel:[0,0,0] op_sel_hi:[0,1,0]
	v_fma_mix_f32 v53, v12, v45, v53 op_sel:[0,0,0] op_sel_hi:[0,1,0]
	v_fma_mix_f32 v14, v13, v75, v14 op_sel:[0,1,0] op_sel_hi:[0,1,0]
	v_fma_mix_f32 v16, v10, v72, 0 op_sel:[0,0,0] op_sel_hi:[0,1,0]
	v_fma_mix_f32 v17, v11, v72, 0 op_sel:[0,1,0] op_sel_hi:[0,1,0]
	v_add_f32_dpp v20, v14, v14 quad_perm:[1,0,3,2] row_mask:0xf bank_mask:0xf bound_ctrl:1
	v_fma_mix_f32 v53, v13, v45, v53 op_sel:[0,1,0] op_sel_hi:[0,1,0]
	v_fma_mix_f32 v18, v12, v73, 0 op_sel:[0,0,0] op_sel_hi:[0,1,0]
	v_add_f32_dpp v20, v20, v20 quad_perm:[2,3,0,1] row_mask:0xf bank_mask:0xf bound_ctrl:1
	v_fma_mix_f32 v19, v13, v73, 0 op_sel:[0,1,0] op_sel_hi:[0,1,0]
	v_fma_mix_f32 v16, v82, v78, v16 op_sel:[0,0,0] op_sel_hi:[1,1,0]
	v_add_f32_dpp v20, v20, v20 row_half_mirror row_mask:0xf bank_mask:0xf bound_ctrl:1
	v_fma_mix_f32 v17, v82, v78, v17 op_sel:[0,1,0] op_sel_hi:[1,1,0]
	v_fma_mix_f32 v18, v82, v79, v18 op_sel:[0,0,0] op_sel_hi:[1,1,0]
	v_add_f32_dpp v20, v20, v20 row_mirror row_mask:0xf bank_mask:0xf bound_ctrl:1
	v_fma_mix_f32 v19, v82, v79, v19 op_sel:[0,1,0] op_sel_hi:[1,1,0]
	v_fma_mix_f32 v10, v20, v76, v16 op_sel:[0,0,0] op_sel_hi:[0,1,0]
	v_fma_mix_f32 v11, v20, v76, v17 op_sel:[0,1,0] op_sel_hi:[0,1,0]
	v_fma_mix_f32 v12, v20, v77, v18 op_sel:[0,0,0] op_sel_hi:[0,1,0]
	v_fma_mix_f32 v13, v20, v77, v19 op_sel:[0,1,0] op_sel_hi:[0,1,0]
	ds_read_b64 v[36:37], v6 offset:6168
	ds_read_b128 v[38:41], v6 offset:6416
	ds_read_b128 v[42:45], v6 offset:6672
	ds_read_u16 v46, v7 offset:6160
	v_fma_mix_f32 v14, v10, v86, 0 op_sel:[0,0,0] op_sel_hi:[0,1,0]
	v_fma_mix_f32 v54, v10, v80, 0 op_sel:[0,0,0] op_sel_hi:[0,1,0]
	v_fma_mix_f32 v14, v11, v86, v14 op_sel:[0,1,0] op_sel_hi:[0,1,0]
	v_fma_mix_f32 v54, v11, v80, v54 op_sel:[0,1,0] op_sel_hi:[0,1,0]
	v_fma_mix_f32 v14, v12, v87, v14 op_sel:[0,0,0] op_sel_hi:[0,1,0]
	v_fma_mix_f32 v54, v12, v81, v54 op_sel:[0,0,0] op_sel_hi:[0,1,0]
	v_fma_mix_f32 v14, v13, v87, v14 op_sel:[0,1,0] op_sel_hi:[0,1,0]
	v_fma_mix_f32 v16, v10, v84, 0 op_sel:[0,0,0] op_sel_hi:[0,1,0]
	v_fma_mix_f32 v17, v11, v84, 0 op_sel:[0,1,0] op_sel_hi:[0,1,0]
	v_add_f32_dpp v20, v14, v14 quad_perm:[1,0,3,2] row_mask:0xf bank_mask:0xf bound_ctrl:1
	v_fma_mix_f32 v54, v13, v81, v54 op_sel:[0,1,0] op_sel_hi:[0,1,0]
	v_fma_mix_f32 v18, v12, v85, 0 op_sel:[0,0,0] op_sel_hi:[0,1,0]
	v_add_f32_dpp v20, v20, v20 quad_perm:[2,3,0,1] row_mask:0xf bank_mask:0xf bound_ctrl:1
	v_fma_mix_f32 v19, v13, v85, 0 op_sel:[0,1,0] op_sel_hi:[0,1,0]
	v_fma_mix_f32 v16, v94, v90, v16 op_sel:[0,0,0] op_sel_hi:[1,1,0]
	v_add_f32_dpp v20, v20, v20 row_half_mirror row_mask:0xf bank_mask:0xf bound_ctrl:1
	v_fma_mix_f32 v17, v94, v90, v17 op_sel:[0,1,0] op_sel_hi:[1,1,0]
	v_fma_mix_f32 v18, v94, v91, v18 op_sel:[0,0,0] op_sel_hi:[1,1,0]
	v_add_f32_dpp v20, v20, v20 row_mirror row_mask:0xf bank_mask:0xf bound_ctrl:1
	v_fma_mix_f32 v19, v94, v91, v19 op_sel:[0,1,0] op_sel_hi:[1,1,0]
	v_fma_mix_f32 v10, v20, v88, v16 op_sel:[0,0,0] op_sel_hi:[0,1,0]
	v_fma_mix_f32 v11, v20, v88, v17 op_sel:[0,1,0] op_sel_hi:[0,1,0]
	v_fma_mix_f32 v12, v20, v89, v18 op_sel:[0,0,0] op_sel_hi:[0,1,0]
	v_fma_mix_f32 v13, v20, v89, v19 op_sel:[0,1,0] op_sel_hi:[0,1,0]
	s_waitcnt lgkmcnt(0)
	ds_read_b64 v[72:73], v6 offset:5144
	ds_read_b128 v[74:77], v6 offset:5392
	ds_read_b128 v[78:81], v6 offset:5648
	ds_read_u16 v82, v7 offset:5136
	v_fma_mix_f32 v14, v10, v26, 0 op_sel:[0,0,0] op_sel_hi:[0,1,0]
	v_fma_mix_f32 v55, v10, v92, 0 op_sel:[0,0,0] op_sel_hi:[0,1,0]
	v_fma_mix_f32 v14, v11, v26, v14 op_sel:[0,1,0] op_sel_hi:[0,1,0]
	v_fma_mix_f32 v55, v11, v92, v55 op_sel:[0,1,0] op_sel_hi:[0,1,0]
	v_fma_mix_f32 v14, v12, v27, v14 op_sel:[0,0,0] op_sel_hi:[0,1,0]
	v_fma_mix_f32 v55, v12, v93, v55 op_sel:[0,0,0] op_sel_hi:[0,1,0]
	v_fma_mix_f32 v14, v13, v27, v14 op_sel:[0,1,0] op_sel_hi:[0,1,0]
	v_fma_mix_f32 v16, v10, v24, 0 op_sel:[0,0,0] op_sel_hi:[0,1,0]
	v_fma_mix_f32 v17, v11, v24, 0 op_sel:[0,1,0] op_sel_hi:[0,1,0]
	v_add_f32_dpp v20, v14, v14 quad_perm:[1,0,3,2] row_mask:0xf bank_mask:0xf bound_ctrl:1
	v_fma_mix_f32 v55, v13, v93, v55 op_sel:[0,1,0] op_sel_hi:[0,1,0]
	v_fma_mix_f32 v18, v12, v25, 0 op_sel:[0,0,0] op_sel_hi:[0,1,0]
	v_add_f32_dpp v20, v20, v20 quad_perm:[2,3,0,1] row_mask:0xf bank_mask:0xf bound_ctrl:1
	v_fma_mix_f32 v19, v13, v25, 0 op_sel:[0,1,0] op_sel_hi:[0,1,0]
	v_fma_mix_f32 v16, v34, v30, v16 op_sel:[0,0,0] op_sel_hi:[1,1,0]
	v_add_f32_dpp v20, v20, v20 row_half_mirror row_mask:0xf bank_mask:0xf bound_ctrl:1
	v_fma_mix_f32 v17, v34, v30, v17 op_sel:[0,1,0] op_sel_hi:[1,1,0]
	v_fma_mix_f32 v18, v34, v31, v18 op_sel:[0,0,0] op_sel_hi:[1,1,0]
	v_add_f32_dpp v20, v20, v20 row_mirror row_mask:0xf bank_mask:0xf bound_ctrl:1
	v_fma_mix_f32 v19, v34, v31, v19 op_sel:[0,1,0] op_sel_hi:[1,1,0]
	v_fma_mix_f32 v10, v20, v28, v16 op_sel:[0,0,0] op_sel_hi:[0,1,0]
	v_fma_mix_f32 v11, v20, v28, v17 op_sel:[0,1,0] op_sel_hi:[0,1,0]
	v_fma_mix_f32 v12, v20, v29, v18 op_sel:[0,0,0] op_sel_hi:[0,1,0]
	v_fma_mix_f32 v13, v20, v29, v19 op_sel:[0,1,0] op_sel_hi:[0,1,0]
	ds_read_b64 v[84:85], v6 offset:4120
	ds_read_b128 v[86:89], v6 offset:4368
	ds_read_b128 v[90:93], v6 offset:4624
	ds_read_u16 v94, v7 offset:4112
	v_fma_mix_f32 v14, v10, v38, 0 op_sel:[0,0,0] op_sel_hi:[0,1,0]
	v_fma_mix_f32 v56, v10, v32, 0 op_sel:[0,0,0] op_sel_hi:[0,1,0]
	v_fma_mix_f32 v14, v11, v38, v14 op_sel:[0,1,0] op_sel_hi:[0,1,0]
	v_fma_mix_f32 v56, v11, v32, v56 op_sel:[0,1,0] op_sel_hi:[0,1,0]
	v_fma_mix_f32 v14, v12, v39, v14 op_sel:[0,0,0] op_sel_hi:[0,1,0]
	v_fma_mix_f32 v56, v12, v33, v56 op_sel:[0,0,0] op_sel_hi:[0,1,0]
	v_fma_mix_f32 v14, v13, v39, v14 op_sel:[0,1,0] op_sel_hi:[0,1,0]
	v_fma_mix_f32 v16, v10, v36, 0 op_sel:[0,0,0] op_sel_hi:[0,1,0]
	v_fma_mix_f32 v17, v11, v36, 0 op_sel:[0,1,0] op_sel_hi:[0,1,0]
	v_add_f32_dpp v20, v14, v14 quad_perm:[1,0,3,2] row_mask:0xf bank_mask:0xf bound_ctrl:1
	v_fma_mix_f32 v56, v13, v33, v56 op_sel:[0,1,0] op_sel_hi:[0,1,0]
	v_fma_mix_f32 v18, v12, v37, 0 op_sel:[0,0,0] op_sel_hi:[0,1,0]
	v_add_f32_dpp v20, v20, v20 quad_perm:[2,3,0,1] row_mask:0xf bank_mask:0xf bound_ctrl:1
	v_fma_mix_f32 v19, v13, v37, 0 op_sel:[0,1,0] op_sel_hi:[0,1,0]
	v_fma_mix_f32 v16, v46, v42, v16 op_sel:[0,0,0] op_sel_hi:[1,1,0]
	v_add_f32_dpp v20, v20, v20 row_half_mirror row_mask:0xf bank_mask:0xf bound_ctrl:1
	v_fma_mix_f32 v17, v46, v42, v17 op_sel:[0,1,0] op_sel_hi:[1,1,0]
	v_fma_mix_f32 v18, v46, v43, v18 op_sel:[0,0,0] op_sel_hi:[1,1,0]
	v_add_f32_dpp v20, v20, v20 row_mirror row_mask:0xf bank_mask:0xf bound_ctrl:1
	v_fma_mix_f32 v19, v46, v43, v19 op_sel:[0,1,0] op_sel_hi:[1,1,0]
	v_fma_mix_f32 v10, v20, v40, v16 op_sel:[0,0,0] op_sel_hi:[0,1,0]
	v_fma_mix_f32 v11, v20, v40, v17 op_sel:[0,1,0] op_sel_hi:[0,1,0]
	v_fma_mix_f32 v12, v20, v41, v18 op_sel:[0,0,0] op_sel_hi:[0,1,0]
	v_fma_mix_f32 v13, v20, v41, v19 op_sel:[0,1,0] op_sel_hi:[0,1,0]
	s_waitcnt lgkmcnt(0)
	ds_read_b64 v[24:25], v6 offset:3096
	ds_read_b128 v[26:29], v6 offset:3344
	ds_read_b128 v[30:33], v6 offset:3600
	ds_read_u16 v34, v7 offset:3088
	v_fma_mix_f32 v14, v10, v74, 0 op_sel:[0,0,0] op_sel_hi:[0,1,0]
	v_fma_mix_f32 v57, v10, v44, 0 op_sel:[0,0,0] op_sel_hi:[0,1,0]
	v_fma_mix_f32 v14, v11, v74, v14 op_sel:[0,1,0] op_sel_hi:[0,1,0]
	v_fma_mix_f32 v57, v11, v44, v57 op_sel:[0,1,0] op_sel_hi:[0,1,0]
	v_fma_mix_f32 v14, v12, v75, v14 op_sel:[0,0,0] op_sel_hi:[0,1,0]
	v_fma_mix_f32 v57, v12, v45, v57 op_sel:[0,0,0] op_sel_hi:[0,1,0]
	v_fma_mix_f32 v14, v13, v75, v14 op_sel:[0,1,0] op_sel_hi:[0,1,0]
	v_fma_mix_f32 v16, v10, v72, 0 op_sel:[0,0,0] op_sel_hi:[0,1,0]
	v_fma_mix_f32 v17, v11, v72, 0 op_sel:[0,1,0] op_sel_hi:[0,1,0]
	v_add_f32_dpp v20, v14, v14 quad_perm:[1,0,3,2] row_mask:0xf bank_mask:0xf bound_ctrl:1
	v_fma_mix_f32 v57, v13, v45, v57 op_sel:[0,1,0] op_sel_hi:[0,1,0]
	v_fma_mix_f32 v18, v12, v73, 0 op_sel:[0,0,0] op_sel_hi:[0,1,0]
	v_add_f32_dpp v20, v20, v20 quad_perm:[2,3,0,1] row_mask:0xf bank_mask:0xf bound_ctrl:1
	v_fma_mix_f32 v19, v13, v73, 0 op_sel:[0,1,0] op_sel_hi:[0,1,0]
	v_fma_mix_f32 v16, v82, v78, v16 op_sel:[0,0,0] op_sel_hi:[1,1,0]
	v_add_f32_dpp v20, v20, v20 row_half_mirror row_mask:0xf bank_mask:0xf bound_ctrl:1
	v_fma_mix_f32 v17, v82, v78, v17 op_sel:[0,1,0] op_sel_hi:[1,1,0]
	v_fma_mix_f32 v18, v82, v79, v18 op_sel:[0,0,0] op_sel_hi:[1,1,0]
	v_add_f32_dpp v20, v20, v20 row_mirror row_mask:0xf bank_mask:0xf bound_ctrl:1
	v_fma_mix_f32 v19, v82, v79, v19 op_sel:[0,1,0] op_sel_hi:[1,1,0]
	v_fma_mix_f32 v10, v20, v76, v16 op_sel:[0,0,0] op_sel_hi:[0,1,0]
	v_fma_mix_f32 v11, v20, v76, v17 op_sel:[0,1,0] op_sel_hi:[0,1,0]
	v_fma_mix_f32 v12, v20, v77, v18 op_sel:[0,0,0] op_sel_hi:[0,1,0]
	v_fma_mix_f32 v13, v20, v77, v19 op_sel:[0,1,0] op_sel_hi:[0,1,0]
	ds_read_b64 v[36:37], v6 offset:2072
	ds_read_b128 v[38:41], v6 offset:2320
	ds_read_b128 v[42:45], v6 offset:2576
	ds_read_u16 v46, v7 offset:2064
	v_fma_mix_f32 v14, v10, v86, 0 op_sel:[0,0,0] op_sel_hi:[0,1,0]
	v_fma_mix_f32 v58, v10, v80, 0 op_sel:[0,0,0] op_sel_hi:[0,1,0]
	v_fma_mix_f32 v14, v11, v86, v14 op_sel:[0,1,0] op_sel_hi:[0,1,0]
	v_fma_mix_f32 v58, v11, v80, v58 op_sel:[0,1,0] op_sel_hi:[0,1,0]
	v_fma_mix_f32 v14, v12, v87, v14 op_sel:[0,0,0] op_sel_hi:[0,1,0]
	v_fma_mix_f32 v58, v12, v81, v58 op_sel:[0,0,0] op_sel_hi:[0,1,0]
	v_fma_mix_f32 v14, v13, v87, v14 op_sel:[0,1,0] op_sel_hi:[0,1,0]
	v_fma_mix_f32 v16, v10, v84, 0 op_sel:[0,0,0] op_sel_hi:[0,1,0]
	v_fma_mix_f32 v17, v11, v84, 0 op_sel:[0,1,0] op_sel_hi:[0,1,0]
	v_add_f32_dpp v20, v14, v14 quad_perm:[1,0,3,2] row_mask:0xf bank_mask:0xf bound_ctrl:1
	v_fma_mix_f32 v58, v13, v81, v58 op_sel:[0,1,0] op_sel_hi:[0,1,0]
	v_fma_mix_f32 v18, v12, v85, 0 op_sel:[0,0,0] op_sel_hi:[0,1,0]
	v_add_f32_dpp v20, v20, v20 quad_perm:[2,3,0,1] row_mask:0xf bank_mask:0xf bound_ctrl:1
	v_fma_mix_f32 v19, v13, v85, 0 op_sel:[0,1,0] op_sel_hi:[0,1,0]
	v_fma_mix_f32 v16, v94, v90, v16 op_sel:[0,0,0] op_sel_hi:[1,1,0]
	v_add_f32_dpp v20, v20, v20 row_half_mirror row_mask:0xf bank_mask:0xf bound_ctrl:1
	v_fma_mix_f32 v17, v94, v90, v17 op_sel:[0,1,0] op_sel_hi:[1,1,0]
	v_fma_mix_f32 v18, v94, v91, v18 op_sel:[0,0,0] op_sel_hi:[1,1,0]
	v_add_f32_dpp v20, v20, v20 row_mirror row_mask:0xf bank_mask:0xf bound_ctrl:1
	v_fma_mix_f32 v19, v94, v91, v19 op_sel:[0,1,0] op_sel_hi:[1,1,0]
	v_fma_mix_f32 v10, v20, v88, v16 op_sel:[0,0,0] op_sel_hi:[0,1,0]
	v_fma_mix_f32 v11, v20, v88, v17 op_sel:[0,1,0] op_sel_hi:[0,1,0]
	v_fma_mix_f32 v12, v20, v89, v18 op_sel:[0,0,0] op_sel_hi:[0,1,0]
	v_fma_mix_f32 v13, v20, v89, v19 op_sel:[0,1,0] op_sel_hi:[0,1,0]
	s_waitcnt lgkmcnt(0)
	ds_read_b64 v[72:73], v6 offset:1048
	ds_read_b128 v[74:77], v6 offset:1296
	ds_read_b128 v[78:81], v6 offset:1552
	ds_read_u16 v82, v7 offset:1040
	v_fma_mix_f32 v14, v10, v26, 0 op_sel:[0,0,0] op_sel_hi:[0,1,0]
	v_fma_mix_f32 v59, v10, v92, 0 op_sel:[0,0,0] op_sel_hi:[0,1,0]
	v_fma_mix_f32 v14, v11, v26, v14 op_sel:[0,1,0] op_sel_hi:[0,1,0]
	v_fma_mix_f32 v59, v11, v92, v59 op_sel:[0,1,0] op_sel_hi:[0,1,0]
	v_fma_mix_f32 v14, v12, v27, v14 op_sel:[0,0,0] op_sel_hi:[0,1,0]
	v_fma_mix_f32 v59, v12, v93, v59 op_sel:[0,0,0] op_sel_hi:[0,1,0]
	v_fma_mix_f32 v14, v13, v27, v14 op_sel:[0,1,0] op_sel_hi:[0,1,0]
	v_fma_mix_f32 v16, v10, v24, 0 op_sel:[0,0,0] op_sel_hi:[0,1,0]
	v_fma_mix_f32 v17, v11, v24, 0 op_sel:[0,1,0] op_sel_hi:[0,1,0]
	v_add_f32_dpp v20, v14, v14 quad_perm:[1,0,3,2] row_mask:0xf bank_mask:0xf bound_ctrl:1
	v_fma_mix_f32 v59, v13, v93, v59 op_sel:[0,1,0] op_sel_hi:[0,1,0]
	v_fma_mix_f32 v18, v12, v25, 0 op_sel:[0,0,0] op_sel_hi:[0,1,0]
	v_add_f32_dpp v20, v20, v20 quad_perm:[2,3,0,1] row_mask:0xf bank_mask:0xf bound_ctrl:1
	v_fma_mix_f32 v19, v13, v25, 0 op_sel:[0,1,0] op_sel_hi:[0,1,0]
	v_fma_mix_f32 v16, v34, v30, v16 op_sel:[0,0,0] op_sel_hi:[1,1,0]
	v_add_f32_dpp v20, v20, v20 row_half_mirror row_mask:0xf bank_mask:0xf bound_ctrl:1
	v_fma_mix_f32 v17, v34, v30, v17 op_sel:[0,1,0] op_sel_hi:[1,1,0]
	v_fma_mix_f32 v18, v34, v31, v18 op_sel:[0,0,0] op_sel_hi:[1,1,0]
	v_add_f32_dpp v20, v20, v20 row_mirror row_mask:0xf bank_mask:0xf bound_ctrl:1
	v_fma_mix_f32 v19, v34, v31, v19 op_sel:[0,1,0] op_sel_hi:[1,1,0]
	v_fma_mix_f32 v10, v20, v28, v16 op_sel:[0,0,0] op_sel_hi:[0,1,0]
	v_fma_mix_f32 v11, v20, v28, v17 op_sel:[0,1,0] op_sel_hi:[0,1,0]
	v_fma_mix_f32 v12, v20, v29, v18 op_sel:[0,0,0] op_sel_hi:[0,1,0]
	v_fma_mix_f32 v13, v20, v29, v19 op_sel:[0,1,0] op_sel_hi:[0,1,0]
	ds_read_b128 v[100:103], v9
	ds_read_b64 v[84:85], v6 offset:24
	ds_read_b128 v[86:89], v6 offset:272
	ds_read_b128 v[90:93], v6 offset:528
	ds_read_u16 v94, v7 offset:16
	v_fma_mix_f32 v14, v10, v38, 0 op_sel:[0,0,0] op_sel_hi:[0,1,0]
	v_fma_mix_f32 v60, v10, v32, 0 op_sel:[0,0,0] op_sel_hi:[0,1,0]
	v_fma_mix_f32 v14, v11, v38, v14 op_sel:[0,1,0] op_sel_hi:[0,1,0]
	v_fma_mix_f32 v60, v11, v32, v60 op_sel:[0,1,0] op_sel_hi:[0,1,0]
	v_fma_mix_f32 v14, v12, v39, v14 op_sel:[0,0,0] op_sel_hi:[0,1,0]
	v_fma_mix_f32 v60, v12, v33, v60 op_sel:[0,0,0] op_sel_hi:[0,1,0]
	v_fma_mix_f32 v14, v13, v39, v14 op_sel:[0,1,0] op_sel_hi:[0,1,0]
	v_fma_mix_f32 v16, v10, v36, 0 op_sel:[0,0,0] op_sel_hi:[0,1,0]
	v_fma_mix_f32 v17, v11, v36, 0 op_sel:[0,1,0] op_sel_hi:[0,1,0]
	v_add_f32_dpp v20, v14, v14 quad_perm:[1,0,3,2] row_mask:0xf bank_mask:0xf bound_ctrl:1
	v_fma_mix_f32 v60, v13, v33, v60 op_sel:[0,1,0] op_sel_hi:[0,1,0]
	v_fma_mix_f32 v18, v12, v37, 0 op_sel:[0,0,0] op_sel_hi:[0,1,0]
	v_add_f32_dpp v20, v20, v20 quad_perm:[2,3,0,1] row_mask:0xf bank_mask:0xf bound_ctrl:1
	v_fma_mix_f32 v19, v13, v37, 0 op_sel:[0,1,0] op_sel_hi:[0,1,0]
	v_fma_mix_f32 v16, v46, v42, v16 op_sel:[0,0,0] op_sel_hi:[1,1,0]
	v_add_f32_dpp v20, v20, v20 row_half_mirror row_mask:0xf bank_mask:0xf bound_ctrl:1
	v_fma_mix_f32 v17, v46, v42, v17 op_sel:[0,1,0] op_sel_hi:[1,1,0]
	v_fma_mix_f32 v18, v46, v43, v18 op_sel:[0,0,0] op_sel_hi:[1,1,0]
	v_add_f32_dpp v20, v20, v20 row_mirror row_mask:0xf bank_mask:0xf bound_ctrl:1
	v_fma_mix_f32 v19, v46, v43, v19 op_sel:[0,1,0] op_sel_hi:[1,1,0]
	v_fma_mix_f32 v10, v20, v40, v16 op_sel:[0,0,0] op_sel_hi:[0,1,0]
	v_fma_mix_f32 v11, v20, v40, v17 op_sel:[0,1,0] op_sel_hi:[0,1,0]
	v_fma_mix_f32 v12, v20, v41, v18 op_sel:[0,0,0] op_sel_hi:[0,1,0]
	v_fma_mix_f32 v13, v20, v41, v19 op_sel:[0,1,0] op_sel_hi:[0,1,0]
	s_waitcnt lgkmcnt(0)
	v_add_u32_e32 v6, 0xffffc000, v6
	v_add_u32_e32 v7, 0xffffc000, v7
	v_and_b32_e32 v6, 0x1ffff, v6
	v_and_b32_e32 v7, 0x1ffff, v7
	ds_read_b64 v[24:25], v6 offset:15384
	ds_read_b128 v[26:29], v6 offset:15632
	ds_read_b128 v[30:33], v6 offset:15888
	ds_read_u16 v34, v7 offset:15376
	v_fma_mix_f32 v14, v10, v74, 0 op_sel:[0,0,0] op_sel_hi:[0,1,0]
	v_fma_mix_f32 v61, v10, v44, 0 op_sel:[0,0,0] op_sel_hi:[0,1,0]
	v_fma_mix_f32 v14, v11, v74, v14 op_sel:[0,1,0] op_sel_hi:[0,1,0]
	v_fma_mix_f32 v61, v11, v44, v61 op_sel:[0,1,0] op_sel_hi:[0,1,0]
	v_fma_mix_f32 v14, v12, v75, v14 op_sel:[0,0,0] op_sel_hi:[0,1,0]
	v_fma_mix_f32 v61, v12, v45, v61 op_sel:[0,0,0] op_sel_hi:[0,1,0]
	v_fma_mix_f32 v14, v13, v75, v14 op_sel:[0,1,0] op_sel_hi:[0,1,0]
	v_fma_mix_f32 v16, v10, v72, 0 op_sel:[0,0,0] op_sel_hi:[0,1,0]
	v_fma_mix_f32 v17, v11, v72, 0 op_sel:[0,1,0] op_sel_hi:[0,1,0]
	v_add_f32_dpp v20, v14, v14 quad_perm:[1,0,3,2] row_mask:0xf bank_mask:0xf bound_ctrl:1
	v_fma_mix_f32 v61, v13, v45, v61 op_sel:[0,1,0] op_sel_hi:[0,1,0]
	v_fma_mix_f32 v18, v12, v73, 0 op_sel:[0,0,0] op_sel_hi:[0,1,0]
	v_add_f32_dpp v20, v20, v20 quad_perm:[2,3,0,1] row_mask:0xf bank_mask:0xf bound_ctrl:1
	v_fma_mix_f32 v19, v13, v73, 0 op_sel:[0,1,0] op_sel_hi:[0,1,0]
	v_fma_mix_f32 v16, v82, v78, v16 op_sel:[0,0,0] op_sel_hi:[1,1,0]
	v_add_f32_dpp v20, v20, v20 row_half_mirror row_mask:0xf bank_mask:0xf bound_ctrl:1
	v_fma_mix_f32 v17, v82, v78, v17 op_sel:[0,1,0] op_sel_hi:[1,1,0]
	v_fma_mix_f32 v18, v82, v79, v18 op_sel:[0,0,0] op_sel_hi:[1,1,0]
	v_add_f32_dpp v20, v20, v20 row_mirror row_mask:0xf bank_mask:0xf bound_ctrl:1
	v_fma_mix_f32 v19, v82, v79, v19 op_sel:[0,1,0] op_sel_hi:[1,1,0]
	v_fma_mix_f32 v10, v20, v76, v16 op_sel:[0,0,0] op_sel_hi:[0,1,0]
	v_fma_mix_f32 v11, v20, v76, v17 op_sel:[0,1,0] op_sel_hi:[0,1,0]
	v_fma_mix_f32 v12, v20, v77, v18 op_sel:[0,0,0] op_sel_hi:[0,1,0]
	v_fma_mix_f32 v13, v20, v77, v19 op_sel:[0,1,0] op_sel_hi:[0,1,0]
; DEVINL u16 f2bf(float a) { return (u16)(pk2(a, 0.f) & 0xffffu); }
; #define RW_STEP2(B) RW_STEP(B, WvA, XA, KrA, vhA, WvB, XB, KrB, vhB); RW_STEP((B) + 1, WvB, XB, KrB, vhB, WvA, XA, KrA, vhA)
; #define RW_STEP4(B) RW_STEP2(B); RW_STEP2((B) + 2)
; template <int DIR>
; DEVINL void rwkv_scan_dir(const Params& p, int task, int lane, int wave) {
;     ...
;     if (st > 0) { const int q0 = st - 16 + seg; yo[(long)(DIR ? (4095 - q0) : q0) * 1024] = f2bf(ykeep); }
;     RW_STEP(1, WvB, XB, KrB, vhB, WvA, XA, KrA, vhA);
;     RW_STEP2(2); RW_STEP4(4); RW_STEP4(8); RW_STEP4(12);
;     RW_STEP(16, WvA, XA, KrA, vhA, WvB, XB, KrB, vhB);
;     { const int q0 = st + seg; yo[(long)(DIR ? (4095 - q0) : q0) * 1024] = f2bf(ykeep); }
	ds_read_b64 v[36:37], v6 offset:14360
	ds_read_b128 v[38:41], v6 offset:14608
	ds_read_b128 v[42:45], v6 offset:14864
	ds_read_u16 v46, v7 offset:14352
	v_fma_mix_f32 v14, v10, v86, 0 op_sel:[0,0,0] op_sel_hi:[0,1,0]
	v_fma_mix_f32 v62, v10, v80, 0 op_sel:[0,0,0] op_sel_hi:[0,1,0]
	v_fma_mix_f32 v14, v11, v86, v14 op_sel:[0,1,0] op_sel_hi:[0,1,0]
	v_fma_mix_f32 v62, v11, v80, v62 op_sel:[0,1,0] op_sel_hi:[0,1,0]
	v_fma_mix_f32 v14, v12, v87, v14 op_sel:[0,0,0] op_sel_hi:[0,1,0]
	v_fma_mix_f32 v62, v12, v81, v62 op_sel:[0,0,0] op_sel_hi:[0,1,0]
	v_fma_mix_f32 v14, v13, v87, v14 op_sel:[0,1,0] op_sel_hi:[0,1,0]
	v_fma_mix_f32 v16, v10, v84, 0 op_sel:[0,0,0] op_sel_hi:[0,1,0]
	v_fma_mix_f32 v17, v11, v84, 0 op_sel:[0,1,0] op_sel_hi:[0,1,0]
	v_add_f32_dpp v20, v14, v14 quad_perm:[1,0,3,2] row_mask:0xf bank_mask:0xf bound_ctrl:1
	v_fma_mix_f32 v62, v13, v81, v62 op_sel:[0,1,0] op_sel_hi:[0,1,0]
	v_fma_mix_f32 v18, v12, v85, 0 op_sel:[0,0,0] op_sel_hi:[0,1,0]
	v_add_f32_dpp v20, v20, v20 quad_perm:[2,3,0,1] row_mask:0xf bank_mask:0xf bound_ctrl:1
	v_fma_mix_f32 v19, v13, v85, 0 op_sel:[0,1,0] op_sel_hi:[0,1,0]
	v_fma_mix_f32 v16, v94, v90, v16 op_sel:[0,0,0] op_sel_hi:[1,1,0]
	v_add_f32_dpp v20, v20, v20 row_half_mirror row_mask:0xf bank_mask:0xf bound_ctrl:1
	v_fma_mix_f32 v17, v94, v90, v17 op_sel:[0,1,0] op_sel_hi:[1,1,0]
	v_fma_mix_f32 v18, v94, v91, v18 op_sel:[0,0,0] op_sel_hi:[1,1,0]
	v_add_f32_dpp v20, v20, v20 row_mirror row_mask:0xf bank_mask:0xf bound_ctrl:1
	v_fma_mix_f32 v19, v94, v91, v19 op_sel:[0,1,0] op_sel_hi:[1,1,0]
	v_fma_mix_f32 v10, v20, v88, v16 op_sel:[0,0,0] op_sel_hi:[0,1,0]
	v_fma_mix_f32 v11, v20, v88, v17 op_sel:[0,1,0] op_sel_hi:[0,1,0]
	v_fma_mix_f32 v12, v20, v89, v18 op_sel:[0,0,0] op_sel_hi:[0,1,0]
	v_fma_mix_f32 v13, v20, v89, v19 op_sel:[0,1,0] op_sel_hi:[0,1,0]
	s_waitcnt lgkmcnt(0)
	s_add_u32 s43, s43, 1
	s_waitcnt vmcnt(0)
	v_add_u32_e32 v69, 1, v69
	ds_write_b32 v23, v69
	v_min3_u32 v100, v100, v101, v102
	v_min_u32_e32 v100, v100, v103
	s_nop 0
	v_readfirstlane_b32 s24, v100
	s_nop 0
	s_cmp_ge_u32 s24, s43
	s_cbranch_scc0 .Lrw_slow_d1b1
.Lrw_ready_d1b1:
	s_add_u32 m0, s41, 16
	s_nop 0
	global_load_lds_dwordx4 v5, s[10:11] offset:0
	global_load_lds_dwordx4 v5, s[10:11] offset:1024
	global_load_lds_dwordx4 v5, s[10:11] offset:2048
	global_load_lds_dwordx4 v5, s[10:11] offset:3072
	s_sub_u32 s10, s10, 0x4000
	s_subb_u32 s11, s11, 0
	s_sub_u32 s41, s41, 0x4000
	s_and_b32 s41, s41, 0x1ffff
	ds_read_b64 v[72:73], v6 offset:13336
	ds_read_b128 v[74:77], v6 offset:13584
	ds_read_b128 v[78:81], v6 offset:13840
	ds_read_u16 v82, v7 offset:13328
	v_fma_mix_f32 v14, v10, v26, 0 op_sel:[0,0,0] op_sel_hi:[0,1,0]
	v_fma_mix_f32 v63, v10, v92, 0 op_sel:[0,0,0] op_sel_hi:[0,1,0]
	v_fma_mix_f32 v14, v11, v26, v14 op_sel:[0,1,0] op_sel_hi:[0,1,0]
	v_fma_mix_f32 v63, v11, v92, v63 op_sel:[0,1,0] op_sel_hi:[0,1,0]
	v_fma_mix_f32 v14, v12, v27, v14 op_sel:[0,0,0] op_sel_hi:[0,1,0]
	v_fma_mix_f32 v63, v12, v93, v63 op_sel:[0,0,0] op_sel_hi:[0,1,0]
	v_fma_mix_f32 v14, v13, v27, v14 op_sel:[0,1,0] op_sel_hi:[0,1,0]
	v_fma_mix_f32 v16, v10, v24, 0 op_sel:[0,0,0] op_sel_hi:[0,1,0]
	v_fma_mix_f32 v17, v11, v24, 0 op_sel:[0,1,0] op_sel_hi:[0,1,0]
	v_add_f32_dpp v20, v14, v14 quad_perm:[1,0,3,2] row_mask:0xf bank_mask:0xf bound_ctrl:1
	v_fma_mix_f32 v63, v13, v93, v63 op_sel:[0,1,0] op_sel_hi:[0,1,0]
	v_fma_mix_f32 v18, v12, v25, 0 op_sel:[0,0,0] op_sel_hi:[0,1,0]
	v_add_f32_dpp v20, v20, v20 quad_perm:[2,3,0,1] row_mask:0xf bank_mask:0xf bound_ctrl:1
	v_fma_mix_f32 v19, v13, v25, 0 op_sel:[0,1,0] op_sel_hi:[0,1,0]
	v_fma_mix_f32 v16, v34, v30, v16 op_sel:[0,0,0] op_sel_hi:[1,1,0]
	v_add_f32_dpp v20, v20, v20 row_half_mirror row_mask:0xf bank_mask:0xf bound_ctrl:1
	v_fma_mix_f32 v17, v34, v30, v17 op_sel:[0,1,0] op_sel_hi:[1,1,0]
	v_fma_mix_f32 v18, v34, v31, v18 op_sel:[0,0,0] op_sel_hi:[1,1,0]
	v_add_f32_dpp v20, v20, v20 row_mirror row_mask:0xf bank_mask:0xf bound_ctrl:1
	v_fma_mix_f32 v19, v34, v31, v19 op_sel:[0,1,0] op_sel_hi:[1,1,0]
	v_fma_mix_f32 v10, v20, v28, v16 op_sel:[0,0,0] op_sel_hi:[0,1,0]
	v_fma_mix_f32 v11, v20, v28, v17 op_sel:[0,1,0] op_sel_hi:[0,1,0]
	v_fma_mix_f32 v12, v20, v29, v18 op_sel:[0,0,0] op_sel_hi:[0,1,0]
	v_fma_mix_f32 v13, v20, v29, v19 op_sel:[0,1,0] op_sel_hi:[0,1,0]
	v_add_f32_dpp v48, v48, v48 row_ror:8 row_mask:0xf bank_mask:0x3
	v_add_f32_dpp v49, v49, v49 row_ror:8 row_mask:0xf bank_mask:0x3
	v_add_f32_dpp v50, v50, v50 row_ror:8 row_mask:0xf bank_mask:0x3
	v_add_f32_dpp v51, v51, v51 row_ror:8 row_mask:0xf bank_mask:0x3
	v_add_f32_dpp v52, v52, v52 row_ror:8 row_mask:0xf bank_mask:0x3
	v_add_f32_dpp v53, v53, v53 row_ror:8 row_mask:0xf bank_mask:0x3
	v_add_f32_dpp v54, v54, v54 row_ror:8 row_mask:0xf bank_mask:0x3
	v_add_f32_dpp v55, v55, v55 row_ror:8 row_mask:0xf bank_mask:0x3
	v_add_f32_dpp v48, v56, v56 row_ror:8 row_mask:0xf bank_mask:0xc
	v_add_f32_dpp v49, v57, v57 row_ror:8 row_mask:0xf bank_mask:0xc
	v_add_f32_dpp v50, v58, v58 row_ror:8 row_mask:0xf bank_mask:0xc
	v_add_f32_dpp v51, v59, v59 row_ror:8 row_mask:0xf bank_mask:0xc
	v_add_f32_dpp v52, v60, v60 row_ror:8 row_mask:0xf bank_mask:0xc
	v_add_f32_dpp v53, v61, v61 row_ror:8 row_mask:0xf bank_mask:0xc
	v_add_f32_dpp v54, v62, v62 row_ror:8 row_mask:0xf bank_mask:0xc
	v_add_f32_dpp v55, v63, v63 row_ror:8 row_mask:0xf bank_mask:0xc
	v_add_f32_dpp v48, v48, v48 row_ror:12 row_mask:0xf bank_mask:0x5
	v_add_f32_dpp v49, v49, v49 row_ror:12 row_mask:0xf bank_mask:0x5
	v_add_f32_dpp v50, v50, v50 row_ror:12 row_mask:0xf bank_mask:0x5
	v_add_f32_dpp v51, v51, v51 row_ror:12 row_mask:0xf bank_mask:0x5
; DEVINL u16 f2bf(float a) { return (u16)(pk2(a, 0.f) & 0xffffu); }
; #define RW_STEP2(B) RW_STEP(B, WvA, XA, KrA, vhA, WvB, XB, KrB, vhB); RW_STEP((B) + 1, WvB, XB, KrB, vhB, WvA, XA, KrA, vhA)
; #define RW_STEP4(B) RW_STEP2(B); RW_STEP2((B) + 2)
; template <int DIR>
; DEVINL void rwkv_scan_dir(const Params& p, int task, int lane, int wave) {
;     ...
;     if (st > 0) { const int q0 = st - 16 + seg; yo[(long)(DIR ? (4095 - q0) : q0) * 1024] = f2bf(ykeep); }
;     RW_STEP(1, WvB, XB, KrB, vhB, WvA, XA, KrA, vhA);
;     RW_STEP2(2); RW_STEP4(4); RW_STEP4(8); RW_STEP4(12);
;     RW_STEP(16, WvA, XA, KrA, vhA, WvB, XB, KrB, vhB);
;     { const int q0 = st + seg; yo[(long)(DIR ? (4095 - q0) : q0) * 1024] = f2bf(ykeep); }
	v_add_f32_dpp v48, v52, v52 row_ror:4 row_mask:0xf bank_mask:0xa
	v_add_f32_dpp v49, v53, v53 row_ror:4 row_mask:0xf bank_mask:0xa
	v_add_f32_dpp v50, v54, v54 row_ror:4 row_mask:0xf bank_mask:0xa
	v_add_f32_dpp v51, v55, v55 row_ror:4 row_mask:0xf bank_mask:0xa
	v_add_f32_dpp v64, v48, v48 quad_perm:[2,3,0,1] row_mask:0xf bank_mask:0xf bound_ctrl:1
	v_add_f32_dpp v65, v50, v50 quad_perm:[2,3,0,1] row_mask:0xf bank_mask:0xf bound_ctrl:1
	v_cndmask_b32_e64 v56, v64, v65, s[50:51]
	v_add_f32_dpp v64, v49, v49 quad_perm:[2,3,0,1] row_mask:0xf bank_mask:0xf bound_ctrl:1
	v_add_f32_dpp v65, v51, v51 quad_perm:[2,3,0,1] row_mask:0xf bank_mask:0xf bound_ctrl:1
	v_cndmask_b32_e64 v57, v64, v65, s[50:51]
	v_add_f32_dpp v64, v56, v56 quad_perm:[1,0,3,2] row_mask:0xf bank_mask:0xf bound_ctrl:1
	s_nop 0
	v_add_f32_dpp v65, v57, v57 quad_perm:[1,0,3,2] row_mask:0xf bank_mask:0xf bound_ctrl:1
	v_cndmask_b32_e64 v66, v64, v65, s[48:49]
	v_cvt_pk_bf16_f32 v66, v66, v66
	global_store_short v8, v66, s[12:13]
	s_sub_u32 s12, s12, 0x8000
	s_subb_u32 s13, s13, 0
	ds_read_b64 v[84:85], v6 offset:12312
	ds_read_b128 v[86:89], v6 offset:12560
	ds_read_b128 v[90:93], v6 offset:12816
	ds_read_u16 v94, v7 offset:12304
	v_fma_mix_f32 v14, v10, v38, 0 op_sel:[0,0,0] op_sel_hi:[0,1,0]
	v_fma_mix_f32 v48, v10, v32, 0 op_sel:[0,0,0] op_sel_hi:[0,1,0]
	v_fma_mix_f32 v14, v11, v38, v14 op_sel:[0,1,0] op_sel_hi:[0,1,0]
	v_fma_mix_f32 v48, v11, v32, v48 op_sel:[0,1,0] op_sel_hi:[0,1,0]
	v_fma_mix_f32 v14, v12, v39, v14 op_sel:[0,0,0] op_sel_hi:[0,1,0]
	v_fma_mix_f32 v48, v12, v33, v48 op_sel:[0,0,0] op_sel_hi:[0,1,0]
	v_fma_mix_f32 v14, v13, v39, v14 op_sel:[0,1,0] op_sel_hi:[0,1,0]
	v_fma_mix_f32 v16, v10, v36, 0 op_sel:[0,0,0] op_sel_hi:[0,1,0]
	v_fma_mix_f32 v17, v11, v36, 0 op_sel:[0,1,0] op_sel_hi:[0,1,0]
	v_add_f32_dpp v20, v14, v14 quad_perm:[1,0,3,2] row_mask:0xf bank_mask:0xf bound_ctrl:1
	v_fma_mix_f32 v48, v13, v33, v48 op_sel:[0,1,0] op_sel_hi:[0,1,0]
	v_fma_mix_f32 v18, v12, v37, 0 op_sel:[0,0,0] op_sel_hi:[0,1,0]
	v_add_f32_dpp v20, v20, v20 quad_perm:[2,3,0,1] row_mask:0xf bank_mask:0xf bound_ctrl:1
	v_fma_mix_f32 v19, v13, v37, 0 op_sel:[0,1,0] op_sel_hi:[0,1,0]
	v_fma_mix_f32 v16, v46, v42, v16 op_sel:[0,0,0] op_sel_hi:[1,1,0]
	v_add_f32_dpp v20, v20, v20 row_half_mirror row_mask:0xf bank_mask:0xf bound_ctrl:1
	v_fma_mix_f32 v17, v46, v42, v17 op_sel:[0,1,0] op_sel_hi:[1,1,0]
	v_fma_mix_f32 v18, v46, v43, v18 op_sel:[0,0,0] op_sel_hi:[1,1,0]
	v_add_f32_dpp v20, v20, v20 row_mirror row_mask:0xf bank_mask:0xf bound_ctrl:1
	v_fma_mix_f32 v19, v46, v43, v19 op_sel:[0,1,0] op_sel_hi:[1,1,0]
	v_fma_mix_f32 v10, v20, v40, v16 op_sel:[0,0,0] op_sel_hi:[0,1,0]
	v_fma_mix_f32 v11, v20, v40, v17 op_sel:[0,1,0] op_sel_hi:[0,1,0]
	v_fma_mix_f32 v12, v20, v41, v18 op_sel:[0,0,0] op_sel_hi:[0,1,0]
	v_fma_mix_f32 v13, v20, v41, v19 op_sel:[0,1,0] op_sel_hi:[0,1,0]
	s_waitcnt lgkmcnt(0)
	ds_read_b64 v[24:25], v6 offset:11288
	ds_read_b128 v[26:29], v6 offset:11536
	ds_read_b128 v[30:33], v6 offset:11792
	ds_read_u16 v34, v7 offset:11280
	v_fma_mix_f32 v14, v10, v74, 0 op_sel:[0,0,0] op_sel_hi:[0,1,0]
	v_fma_mix_f32 v49, v10, v44, 0 op_sel:[0,0,0] op_sel_hi:[0,1,0]
	v_fma_mix_f32 v14, v11, v74, v14 op_sel:[0,1,0] op_sel_hi:[0,1,0]
	v_fma_mix_f32 v49, v11, v44, v49 op_sel:[0,1,0] op_sel_hi:[0,1,0]
	v_fma_mix_f32 v14, v12, v75, v14 op_sel:[0,0,0] op_sel_hi:[0,1,0]
	v_fma_mix_f32 v49, v12, v45, v49 op_sel:[0,0,0] op_sel_hi:[0,1,0]
	v_fma_mix_f32 v14, v13, v75, v14 op_sel:[0,1,0] op_sel_hi:[0,1,0]
	v_fma_mix_f32 v16, v10, v72, 0 op_sel:[0,0,0] op_sel_hi:[0,1,0]
	v_fma_mix_f32 v17, v11, v72, 0 op_sel:[0,1,0] op_sel_hi:[0,1,0]
	v_add_f32_dpp v20, v14, v14 quad_perm:[1,0,3,2] row_mask:0xf bank_mask:0xf bound_ctrl:1
	v_fma_mix_f32 v49, v13, v45, v49 op_sel:[0,1,0] op_sel_hi:[0,1,0]
	v_fma_mix_f32 v18, v12, v73, 0 op_sel:[0,0,0] op_sel_hi:[0,1,0]
	v_add_f32_dpp v20, v20, v20 quad_perm:[2,3,0,1] row_mask:0xf bank_mask:0xf bound_ctrl:1
	v_fma_mix_f32 v19, v13, v73, 0 op_sel:[0,1,0] op_sel_hi:[0,1,0]
	v_fma_mix_f32 v16, v82, v78, v16 op_sel:[0,0,0] op_sel_hi:[1,1,0]
	v_add_f32_dpp v20, v20, v20 row_half_mirror row_mask:0xf bank_mask:0xf bound_ctrl:1
	v_fma_mix_f32 v17, v82, v78, v17 op_sel:[0,1,0] op_sel_hi:[1,1,0]
	v_fma_mix_f32 v18, v82, v79, v18 op_sel:[0,0,0] op_sel_hi:[1,1,0]
	v_add_f32_dpp v20, v20, v20 row_mirror row_mask:0xf bank_mask:0xf bound_ctrl:1
	v_fma_mix_f32 v19, v82, v79, v19 op_sel:[0,1,0] op_sel_hi:[1,1,0]
	v_fma_mix_f32 v10, v20, v76, v16 op_sel:[0,0,0] op_sel_hi:[0,1,0]
	v_fma_mix_f32 v11, v20, v76, v17 op_sel:[0,1,0] op_sel_hi:[0,1,0]
	v_fma_mix_f32 v12, v20, v77, v18 op_sel:[0,0,0] op_sel_hi:[0,1,0]
	v_fma_mix_f32 v13, v20, v77, v19 op_sel:[0,1,0] op_sel_hi:[0,1,0]
	ds_read_b64 v[36:37], v6 offset:10264
	ds_read_b128 v[38:41], v6 offset:10512
	ds_read_b128 v[42:45], v6 offset:10768
	ds_read_u16 v46, v7 offset:10256
	v_fma_mix_f32 v14, v10, v86, 0 op_sel:[0,0,0] op_sel_hi:[0,1,0]
	v_fma_mix_f32 v50, v10, v80, 0 op_sel:[0,0,0] op_sel_hi:[0,1,0]
	v_fma_mix_f32 v14, v11, v86, v14 op_sel:[0,1,0] op_sel_hi:[0,1,0]
	v_fma_mix_f32 v50, v11, v80, v50 op_sel:[0,1,0] op_sel_hi:[0,1,0]
	v_fma_mix_f32 v14, v12, v87, v14 op_sel:[0,0,0] op_sel_hi:[0,1,0]
	v_fma_mix_f32 v50, v12, v81, v50 op_sel:[0,0,0] op_sel_hi:[0,1,0]
	v_fma_mix_f32 v14, v13, v87, v14 op_sel:[0,1,0] op_sel_hi:[0,1,0]
	v_fma_mix_f32 v16, v10, v84, 0 op_sel:[0,0,0] op_sel_hi:[0,1,0]
	v_fma_mix_f32 v17, v11, v84, 0 op_sel:[0,1,0] op_sel_hi:[0,1,0]
	v_add_f32_dpp v20, v14, v14 quad_perm:[1,0,3,2] row_mask:0xf bank_mask:0xf bound_ctrl:1
	v_fma_mix_f32 v50, v13, v81, v50 op_sel:[0,1,0] op_sel_hi:[0,1,0]
	v_fma_mix_f32 v18, v12, v85, 0 op_sel:[0,0,0] op_sel_hi:[0,1,0]
	v_add_f32_dpp v20, v20, v20 quad_perm:[2,3,0,1] row_mask:0xf bank_mask:0xf bound_ctrl:1
	v_fma_mix_f32 v19, v13, v85, 0 op_sel:[0,1,0] op_sel_hi:[0,1,0]
	v_fma_mix_f32 v16, v94, v90, v16 op_sel:[0,0,0] op_sel_hi:[1,1,0]
	v_add_f32_dpp v20, v20, v20 row_half_mirror row_mask:0xf bank_mask:0xf bound_ctrl:1
	v_fma_mix_f32 v17, v94, v90, v17 op_sel:[0,1,0] op_sel_hi:[1,1,0]
	v_fma_mix_f32 v18, v94, v91, v18 op_sel:[0,0,0] op_sel_hi:[1,1,0]
	v_add_f32_dpp v20, v20, v20 row_mirror row_mask:0xf bank_mask:0xf bound_ctrl:1
	v_fma_mix_f32 v19, v94, v91, v19 op_sel:[0,1,0] op_sel_hi:[1,1,0]
	v_fma_mix_f32 v10, v20, v88, v16 op_sel:[0,0,0] op_sel_hi:[0,1,0]
	v_fma_mix_f32 v11, v20, v88, v17 op_sel:[0,1,0] op_sel_hi:[0,1,0]
	v_fma_mix_f32 v12, v20, v89, v18 op_sel:[0,0,0] op_sel_hi:[0,1,0]
	v_fma_mix_f32 v13, v20, v89, v19 op_sel:[0,1,0] op_sel_hi:[0,1,0]
	s_waitcnt lgkmcnt(0)
	ds_read_b64 v[72:73], v6 offset:9240
	ds_read_b128 v[74:77], v6 offset:9488
	ds_read_b128 v[78:81], v6 offset:9744
	ds_read_u16 v82, v7 offset:9232
	v_fma_mix_f32 v14, v10, v26, 0 op_sel:[0,0,0] op_sel_hi:[0,1,0]
	v_fma_mix_f32 v51, v10, v92, 0 op_sel:[0,0,0] op_sel_hi:[0,1,0]
	v_fma_mix_f32 v14, v11, v26, v14 op_sel:[0,1,0] op_sel_hi:[0,1,0]
	v_fma_mix_f32 v51, v11, v92, v51 op_sel:[0,1,0] op_sel_hi:[0,1,0]
	v_fma_mix_f32 v14, v12, v27, v14 op_sel:[0,0,0] op_sel_hi:[0,1,0]
	v_fma_mix_f32 v51, v12, v93, v51 op_sel:[0,0,0] op_sel_hi:[0,1,0]
	v_fma_mix_f32 v14, v13, v27, v14 op_sel:[0,1,0] op_sel_hi:[0,1,0]
	v_fma_mix_f32 v16, v10, v24, 0 op_sel:[0,0,0] op_sel_hi:[0,1,0]
	v_fma_mix_f32 v17, v11, v24, 0 op_sel:[0,1,0] op_sel_hi:[0,1,0]
	v_add_f32_dpp v20, v14, v14 quad_perm:[1,0,3,2] row_mask:0xf bank_mask:0xf bound_ctrl:1
	v_fma_mix_f32 v51, v13, v93, v51 op_sel:[0,1,0] op_sel_hi:[0,1,0]
	v_fma_mix_f32 v18, v12, v25, 0 op_sel:[0,0,0] op_sel_hi:[0,1,0]
	v_add_f32_dpp v20, v20, v20 quad_perm:[2,3,0,1] row_mask:0xf bank_mask:0xf bound_ctrl:1
	v_fma_mix_f32 v19, v13, v25, 0 op_sel:[0,1,0] op_sel_hi:[0,1,0]
	v_fma_mix_f32 v16, v34, v30, v16 op_sel:[0,0,0] op_sel_hi:[1,1,0]
	v_add_f32_dpp v20, v20, v20 row_half_mirror row_mask:0xf bank_mask:0xf bound_ctrl:1
	v_fma_mix_f32 v17, v34, v30, v17 op_sel:[0,1,0] op_sel_hi:[1,1,0]
	v_fma_mix_f32 v18, v34, v31, v18 op_sel:[0,0,0] op_sel_hi:[1,1,0]
	v_add_f32_dpp v20, v20, v20 row_mirror row_mask:0xf bank_mask:0xf bound_ctrl:1
	v_fma_mix_f32 v19, v34, v31, v19 op_sel:[0,1,0] op_sel_hi:[1,1,0]
	v_fma_mix_f32 v10, v20, v28, v16 op_sel:[0,0,0] op_sel_hi:[0,1,0]
	v_fma_mix_f32 v11, v20, v28, v17 op_sel:[0,1,0] op_sel_hi:[0,1,0]
	v_fma_mix_f32 v12, v20, v29, v18 op_sel:[0,0,0] op_sel_hi:[0,1,0]
	v_fma_mix_f32 v13, v20, v29, v19 op_sel:[0,1,0] op_sel_hi:[0,1,0]
	ds_read_b64 v[84:85], v6 offset:8216
	ds_read_b128 v[86:89], v6 offset:8464
	ds_read_b128 v[90:93], v6 offset:8720
	ds_read_u16 v94, v7 offset:8208
	v_fma_mix_f32 v14, v10, v38, 0 op_sel:[0,0,0] op_sel_hi:[0,1,0]
	v_fma_mix_f32 v52, v10, v32, 0 op_sel:[0,0,0] op_sel_hi:[0,1,0]
	v_fma_mix_f32 v14, v11, v38, v14 op_sel:[0,1,0] op_sel_hi:[0,1,0]
	v_fma_mix_f32 v52, v11, v32, v52 op_sel:[0,1,0] op_sel_hi:[0,1,0]
	v_fma_mix_f32 v14, v12, v39, v14 op_sel:[0,0,0] op_sel_hi:[0,1,0]
	v_fma_mix_f32 v52, v12, v33, v52 op_sel:[0,0,0] op_sel_hi:[0,1,0]
	v_fma_mix_f32 v14, v13, v39, v14 op_sel:[0,1,0] op_sel_hi:[0,1,0]
	v_fma_mix_f32 v16, v10, v36, 0 op_sel:[0,0,0] op_sel_hi:[0,1,0]
	v_fma_mix_f32 v17, v11, v36, 0 op_sel:[0,1,0] op_sel_hi:[0,1,0]
	v_add_f32_dpp v20, v14, v14 quad_perm:[1,0,3,2] row_mask:0xf bank_mask:0xf bound_ctrl:1
	v_fma_mix_f32 v52, v13, v33, v52 op_sel:[0,1,0] op_sel_hi:[0,1,0]
	v_fma_mix_f32 v18, v12, v37, 0 op_sel:[0,0,0] op_sel_hi:[0,1,0]
	v_add_f32_dpp v20, v20, v20 quad_perm:[2,3,0,1] row_mask:0xf bank_mask:0xf bound_ctrl:1
	v_fma_mix_f32 v19, v13, v37, 0 op_sel:[0,1,0] op_sel_hi:[0,1,0]
	v_fma_mix_f32 v16, v46, v42, v16 op_sel:[0,0,0] op_sel_hi:[1,1,0]
	v_add_f32_dpp v20, v20, v20 row_half_mirror row_mask:0xf bank_mask:0xf bound_ctrl:1
	v_fma_mix_f32 v17, v46, v42, v17 op_sel:[0,1,0] op_sel_hi:[1,1,0]
	v_fma_mix_f32 v18, v46, v43, v18 op_sel:[0,0,0] op_sel_hi:[1,1,0]
	v_add_f32_dpp v20, v20, v20 row_mirror row_mask:0xf bank_mask:0xf bound_ctrl:1
	v_fma_mix_f32 v19, v46, v43, v19 op_sel:[0,1,0] op_sel_hi:[1,1,0]
	v_fma_mix_f32 v10, v20, v40, v16 op_sel:[0,0,0] op_sel_hi:[0,1,0]
	v_fma_mix_f32 v11, v20, v40, v17 op_sel:[0,1,0] op_sel_hi:[0,1,0]
	v_fma_mix_f32 v12, v20, v41, v18 op_sel:[0,0,0] op_sel_hi:[0,1,0]
	v_fma_mix_f32 v13, v20, v41, v19 op_sel:[0,1,0] op_sel_hi:[0,1,0]
	s_waitcnt lgkmcnt(0)
	ds_read_b64 v[24:25], v6 offset:7192
	ds_read_b128 v[26:29], v6 offset:7440
	ds_read_b128 v[30:33], v6 offset:7696
	ds_read_u16 v34, v7 offset:7184
	v_fma_mix_f32 v14, v10, v74, 0 op_sel:[0,0,0] op_sel_hi:[0,1,0]
	v_fma_mix_f32 v53, v10, v44, 0 op_sel:[0,0,0] op_sel_hi:[0,1,0]
	v_fma_mix_f32 v14, v11, v74, v14 op_sel:[0,1,0] op_sel_hi:[0,1,0]
	v_fma_mix_f32 v53, v11, v44, v53 op_sel:[0,1,0] op_sel_hi:[0,1,0]
	v_fma_mix_f32 v14, v12, v75, v14 op_sel:[0,0,0] op_sel_hi:[0,1,0]
	v_fma_mix_f32 v53, v12, v45, v53 op_sel:[0,0,0] op_sel_hi:[0,1,0]
	v_fma_mix_f32 v14, v13, v75, v14 op_sel:[0,1,0] op_sel_hi:[0,1,0]
	v_fma_mix_f32 v16, v10, v72, 0 op_sel:[0,0,0] op_sel_hi:[0,1,0]
	v_fma_mix_f32 v17, v11, v72, 0 op_sel:[0,1,0] op_sel_hi:[0,1,0]
	v_add_f32_dpp v20, v14, v14 quad_perm:[1,0,3,2] row_mask:0xf bank_mask:0xf bound_ctrl:1
	v_fma_mix_f32 v53, v13, v45, v53 op_sel:[0,1,0] op_sel_hi:[0,1,0]
	v_fma_mix_f32 v18, v12, v73, 0 op_sel:[0,0,0] op_sel_hi:[0,1,0]
	v_add_f32_dpp v20, v20, v20 quad_perm:[2,3,0,1] row_mask:0xf bank_mask:0xf bound_ctrl:1
	v_fma_mix_f32 v19, v13, v73, 0 op_sel:[0,1,0] op_sel_hi:[0,1,0]
	v_fma_mix_f32 v16, v82, v78, v16 op_sel:[0,0,0] op_sel_hi:[1,1,0]
	v_add_f32_dpp v20, v20, v20 row_half_mirror row_mask:0xf bank_mask:0xf bound_ctrl:1
	v_fma_mix_f32 v17, v82, v78, v17 op_sel:[0,1,0] op_sel_hi:[1,1,0]
	v_fma_mix_f32 v18, v82, v79, v18 op_sel:[0,0,0] op_sel_hi:[1,1,0]
	v_add_f32_dpp v20, v20, v20 row_mirror row_mask:0xf bank_mask:0xf bound_ctrl:1
	v_fma_mix_f32 v19, v82, v79, v19 op_sel:[0,1,0] op_sel_hi:[1,1,0]
	v_fma_mix_f32 v10, v20, v76, v16 op_sel:[0,0,0] op_sel_hi:[0,1,0]
	v_fma_mix_f32 v11, v20, v76, v17 op_sel:[0,1,0] op_sel_hi:[0,1,0]
	v_fma_mix_f32 v12, v20, v77, v18 op_sel:[0,0,0] op_sel_hi:[0,1,0]
	v_fma_mix_f32 v13, v20, v77, v19 op_sel:[0,1,0] op_sel_hi:[0,1,0]
	ds_read_b64 v[36:37], v6 offset:6168
	ds_read_b128 v[38:41], v6 offset:6416
	ds_read_b128 v[42:45], v6 offset:6672
	ds_read_u16 v46, v7 offset:6160
	v_fma_mix_f32 v14, v10, v86, 0 op_sel:[0,0,0] op_sel_hi:[0,1,0]
	v_fma_mix_f32 v54, v10, v80, 0 op_sel:[0,0,0] op_sel_hi:[0,1,0]
	v_fma_mix_f32 v14, v11, v86, v14 op_sel:[0,1,0] op_sel_hi:[0,1,0]
	v_fma_mix_f32 v54, v11, v80, v54 op_sel:[0,1,0] op_sel_hi:[0,1,0]
	v_fma_mix_f32 v14, v12, v87, v14 op_sel:[0,0,0] op_sel_hi:[0,1,0]
	v_fma_mix_f32 v54, v12, v81, v54 op_sel:[0,0,0] op_sel_hi:[0,1,0]
	v_fma_mix_f32 v14, v13, v87, v14 op_sel:[0,1,0] op_sel_hi:[0,1,0]
	v_fma_mix_f32 v16, v10, v84, 0 op_sel:[0,0,0] op_sel_hi:[0,1,0]
	v_fma_mix_f32 v17, v11, v84, 0 op_sel:[0,1,0] op_sel_hi:[0,1,0]
	v_add_f32_dpp v20, v14, v14 quad_perm:[1,0,3,2] row_mask:0xf bank_mask:0xf bound_ctrl:1
	v_fma_mix_f32 v54, v13, v81, v54 op_sel:[0,1,0] op_sel_hi:[0,1,0]
	v_fma_mix_f32 v18, v12, v85, 0 op_sel:[0,0,0] op_sel_hi:[0,1,0]
	v_add_f32_dpp v20, v20, v20 quad_perm:[2,3,0,1] row_mask:0xf bank_mask:0xf bound_ctrl:1
	v_fma_mix_f32 v19, v13, v85, 0 op_sel:[0,1,0] op_sel_hi:[0,1,0]
	v_fma_mix_f32 v16, v94, v90, v16 op_sel:[0,0,0] op_sel_hi:[1,1,0]
	v_add_f32_dpp v20, v20, v20 row_half_mirror row_mask:0xf bank_mask:0xf bound_ctrl:1
	v_fma_mix_f32 v17, v94, v90, v17 op_sel:[0,1,0] op_sel_hi:[1,1,0]
	v_fma_mix_f32 v18, v94, v91, v18 op_sel:[0,0,0] op_sel_hi:[1,1,0]
	v_add_f32_dpp v20, v20, v20 row_mirror row_mask:0xf bank_mask:0xf bound_ctrl:1
	v_fma_mix_f32 v19, v94, v91, v19 op_sel:[0,1,0] op_sel_hi:[1,1,0]
	v_fma_mix_f32 v10, v20, v88, v16 op_sel:[0,0,0] op_sel_hi:[0,1,0]
	v_fma_mix_f32 v11, v20, v88, v17 op_sel:[0,1,0] op_sel_hi:[0,1,0]
	v_fma_mix_f32 v12, v20, v89, v18 op_sel:[0,0,0] op_sel_hi:[0,1,0]
	v_fma_mix_f32 v13, v20, v89, v19 op_sel:[0,1,0] op_sel_hi:[0,1,0]
	s_waitcnt lgkmcnt(0)
	ds_read_b64 v[72:73], v6 offset:5144
	ds_read_b128 v[74:77], v6 offset:5392
	ds_read_b128 v[78:81], v6 offset:5648
	ds_read_u16 v82, v7 offset:5136
	v_fma_mix_f32 v14, v10, v26, 0 op_sel:[0,0,0] op_sel_hi:[0,1,0]
	v_fma_mix_f32 v55, v10, v92, 0 op_sel:[0,0,0] op_sel_hi:[0,1,0]
	v_fma_mix_f32 v14, v11, v26, v14 op_sel:[0,1,0] op_sel_hi:[0,1,0]
	v_fma_mix_f32 v55, v11, v92, v55 op_sel:[0,1,0] op_sel_hi:[0,1,0]
	v_fma_mix_f32 v14, v12, v27, v14 op_sel:[0,0,0] op_sel_hi:[0,1,0]
	v_fma_mix_f32 v55, v12, v93, v55 op_sel:[0,0,0] op_sel_hi:[0,1,0]
	v_fma_mix_f32 v14, v13, v27, v14 op_sel:[0,1,0] op_sel_hi:[0,1,0]
	v_fma_mix_f32 v16, v10, v24, 0 op_sel:[0,0,0] op_sel_hi:[0,1,0]
	v_fma_mix_f32 v17, v11, v24, 0 op_sel:[0,1,0] op_sel_hi:[0,1,0]
	v_add_f32_dpp v20, v14, v14 quad_perm:[1,0,3,2] row_mask:0xf bank_mask:0xf bound_ctrl:1
	v_fma_mix_f32 v55, v13, v93, v55 op_sel:[0,1,0] op_sel_hi:[0,1,0]
	v_fma_mix_f32 v18, v12, v25, 0 op_sel:[0,0,0] op_sel_hi:[0,1,0]
	v_add_f32_dpp v20, v20, v20 quad_perm:[2,3,0,1] row_mask:0xf bank_mask:0xf bound_ctrl:1
	v_fma_mix_f32 v19, v13, v25, 0 op_sel:[0,1,0] op_sel_hi:[0,1,0]
	v_fma_mix_f32 v16, v34, v30, v16 op_sel:[0,0,0] op_sel_hi:[1,1,0]
	v_add_f32_dpp v20, v20, v20 row_half_mirror row_mask:0xf bank_mask:0xf bound_ctrl:1
	v_fma_mix_f32 v17, v34, v30, v17 op_sel:[0,1,0] op_sel_hi:[1,1,0]
	v_fma_mix_f32 v18, v34, v31, v18 op_sel:[0,0,0] op_sel_hi:[1,1,0]
	v_add_f32_dpp v20, v20, v20 row_mirror row_mask:0xf bank_mask:0xf bound_ctrl:1
	v_fma_mix_f32 v19, v34, v31, v19 op_sel:[0,1,0] op_sel_hi:[1,1,0]
	v_fma_mix_f32 v10, v20, v28, v16 op_sel:[0,0,0] op_sel_hi:[0,1,0]
	v_fma_mix_f32 v11, v20, v28, v17 op_sel:[0,1,0] op_sel_hi:[0,1,0]
	v_fma_mix_f32 v12, v20, v29, v18 op_sel:[0,0,0] op_sel_hi:[0,1,0]
	v_fma_mix_f32 v13, v20, v29, v19 op_sel:[0,1,0] op_sel_hi:[0,1,0]
	ds_read_b64 v[84:85], v6 offset:4120
	ds_read_b128 v[86:89], v6 offset:4368
	ds_read_b128 v[90:93], v6 offset:4624
	ds_read_u16 v94, v7 offset:4112
	v_fma_mix_f32 v14, v10, v38, 0 op_sel:[0,0,0] op_sel_hi:[0,1,0]
	v_fma_mix_f32 v56, v10, v32, 0 op_sel:[0,0,0] op_sel_hi:[0,1,0]
	v_fma_mix_f32 v14, v11, v38, v14 op_sel:[0,1,0] op_sel_hi:[0,1,0]
	v_fma_mix_f32 v56, v11, v32, v56 op_sel:[0,1,0] op_sel_hi:[0,1,0]
	v_fma_mix_f32 v14, v12, v39, v14 op_sel:[0,0,0] op_sel_hi:[0,1,0]
	v_fma_mix_f32 v56, v12, v33, v56 op_sel:[0,0,0] op_sel_hi:[0,1,0]
	v_fma_mix_f32 v14, v13, v39, v14 op_sel:[0,1,0] op_sel_hi:[0,1,0]
	v_fma_mix_f32 v16, v10, v36, 0 op_sel:[0,0,0] op_sel_hi:[0,1,0]
	v_fma_mix_f32 v17, v11, v36, 0 op_sel:[0,1,0] op_sel_hi:[0,1,0]
	v_add_f32_dpp v20, v14, v14 quad_perm:[1,0,3,2] row_mask:0xf bank_mask:0xf bound_ctrl:1
	v_fma_mix_f32 v56, v13, v33, v56 op_sel:[0,1,0] op_sel_hi:[0,1,0]
	v_fma_mix_f32 v18, v12, v37, 0 op_sel:[0,0,0] op_sel_hi:[0,1,0]
	v_add_f32_dpp v20, v20, v20 quad_perm:[2,3,0,1] row_mask:0xf bank_mask:0xf bound_ctrl:1
	v_fma_mix_f32 v19, v13, v37, 0 op_sel:[0,1,0] op_sel_hi:[0,1,0]
	v_fma_mix_f32 v16, v46, v42, v16 op_sel:[0,0,0] op_sel_hi:[1,1,0]
	v_add_f32_dpp v20, v20, v20 row_half_mirror row_mask:0xf bank_mask:0xf bound_ctrl:1
	v_fma_mix_f32 v17, v46, v42, v17 op_sel:[0,1,0] op_sel_hi:[1,1,0]
	v_fma_mix_f32 v18, v46, v43, v18 op_sel:[0,0,0] op_sel_hi:[1,1,0]
	v_add_f32_dpp v20, v20, v20 row_mirror row_mask:0xf bank_mask:0xf bound_ctrl:1
	v_fma_mix_f32 v19, v46, v43, v19 op_sel:[0,1,0] op_sel_hi:[1,1,0]
	v_fma_mix_f32 v10, v20, v40, v16 op_sel:[0,0,0] op_sel_hi:[0,1,0]
	v_fma_mix_f32 v11, v20, v40, v17 op_sel:[0,1,0] op_sel_hi:[0,1,0]
	v_fma_mix_f32 v12, v20, v41, v18 op_sel:[0,0,0] op_sel_hi:[0,1,0]
	v_fma_mix_f32 v13, v20, v41, v19 op_sel:[0,1,0] op_sel_hi:[0,1,0]
	s_waitcnt lgkmcnt(0)
	ds_read_b64 v[24:25], v6 offset:3096
	ds_read_b128 v[26:29], v6 offset:3344
	ds_read_b128 v[30:33], v6 offset:3600
	ds_read_u16 v34, v7 offset:3088
	v_fma_mix_f32 v14, v10, v74, 0 op_sel:[0,0,0] op_sel_hi:[0,1,0]
	v_fma_mix_f32 v57, v10, v44, 0 op_sel:[0,0,0] op_sel_hi:[0,1,0]
	v_fma_mix_f32 v14, v11, v74, v14 op_sel:[0,1,0] op_sel_hi:[0,1,0]
	v_fma_mix_f32 v57, v11, v44, v57 op_sel:[0,1,0] op_sel_hi:[0,1,0]
	v_fma_mix_f32 v14, v12, v75, v14 op_sel:[0,0,0] op_sel_hi:[0,1,0]
	v_fma_mix_f32 v57, v12, v45, v57 op_sel:[0,0,0] op_sel_hi:[0,1,0]
	v_fma_mix_f32 v14, v13, v75, v14 op_sel:[0,1,0] op_sel_hi:[0,1,0]
	v_fma_mix_f32 v16, v10, v72, 0 op_sel:[0,0,0] op_sel_hi:[0,1,0]
	v_fma_mix_f32 v17, v11, v72, 0 op_sel:[0,1,0] op_sel_hi:[0,1,0]
	v_add_f32_dpp v20, v14, v14 quad_perm:[1,0,3,2] row_mask:0xf bank_mask:0xf bound_ctrl:1
	v_fma_mix_f32 v57, v13, v45, v57 op_sel:[0,1,0] op_sel_hi:[0,1,0]
	v_fma_mix_f32 v18, v12, v73, 0 op_sel:[0,0,0] op_sel_hi:[0,1,0]
	v_add_f32_dpp v20, v20, v20 quad_perm:[2,3,0,1] row_mask:0xf bank_mask:0xf bound_ctrl:1
	v_fma_mix_f32 v19, v13, v73, 0 op_sel:[0,1,0] op_sel_hi:[0,1,0]
	v_fma_mix_f32 v16, v82, v78, v16 op_sel:[0,0,0] op_sel_hi:[1,1,0]
	v_add_f32_dpp v20, v20, v20 row_half_mirror row_mask:0xf bank_mask:0xf bound_ctrl:1
	v_fma_mix_f32 v17, v82, v78, v17 op_sel:[0,1,0] op_sel_hi:[1,1,0]
	v_fma_mix_f32 v18, v82, v79, v18 op_sel:[0,0,0] op_sel_hi:[1,1,0]
	v_add_f32_dpp v20, v20, v20 row_mirror row_mask:0xf bank_mask:0xf bound_ctrl:1
	v_fma_mix_f32 v19, v82, v79, v19 op_sel:[0,1,0] op_sel_hi:[1,1,0]
	v_fma_mix_f32 v10, v20, v76, v16 op_sel:[0,0,0] op_sel_hi:[0,1,0]
	v_fma_mix_f32 v11, v20, v76, v17 op_sel:[0,1,0] op_sel_hi:[0,1,0]
	v_fma_mix_f32 v12, v20, v77, v18 op_sel:[0,0,0] op_sel_hi:[0,1,0]
	v_fma_mix_f32 v13, v20, v77, v19 op_sel:[0,1,0] op_sel_hi:[0,1,0]
	ds_read_b64 v[36:37], v6 offset:2072
	ds_read_b128 v[38:41], v6 offset:2320
	ds_read_b128 v[42:45], v6 offset:2576
	ds_read_u16 v46, v7 offset:2064
	v_fma_mix_f32 v14, v10, v86, 0 op_sel:[0,0,0] op_sel_hi:[0,1,0]
	v_fma_mix_f32 v58, v10, v80, 0 op_sel:[0,0,0] op_sel_hi:[0,1,0]
	v_fma_mix_f32 v14, v11, v86, v14 op_sel:[0,1,0] op_sel_hi:[0,1,0]
	v_fma_mix_f32 v58, v11, v80, v58 op_sel:[0,1,0] op_sel_hi:[0,1,0]
	v_fma_mix_f32 v14, v12, v87, v14 op_sel:[0,0,0] op_sel_hi:[0,1,0]
	v_fma_mix_f32 v58, v12, v81, v58 op_sel:[0,0,0] op_sel_hi:[0,1,0]
	v_fma_mix_f32 v14, v13, v87, v14 op_sel:[0,1,0] op_sel_hi:[0,1,0]
	v_fma_mix_f32 v16, v10, v84, 0 op_sel:[0,0,0] op_sel_hi:[0,1,0]
	v_fma_mix_f32 v17, v11, v84, 0 op_sel:[0,1,0] op_sel_hi:[0,1,0]
	v_add_f32_dpp v20, v14, v14 quad_perm:[1,0,3,2] row_mask:0xf bank_mask:0xf bound_ctrl:1
	v_fma_mix_f32 v58, v13, v81, v58 op_sel:[0,1,0] op_sel_hi:[0,1,0]
	v_fma_mix_f32 v18, v12, v85, 0 op_sel:[0,0,0] op_sel_hi:[0,1,0]
	v_add_f32_dpp v20, v20, v20 quad_perm:[2,3,0,1] row_mask:0xf bank_mask:0xf bound_ctrl:1
	v_fma_mix_f32 v19, v13, v85, 0 op_sel:[0,1,0] op_sel_hi:[0,1,0]
	v_fma_mix_f32 v16, v94, v90, v16 op_sel:[0,0,0] op_sel_hi:[1,1,0]
	v_add_f32_dpp v20, v20, v20 row_half_mirror row_mask:0xf bank_mask:0xf bound_ctrl:1
	v_fma_mix_f32 v17, v94, v90, v17 op_sel:[0,1,0] op_sel_hi:[1,1,0]
	v_fma_mix_f32 v18, v94, v91, v18 op_sel:[0,0,0] op_sel_hi:[1,1,0]
	v_add_f32_dpp v20, v20, v20 row_mirror row_mask:0xf bank_mask:0xf bound_ctrl:1
	v_fma_mix_f32 v19, v94, v91, v19 op_sel:[0,1,0] op_sel_hi:[1,1,0]
	v_fma_mix_f32 v10, v20, v88, v16 op_sel:[0,0,0] op_sel_hi:[0,1,0]
	v_fma_mix_f32 v11, v20, v88, v17 op_sel:[0,1,0] op_sel_hi:[0,1,0]
	v_fma_mix_f32 v12, v20, v89, v18 op_sel:[0,0,0] op_sel_hi:[0,1,0]
	v_fma_mix_f32 v13, v20, v89, v19 op_sel:[0,1,0] op_sel_hi:[0,1,0]
	s_waitcnt lgkmcnt(0)
	ds_read_b64 v[72:73], v6 offset:1048
	ds_read_b128 v[74:77], v6 offset:1296
	ds_read_b128 v[78:81], v6 offset:1552
	ds_read_u16 v82, v7 offset:1040
	v_fma_mix_f32 v14, v10, v26, 0 op_sel:[0,0,0] op_sel_hi:[0,1,0]
	v_fma_mix_f32 v59, v10, v92, 0 op_sel:[0,0,0] op_sel_hi:[0,1,0]
	v_fma_mix_f32 v14, v11, v26, v14 op_sel:[0,1,0] op_sel_hi:[0,1,0]
	v_fma_mix_f32 v59, v11, v92, v59 op_sel:[0,1,0] op_sel_hi:[0,1,0]
	v_fma_mix_f32 v14, v12, v27, v14 op_sel:[0,0,0] op_sel_hi:[0,1,0]
	v_fma_mix_f32 v59, v12, v93, v59 op_sel:[0,0,0] op_sel_hi:[0,1,0]
	v_fma_mix_f32 v14, v13, v27, v14 op_sel:[0,1,0] op_sel_hi:[0,1,0]
	v_fma_mix_f32 v16, v10, v24, 0 op_sel:[0,0,0] op_sel_hi:[0,1,0]
	v_fma_mix_f32 v17, v11, v24, 0 op_sel:[0,1,0] op_sel_hi:[0,1,0]
	v_add_f32_dpp v20, v14, v14 quad_perm:[1,0,3,2] row_mask:0xf bank_mask:0xf bound_ctrl:1
	v_fma_mix_f32 v59, v13, v93, v59 op_sel:[0,1,0] op_sel_hi:[0,1,0]
	v_fma_mix_f32 v18, v12, v25, 0 op_sel:[0,0,0] op_sel_hi:[0,1,0]
	v_add_f32_dpp v20, v20, v20 quad_perm:[2,3,0,1] row_mask:0xf bank_mask:0xf bound_ctrl:1
	v_fma_mix_f32 v19, v13, v25, 0 op_sel:[0,1,0] op_sel_hi:[0,1,0]
	v_fma_mix_f32 v16, v34, v30, v16 op_sel:[0,0,0] op_sel_hi:[1,1,0]
	v_add_f32_dpp v20, v20, v20 row_half_mirror row_mask:0xf bank_mask:0xf bound_ctrl:1
	v_fma_mix_f32 v17, v34, v30, v17 op_sel:[0,1,0] op_sel_hi:[1,1,0]
	v_fma_mix_f32 v18, v34, v31, v18 op_sel:[0,0,0] op_sel_hi:[1,1,0]
	v_add_f32_dpp v20, v20, v20 row_mirror row_mask:0xf bank_mask:0xf bound_ctrl:1
	v_fma_mix_f32 v19, v34, v31, v19 op_sel:[0,1,0] op_sel_hi:[1,1,0]
	v_fma_mix_f32 v10, v20, v28, v16 op_sel:[0,0,0] op_sel_hi:[0,1,0]
	v_fma_mix_f32 v11, v20, v28, v17 op_sel:[0,1,0] op_sel_hi:[0,1,0]
	v_fma_mix_f32 v12, v20, v29, v18 op_sel:[0,0,0] op_sel_hi:[0,1,0]
	v_fma_mix_f32 v13, v20, v29, v19 op_sel:[0,1,0] op_sel_hi:[0,1,0]
	ds_read_b128 v[100:103], v9
	ds_read_b64 v[84:85], v6 offset:24
	ds_read_b128 v[86:89], v6 offset:272
	ds_read_b128 v[90:93], v6 offset:528
	ds_read_u16 v94, v7 offset:16
	v_fma_mix_f32 v14, v10, v38, 0 op_sel:[0,0,0] op_sel_hi:[0,1,0]
	v_fma_mix_f32 v60, v10, v32, 0 op_sel:[0,0,0] op_sel_hi:[0,1,0]
	v_fma_mix_f32 v14, v11, v38, v14 op_sel:[0,1,0] op_sel_hi:[0,1,0]
	v_fma_mix_f32 v60, v11, v32, v60 op_sel:[0,1,0] op_sel_hi:[0,1,0]
	v_fma_mix_f32 v14, v12, v39, v14 op_sel:[0,0,0] op_sel_hi:[0,1,0]
	v_fma_mix_f32 v60, v12, v33, v60 op_sel:[0,0,0] op_sel_hi:[0,1,0]
	v_fma_mix_f32 v14, v13, v39, v14 op_sel:[0,1,0] op_sel_hi:[0,1,0]
	v_fma_mix_f32 v16, v10, v36, 0 op_sel:[0,0,0] op_sel_hi:[0,1,0]
	v_fma_mix_f32 v17, v11, v36, 0 op_sel:[0,1,0] op_sel_hi:[0,1,0]
	v_add_f32_dpp v20, v14, v14 quad_perm:[1,0,3,2] row_mask:0xf bank_mask:0xf bound_ctrl:1
	v_fma_mix_f32 v60, v13, v33, v60 op_sel:[0,1,0] op_sel_hi:[0,1,0]
	v_fma_mix_f32 v18, v12, v37, 0 op_sel:[0,0,0] op_sel_hi:[0,1,0]
	v_add_f32_dpp v20, v20, v20 quad_perm:[2,3,0,1] row_mask:0xf bank_mask:0xf bound_ctrl:1
	v_fma_mix_f32 v19, v13, v37, 0 op_sel:[0,1,0] op_sel_hi:[0,1,0]
	v_fma_mix_f32 v16, v46, v42, v16 op_sel:[0,0,0] op_sel_hi:[1,1,0]
	v_add_f32_dpp v20, v20, v20 row_half_mirror row_mask:0xf bank_mask:0xf bound_ctrl:1
	v_fma_mix_f32 v17, v46, v42, v17 op_sel:[0,1,0] op_sel_hi:[1,1,0]
	v_fma_mix_f32 v18, v46, v43, v18 op_sel:[0,0,0] op_sel_hi:[1,1,0]
	v_add_f32_dpp v20, v20, v20 row_mirror row_mask:0xf bank_mask:0xf bound_ctrl:1
	v_fma_mix_f32 v19, v46, v43, v19 op_sel:[0,1,0] op_sel_hi:[1,1,0]
	v_fma_mix_f32 v10, v20, v40, v16 op_sel:[0,0,0] op_sel_hi:[0,1,0]
	v_fma_mix_f32 v11, v20, v40, v17 op_sel:[0,1,0] op_sel_hi:[0,1,0]
	v_fma_mix_f32 v12, v20, v41, v18 op_sel:[0,0,0] op_sel_hi:[0,1,0]
	v_fma_mix_f32 v13, v20, v41, v19 op_sel:[0,1,0] op_sel_hi:[0,1,0]
	s_waitcnt lgkmcnt(0)
	v_add_u32_e32 v6, 0xffffc000, v6
	v_add_u32_e32 v7, 0xffffc000, v7
	v_and_b32_e32 v6, 0x1ffff, v6
	v_and_b32_e32 v7, 0x1ffff, v7
	ds_read_b64 v[24:25], v6 offset:15384
	ds_read_b128 v[26:29], v6 offset:15632
	ds_read_b128 v[30:33], v6 offset:15888
	ds_read_u16 v34, v7 offset:15376
	v_fma_mix_f32 v14, v10, v74, 0 op_sel:[0,0,0] op_sel_hi:[0,1,0]
	v_fma_mix_f32 v61, v10, v44, 0 op_sel:[0,0,0] op_sel_hi:[0,1,0]
	v_fma_mix_f32 v14, v11, v74, v14 op_sel:[0,1,0] op_sel_hi:[0,1,0]
	v_fma_mix_f32 v61, v11, v44, v61 op_sel:[0,1,0] op_sel_hi:[0,1,0]
	v_fma_mix_f32 v14, v12, v75, v14 op_sel:[0,0,0] op_sel_hi:[0,1,0]
	v_fma_mix_f32 v61, v12, v45, v61 op_sel:[0,0,0] op_sel_hi:[0,1,0]
	v_fma_mix_f32 v14, v13, v75, v14 op_sel:[0,1,0] op_sel_hi:[0,1,0]
	v_fma_mix_f32 v16, v10, v72, 0 op_sel:[0,0,0] op_sel_hi:[0,1,0]
	v_fma_mix_f32 v17, v11, v72, 0 op_sel:[0,1,0] op_sel_hi:[0,1,0]
	v_add_f32_dpp v20, v14, v14 quad_perm:[1,0,3,2] row_mask:0xf bank_mask:0xf bound_ctrl:1
	v_fma_mix_f32 v61, v13, v45, v61 op_sel:[0,1,0] op_sel_hi:[0,1,0]
	v_fma_mix_f32 v18, v12, v73, 0 op_sel:[0,0,0] op_sel_hi:[0,1,0]
	v_add_f32_dpp v20, v20, v20 quad_perm:[2,3,0,1] row_mask:0xf bank_mask:0xf bound_ctrl:1
	v_fma_mix_f32 v19, v13, v73, 0 op_sel:[0,1,0] op_sel_hi:[0,1,0]
	v_fma_mix_f32 v16, v82, v78, v16 op_sel:[0,0,0] op_sel_hi:[1,1,0]
	v_add_f32_dpp v20, v20, v20 row_half_mirror row_mask:0xf bank_mask:0xf bound_ctrl:1
	v_fma_mix_f32 v17, v82, v78, v17 op_sel:[0,1,0] op_sel_hi:[1,1,0]
	v_fma_mix_f32 v18, v82, v79, v18 op_sel:[0,0,0] op_sel_hi:[1,1,0]
	v_add_f32_dpp v20, v20, v20 row_mirror row_mask:0xf bank_mask:0xf bound_ctrl:1
	v_fma_mix_f32 v19, v82, v79, v19 op_sel:[0,1,0] op_sel_hi:[1,1,0]
	v_fma_mix_f32 v10, v20, v76, v16 op_sel:[0,0,0] op_sel_hi:[0,1,0]
	v_fma_mix_f32 v11, v20, v76, v17 op_sel:[0,1,0] op_sel_hi:[0,1,0]
	v_fma_mix_f32 v12, v20, v77, v18 op_sel:[0,0,0] op_sel_hi:[0,1,0]
	v_fma_mix_f32 v13, v20, v77, v19 op_sel:[0,1,0] op_sel_hi:[0,1,0]
	ds_read_b64 v[36:37], v6 offset:14360
	ds_read_b128 v[38:41], v6 offset:14608
	ds_read_b128 v[42:45], v6 offset:14864
	ds_read_u16 v46, v7 offset:14352
	v_fma_mix_f32 v14, v10, v86, 0 op_sel:[0,0,0] op_sel_hi:[0,1,0]
	v_fma_mix_f32 v62, v10, v80, 0 op_sel:[0,0,0] op_sel_hi:[0,1,0]
	v_fma_mix_f32 v14, v11, v86, v14 op_sel:[0,1,0] op_sel_hi:[0,1,0]
	v_fma_mix_f32 v62, v11, v80, v62 op_sel:[0,1,0] op_sel_hi:[0,1,0]
	v_fma_mix_f32 v14, v12, v87, v14 op_sel:[0,0,0] op_sel_hi:[0,1,0]
	v_fma_mix_f32 v62, v12, v81, v62 op_sel:[0,0,0] op_sel_hi:[0,1,0]
	v_fma_mix_f32 v14, v13, v87, v14 op_sel:[0,1,0] op_sel_hi:[0,1,0]
	v_fma_mix_f32 v16, v10, v84, 0 op_sel:[0,0,0] op_sel_hi:[0,1,0]
	v_fma_mix_f32 v17, v11, v84, 0 op_sel:[0,1,0] op_sel_hi:[0,1,0]
	v_add_f32_dpp v20, v14, v14 quad_perm:[1,0,3,2] row_mask:0xf bank_mask:0xf bound_ctrl:1
	v_fma_mix_f32 v62, v13, v81, v62 op_sel:[0,1,0] op_sel_hi:[0,1,0]
	v_fma_mix_f32 v18, v12, v85, 0 op_sel:[0,0,0] op_sel_hi:[0,1,0]
	v_add_f32_dpp v20, v20, v20 quad_perm:[2,3,0,1] row_mask:0xf bank_mask:0xf bound_ctrl:1
	v_fma_mix_f32 v19, v13, v85, 0 op_sel:[0,1,0] op_sel_hi:[0,1,0]
	v_fma_mix_f32 v16, v94, v90, v16 op_sel:[0,0,0] op_sel_hi:[1,1,0]
	v_add_f32_dpp v20, v20, v20 row_half_mirror row_mask:0xf bank_mask:0xf bound_ctrl:1
	v_fma_mix_f32 v17, v94, v90, v17 op_sel:[0,1,0] op_sel_hi:[1,1,0]
	v_fma_mix_f32 v18, v94, v91, v18 op_sel:[0,0,0] op_sel_hi:[1,1,0]
	v_add_f32_dpp v20, v20, v20 row_mirror row_mask:0xf bank_mask:0xf bound_ctrl:1
	v_fma_mix_f32 v19, v94, v91, v19 op_sel:[0,1,0] op_sel_hi:[1,1,0]
	v_fma_mix_f32 v10, v20, v88, v16 op_sel:[0,0,0] op_sel_hi:[0,1,0]
	v_fma_mix_f32 v11, v20, v88, v17 op_sel:[0,1,0] op_sel_hi:[0,1,0]
	v_fma_mix_f32 v12, v20, v89, v18 op_sel:[0,0,0] op_sel_hi:[0,1,0]
	v_fma_mix_f32 v13, v20, v89, v19 op_sel:[0,1,0] op_sel_hi:[0,1,0]
	s_waitcnt lgkmcnt(0)
	s_add_u32 s43, s43, 1

.Lrw_ready_d1:
	s_add_u32 m0, s41, 16
	s_nop 0
	global_load_lds_dwordx4 v5, s[10:11] offset:0
	global_load_lds_dwordx4 v5, s[10:11] offset:1024
	global_load_lds_dwordx4 v5, s[10:11] offset:2048
	global_load_lds_dwordx4 v5, s[10:11] offset:3072
	s_sub_u32 s10, s10, 0x4000
	s_subb_u32 s11, s11, 0
	s_sub_u32 s41, s41, 0x4000
	s_and_b32 s41, s41, 0x1ffff
	ds_read_b64 v[72:73], v6 offset:13336
	ds_read_b128 v[74:77], v6 offset:13584
	ds_read_b128 v[78:81], v6 offset:13840
	ds_read_u16 v82, v7 offset:13328
	v_fma_mix_f32 v14, v10, v26, 0 op_sel:[0,0,0] op_sel_hi:[0,1,0]
	v_fma_mix_f32 v63, v10, v92, 0 op_sel:[0,0,0] op_sel_hi:[0,1,0]
	v_fma_mix_f32 v14, v11, v26, v14 op_sel:[0,1,0] op_sel_hi:[0,1,0]
	v_fma_mix_f32 v63, v11, v92, v63 op_sel:[0,1,0] op_sel_hi:[0,1,0]
	v_fma_mix_f32 v14, v12, v27, v14 op_sel:[0,0,0] op_sel_hi:[0,1,0]
	v_fma_mix_f32 v63, v12, v93, v63 op_sel:[0,0,0] op_sel_hi:[0,1,0]
	v_fma_mix_f32 v14, v13, v27, v14 op_sel:[0,1,0] op_sel_hi:[0,1,0]
	v_fma_mix_f32 v16, v10, v24, 0 op_sel:[0,0,0] op_sel_hi:[0,1,0]
	v_fma_mix_f32 v17, v11, v24, 0 op_sel:[0,1,0] op_sel_hi:[0,1,0]
	v_add_f32_dpp v20, v14, v14 quad_perm:[1,0,3,2] row_mask:0xf bank_mask:0xf bound_ctrl:1
	v_fma_mix_f32 v63, v13, v93, v63 op_sel:[0,1,0] op_sel_hi:[0,1,0]
	v_fma_mix_f32 v18, v12, v25, 0 op_sel:[0,0,0] op_sel_hi:[0,1,0]
	v_add_f32_dpp v20, v20, v20 quad_perm:[2,3,0,1] row_mask:0xf bank_mask:0xf bound_ctrl:1
	v_fma_mix_f32 v19, v13, v25, 0 op_sel:[0,1,0] op_sel_hi:[0,1,0]
	v_fma_mix_f32 v16, v34, v30, v16 op_sel:[0,0,0] op_sel_hi:[1,1,0]
	v_add_f32_dpp v20, v20, v20 row_half_mirror row_mask:0xf bank_mask:0xf bound_ctrl:1
	v_fma_mix_f32 v17, v34, v30, v17 op_sel:[0,1,0] op_sel_hi:[1,1,0]
	v_fma_mix_f32 v18, v34, v31, v18 op_sel:[0,0,0] op_sel_hi:[1,1,0]
	v_add_f32_dpp v20, v20, v20 row_mirror row_mask:0xf bank_mask:0xf bound_ctrl:1
	v_fma_mix_f32 v19, v34, v31, v19 op_sel:[0,1,0] op_sel_hi:[1,1,0]
	v_fma_mix_f32 v10, v20, v28, v16 op_sel:[0,0,0] op_sel_hi:[0,1,0]
	v_fma_mix_f32 v11, v20, v28, v17 op_sel:[0,1,0] op_sel_hi:[0,1,0]
	v_fma_mix_f32 v12, v20, v29, v18 op_sel:[0,0,0] op_sel_hi:[0,1,0]
	v_fma_mix_f32 v13, v20, v29, v19 op_sel:[0,1,0] op_sel_hi:[0,1,0]
	v_add_f32_dpp v48, v48, v48 row_ror:8 row_mask:0xf bank_mask:0x3
	v_add_f32_dpp v49, v49, v49 row_ror:8 row_mask:0xf bank_mask:0x3
	v_add_f32_dpp v50, v50, v50 row_ror:8 row_mask:0xf bank_mask:0x3
	v_add_f32_dpp v51, v51, v51 row_ror:8 row_mask:0xf bank_mask:0x3
	v_add_f32_dpp v52, v52, v52 row_ror:8 row_mask:0xf bank_mask:0x3
	v_add_f32_dpp v53, v53, v53 row_ror:8 row_mask:0xf bank_mask:0x3
	v_add_f32_dpp v54, v54, v54 row_ror:8 row_mask:0xf bank_mask:0x3
	v_add_f32_dpp v55, v55, v55 row_ror:8 row_mask:0xf bank_mask:0x3
	v_add_f32_dpp v48, v56, v56 row_ror:8 row_mask:0xf bank_mask:0xc
	v_add_f32_dpp v49, v57, v57 row_ror:8 row_mask:0xf bank_mask:0xc
	v_add_f32_dpp v50, v58, v58 row_ror:8 row_mask:0xf bank_mask:0xc
	v_add_f32_dpp v51, v59, v59 row_ror:8 row_mask:0xf bank_mask:0xc
	v_add_f32_dpp v52, v60, v60 row_ror:8 row_mask:0xf bank_mask:0xc
	v_add_f32_dpp v53, v61, v61 row_ror:8 row_mask:0xf bank_mask:0xc
	v_add_f32_dpp v54, v62, v62 row_ror:8 row_mask:0xf bank_mask:0xc
	v_add_f32_dpp v55, v63, v63 row_ror:8 row_mask:0xf bank_mask:0xc
	v_add_f32_dpp v48, v48, v48 row_ror:12 row_mask:0xf bank_mask:0x5
	v_add_f32_dpp v49, v49, v49 row_ror:12 row_mask:0xf bank_mask:0x5
	v_add_f32_dpp v50, v50, v50 row_ror:12 row_mask:0xf bank_mask:0x5
	v_add_f32_dpp v51, v51, v51 row_ror:12 row_mask:0xf bank_mask:0x5
	v_add_f32_dpp v48, v52, v52 row_ror:4 row_mask:0xf bank_mask:0xa
	v_add_f32_dpp v49, v53, v53 row_ror:4 row_mask:0xf bank_mask:0xa
	v_add_f32_dpp v50, v54, v54 row_ror:4 row_mask:0xf bank_mask:0xa
	v_add_f32_dpp v51, v55, v55 row_ror:4 row_mask:0xf bank_mask:0xa
	v_add_f32_dpp v64, v48, v48 quad_perm:[2,3,0,1] row_mask:0xf bank_mask:0xf bound_ctrl:1
	v_add_f32_dpp v65, v50, v50 quad_perm:[2,3,0,1] row_mask:0xf bank_mask:0xf bound_ctrl:1
	v_cndmask_b32_e64 v56, v64, v65, s[50:51]
	v_add_f32_dpp v64, v49, v49 quad_perm:[2,3,0,1] row_mask:0xf bank_mask:0xf bound_ctrl:1
	v_add_f32_dpp v65, v51, v51 quad_perm:[2,3,0,1] row_mask:0xf bank_mask:0xf bound_ctrl:1
	v_cndmask_b32_e64 v57, v64, v65, s[50:51]
	v_add_f32_dpp v64, v56, v56 quad_perm:[1,0,3,2] row_mask:0xf bank_mask:0xf bound_ctrl:1
	s_nop 0
	v_add_f32_dpp v65, v57, v57 quad_perm:[1,0,3,2] row_mask:0xf bank_mask:0xf bound_ctrl:1
	v_cndmask_b32_e64 v66, v64, v65, s[48:49]
	v_cvt_pk_bf16_f32 v66, v66, v66
	global_store_short v8, v66, s[12:13]
	s_sub_u32 s12, s12, 0x8000
	s_subb_u32 s13, s13, 0
	ds_read_b64 v[84:85], v6 offset:12312
	ds_read_b128 v[86:89], v6 offset:12560
	ds_read_b128 v[90:93], v6 offset:12816
	ds_read_u16 v94, v7 offset:12304
	v_fma_mix_f32 v14, v10, v38, 0 op_sel:[0,0,0] op_sel_hi:[0,1,0]
	v_fma_mix_f32 v48, v10, v32, 0 op_sel:[0,0,0] op_sel_hi:[0,1,0]
	v_fma_mix_f32 v14, v11, v38, v14 op_sel:[0,1,0] op_sel_hi:[0,1,0]
	v_fma_mix_f32 v48, v11, v32, v48 op_sel:[0,1,0] op_sel_hi:[0,1,0]
	v_fma_mix_f32 v14, v12, v39, v14 op_sel:[0,0,0] op_sel_hi:[0,1,0]
	v_fma_mix_f32 v48, v12, v33, v48 op_sel:[0,0,0] op_sel_hi:[0,1,0]
	v_fma_mix_f32 v14, v13, v39, v14 op_sel:[0,1,0] op_sel_hi:[0,1,0]
	v_fma_mix_f32 v16, v10, v36, 0 op_sel:[0,0,0] op_sel_hi:[0,1,0]
	v_fma_mix_f32 v17, v11, v36, 0 op_sel:[0,1,0] op_sel_hi:[0,1,0]
	v_add_f32_dpp v20, v14, v14 quad_perm:[1,0,3,2] row_mask:0xf bank_mask:0xf bound_ctrl:1
	v_fma_mix_f32 v48, v13, v33, v48 op_sel:[0,1,0] op_sel_hi:[0,1,0]
	v_fma_mix_f32 v18, v12, v37, 0 op_sel:[0,0,0] op_sel_hi:[0,1,0]
	v_add_f32_dpp v20, v20, v20 quad_perm:[2,3,0,1] row_mask:0xf bank_mask:0xf bound_ctrl:1
	v_fma_mix_f32 v19, v13, v37, 0 op_sel:[0,1,0] op_sel_hi:[0,1,0]
	v_fma_mix_f32 v16, v46, v42, v16 op_sel:[0,0,0] op_sel_hi:[1,1,0]
	v_add_f32_dpp v20, v20, v20 row_half_mirror row_mask:0xf bank_mask:0xf bound_ctrl:1
	v_fma_mix_f32 v17, v46, v42, v17 op_sel:[0,1,0] op_sel_hi:[1,1,0]
	v_fma_mix_f32 v18, v46, v43, v18 op_sel:[0,0,0] op_sel_hi:[1,1,0]
	v_add_f32_dpp v20, v20, v20 row_mirror row_mask:0xf bank_mask:0xf bound_ctrl:1
	v_fma_mix_f32 v19, v46, v43, v19 op_sel:[0,1,0] op_sel_hi:[1,1,0]
	v_fma_mix_f32 v10, v20, v40, v16 op_sel:[0,0,0] op_sel_hi:[0,1,0]
	v_fma_mix_f32 v11, v20, v40, v17 op_sel:[0,1,0] op_sel_hi:[0,1,0]
	v_fma_mix_f32 v12, v20, v41, v18 op_sel:[0,0,0] op_sel_hi:[0,1,0]
	v_fma_mix_f32 v13, v20, v41, v19 op_sel:[0,1,0] op_sel_hi:[0,1,0]
	s_waitcnt lgkmcnt(0)
	ds_read_b64 v[24:25], v6 offset:11288
	ds_read_b128 v[26:29], v6 offset:11536
	ds_read_b128 v[30:33], v6 offset:11792
	ds_read_u16 v34, v7 offset:11280
	v_fma_mix_f32 v14, v10, v74, 0 op_sel:[0,0,0] op_sel_hi:[0,1,0]
	v_fma_mix_f32 v49, v10, v44, 0 op_sel:[0,0,0] op_sel_hi:[0,1,0]
	v_fma_mix_f32 v14, v11, v74, v14 op_sel:[0,1,0] op_sel_hi:[0,1,0]
	v_fma_mix_f32 v49, v11, v44, v49 op_sel:[0,1,0] op_sel_hi:[0,1,0]
	v_fma_mix_f32 v14, v12, v75, v14 op_sel:[0,0,0] op_sel_hi:[0,1,0]
	v_fma_mix_f32 v49, v12, v45, v49 op_sel:[0,0,0] op_sel_hi:[0,1,0]
	v_fma_mix_f32 v14, v13, v75, v14 op_sel:[0,1,0] op_sel_hi:[0,1,0]
	v_fma_mix_f32 v16, v10, v72, 0 op_sel:[0,0,0] op_sel_hi:[0,1,0]
	v_fma_mix_f32 v17, v11, v72, 0 op_sel:[0,1,0] op_sel_hi:[0,1,0]
	v_add_f32_dpp v20, v14, v14 quad_perm:[1,0,3,2] row_mask:0xf bank_mask:0xf bound_ctrl:1
	v_fma_mix_f32 v49, v13, v45, v49 op_sel:[0,1,0] op_sel_hi:[0,1,0]
	v_fma_mix_f32 v18, v12, v73, 0 op_sel:[0,0,0] op_sel_hi:[0,1,0]
	v_add_f32_dpp v20, v20, v20 quad_perm:[2,3,0,1] row_mask:0xf bank_mask:0xf bound_ctrl:1
	v_fma_mix_f32 v19, v13, v73, 0 op_sel:[0,1,0] op_sel_hi:[0,1,0]
	v_fma_mix_f32 v16, v82, v78, v16 op_sel:[0,0,0] op_sel_hi:[1,1,0]
	v_add_f32_dpp v20, v20, v20 row_half_mirror row_mask:0xf bank_mask:0xf bound_ctrl:1
	v_fma_mix_f32 v17, v82, v78, v17 op_sel:[0,1,0] op_sel_hi:[1,1,0]
	v_fma_mix_f32 v18, v82, v79, v18 op_sel:[0,0,0] op_sel_hi:[1,1,0]
	v_add_f32_dpp v20, v20, v20 row_mirror row_mask:0xf bank_mask:0xf bound_ctrl:1
	v_fma_mix_f32 v19, v82, v79, v19 op_sel:[0,1,0] op_sel_hi:[1,1,0]
	v_fma_mix_f32 v10, v20, v76, v16 op_sel:[0,0,0] op_sel_hi:[0,1,0]
	v_fma_mix_f32 v11, v20, v76, v17 op_sel:[0,1,0] op_sel_hi:[0,1,0]
	v_fma_mix_f32 v12, v20, v77, v18 op_sel:[0,0,0] op_sel_hi:[0,1,0]
	v_fma_mix_f32 v13, v20, v77, v19 op_sel:[0,1,0] op_sel_hi:[0,1,0]
	ds_read_b64 v[36:37], v6 offset:10264
	ds_read_b128 v[38:41], v6 offset:10512
	ds_read_b128 v[42:45], v6 offset:10768
	ds_read_u16 v46, v7 offset:10256
	v_fma_mix_f32 v14, v10, v86, 0 op_sel:[0,0,0] op_sel_hi:[0,1,0]
	v_fma_mix_f32 v50, v10, v80, 0 op_sel:[0,0,0] op_sel_hi:[0,1,0]
	v_fma_mix_f32 v14, v11, v86, v14 op_sel:[0,1,0] op_sel_hi:[0,1,0]
	v_fma_mix_f32 v50, v11, v80, v50 op_sel:[0,1,0] op_sel_hi:[0,1,0]
	v_fma_mix_f32 v14, v12, v87, v14 op_sel:[0,0,0] op_sel_hi:[0,1,0]
	v_fma_mix_f32 v50, v12, v81, v50 op_sel:[0,0,0] op_sel_hi:[0,1,0]
	v_fma_mix_f32 v14, v13, v87, v14 op_sel:[0,1,0] op_sel_hi:[0,1,0]
	v_fma_mix_f32 v16, v10, v84, 0 op_sel:[0,0,0] op_sel_hi:[0,1,0]
	v_fma_mix_f32 v17, v11, v84, 0 op_sel:[0,1,0] op_sel_hi:[0,1,0]
	v_add_f32_dpp v20, v14, v14 quad_perm:[1,0,3,2] row_mask:0xf bank_mask:0xf bound_ctrl:1
	v_fma_mix_f32 v50, v13, v81, v50 op_sel:[0,1,0] op_sel_hi:[0,1,0]
	v_fma_mix_f32 v18, v12, v85, 0 op_sel:[0,0,0] op_sel_hi:[0,1,0]
	v_add_f32_dpp v20, v20, v20 quad_perm:[2,3,0,1] row_mask:0xf bank_mask:0xf bound_ctrl:1
	v_fma_mix_f32 v19, v13, v85, 0 op_sel:[0,1,0] op_sel_hi:[0,1,0]
	v_fma_mix_f32 v16, v94, v90, v16 op_sel:[0,0,0] op_sel_hi:[1,1,0]
	v_add_f32_dpp v20, v20, v20 row_half_mirror row_mask:0xf bank_mask:0xf bound_ctrl:1
	v_fma_mix_f32 v17, v94, v90, v17 op_sel:[0,1,0] op_sel_hi:[1,1,0]
	v_fma_mix_f32 v18, v94, v91, v18 op_sel:[0,0,0] op_sel_hi:[1,1,0]
	v_add_f32_dpp v20, v20, v20 row_mirror row_mask:0xf bank_mask:0xf bound_ctrl:1
	v_fma_mix_f32 v19, v94, v91, v19 op_sel:[0,1,0] op_sel_hi:[1,1,0]
	v_fma_mix_f32 v10, v20, v88, v16 op_sel:[0,0,0] op_sel_hi:[0,1,0]
	v_fma_mix_f32 v11, v20, v88, v17 op_sel:[0,1,0] op_sel_hi:[0,1,0]
	v_fma_mix_f32 v12, v20, v89, v18 op_sel:[0,0,0] op_sel_hi:[0,1,0]
	v_fma_mix_f32 v13, v20, v89, v19 op_sel:[0,1,0] op_sel_hi:[0,1,0]
	s_waitcnt lgkmcnt(0)
	ds_read_b64 v[72:73], v6 offset:9240
	ds_read_b128 v[74:77], v6 offset:9488
	ds_read_b128 v[78:81], v6 offset:9744
	ds_read_u16 v82, v7 offset:9232
	v_fma_mix_f32 v14, v10, v26, 0 op_sel:[0,0,0] op_sel_hi:[0,1,0]
	v_fma_mix_f32 v51, v10, v92, 0 op_sel:[0,0,0] op_sel_hi:[0,1,0]
	v_fma_mix_f32 v14, v11, v26, v14 op_sel:[0,1,0] op_sel_hi:[0,1,0]
	v_fma_mix_f32 v51, v11, v92, v51 op_sel:[0,1,0] op_sel_hi:[0,1,0]
	v_fma_mix_f32 v14, v12, v27, v14 op_sel:[0,0,0] op_sel_hi:[0,1,0]
	v_fma_mix_f32 v51, v12, v93, v51 op_sel:[0,0,0] op_sel_hi:[0,1,0]
	v_fma_mix_f32 v14, v13, v27, v14 op_sel:[0,1,0] op_sel_hi:[0,1,0]
	v_fma_mix_f32 v16, v10, v24, 0 op_sel:[0,0,0] op_sel_hi:[0,1,0]
	v_fma_mix_f32 v17, v11, v24, 0 op_sel:[0,1,0] op_sel_hi:[0,1,0]
	v_add_f32_dpp v20, v14, v14 quad_perm:[1,0,3,2] row_mask:0xf bank_mask:0xf bound_ctrl:1
	v_fma_mix_f32 v51, v13, v93, v51 op_sel:[0,1,0] op_sel_hi:[0,1,0]
	v_fma_mix_f32 v18, v12, v25, 0 op_sel:[0,0,0] op_sel_hi:[0,1,0]
	v_add_f32_dpp v20, v20, v20 quad_perm:[2,3,0,1] row_mask:0xf bank_mask:0xf bound_ctrl:1
	v_fma_mix_f32 v19, v13, v25, 0 op_sel:[0,1,0] op_sel_hi:[0,1,0]
	v_fma_mix_f32 v16, v34, v30, v16 op_sel:[0,0,0] op_sel_hi:[1,1,0]
	v_add_f32_dpp v20, v20, v20 row_half_mirror row_mask:0xf bank_mask:0xf bound_ctrl:1
	v_fma_mix_f32 v17, v34, v30, v17 op_sel:[0,1,0] op_sel_hi:[1,1,0]
	v_fma_mix_f32 v18, v34, v31, v18 op_sel:[0,0,0] op_sel_hi:[1,1,0]
	v_add_f32_dpp v20, v20, v20 row_mirror row_mask:0xf bank_mask:0xf bound_ctrl:1
	v_fma_mix_f32 v19, v34, v31, v19 op_sel:[0,1,0] op_sel_hi:[1,1,0]
	v_fma_mix_f32 v10, v20, v28, v16 op_sel:[0,0,0] op_sel_hi:[0,1,0]
	v_fma_mix_f32 v11, v20, v28, v17 op_sel:[0,1,0] op_sel_hi:[0,1,0]
	v_fma_mix_f32 v12, v20, v29, v18 op_sel:[0,0,0] op_sel_hi:[0,1,0]
	v_fma_mix_f32 v13, v20, v29, v19 op_sel:[0,1,0] op_sel_hi:[0,1,0]
	ds_read_b64 v[84:85], v6 offset:8216
	ds_read_b128 v[86:89], v6 offset:8464
	ds_read_b128 v[90:93], v6 offset:8720
	ds_read_u16 v94, v7 offset:8208
	v_fma_mix_f32 v14, v10, v38, 0 op_sel:[0,0,0] op_sel_hi:[0,1,0]
	v_fma_mix_f32 v52, v10, v32, 0 op_sel:[0,0,0] op_sel_hi:[0,1,0]
	v_fma_mix_f32 v14, v11, v38, v14 op_sel:[0,1,0] op_sel_hi:[0,1,0]
	v_fma_mix_f32 v52, v11, v32, v52 op_sel:[0,1,0] op_sel_hi:[0,1,0]
	v_fma_mix_f32 v14, v12, v39, v14 op_sel:[0,0,0] op_sel_hi:[0,1,0]
	v_fma_mix_f32 v52, v12, v33, v52 op_sel:[0,0,0] op_sel_hi:[0,1,0]
	v_fma_mix_f32 v14, v13, v39, v14 op_sel:[0,1,0] op_sel_hi:[0,1,0]
	v_fma_mix_f32 v16, v10, v36, 0 op_sel:[0,0,0] op_sel_hi:[0,1,0]
	v_fma_mix_f32 v17, v11, v36, 0 op_sel:[0,1,0] op_sel_hi:[0,1,0]
	v_add_f32_dpp v20, v14, v14 quad_perm:[1,0,3,2] row_mask:0xf bank_mask:0xf bound_ctrl:1
	v_fma_mix_f32 v52, v13, v33, v52 op_sel:[0,1,0] op_sel_hi:[0,1,0]
	v_fma_mix_f32 v18, v12, v37, 0 op_sel:[0,0,0] op_sel_hi:[0,1,0]
	v_add_f32_dpp v20, v20, v20 quad_perm:[2,3,0,1] row_mask:0xf bank_mask:0xf bound_ctrl:1
	v_fma_mix_f32 v19, v13, v37, 0 op_sel:[0,1,0] op_sel_hi:[0,1,0]
	v_fma_mix_f32 v16, v46, v42, v16 op_sel:[0,0,0] op_sel_hi:[1,1,0]
	v_add_f32_dpp v20, v20, v20 row_half_mirror row_mask:0xf bank_mask:0xf bound_ctrl:1
	v_fma_mix_f32 v17, v46, v42, v17 op_sel:[0,1,0] op_sel_hi:[1,1,0]
	v_fma_mix_f32 v18, v46, v43, v18 op_sel:[0,0,0] op_sel_hi:[1,1,0]
	v_add_f32_dpp v20, v20, v20 row_mirror row_mask:0xf bank_mask:0xf bound_ctrl:1
	v_fma_mix_f32 v19, v46, v43, v19 op_sel:[0,1,0] op_sel_hi:[1,1,0]
	v_fma_mix_f32 v10, v20, v40, v16 op_sel:[0,0,0] op_sel_hi:[0,1,0]
	v_fma_mix_f32 v11, v20, v40, v17 op_sel:[0,1,0] op_sel_hi:[0,1,0]
	v_fma_mix_f32 v12, v20, v41, v18 op_sel:[0,0,0] op_sel_hi:[0,1,0]
	v_fma_mix_f32 v13, v20, v41, v19 op_sel:[0,1,0] op_sel_hi:[0,1,0]
	s_waitcnt lgkmcnt(0)
	ds_read_b64 v[24:25], v6 offset:7192
	ds_read_b128 v[26:29], v6 offset:7440
	ds_read_b128 v[30:33], v6 offset:7696
	ds_read_u16 v34, v7 offset:7184
	v_fma_mix_f32 v14, v10, v74, 0 op_sel:[0,0,0] op_sel_hi:[0,1,0]
	v_fma_mix_f32 v53, v10, v44, 0 op_sel:[0,0,0] op_sel_hi:[0,1,0]
	v_fma_mix_f32 v14, v11, v74, v14 op_sel:[0,1,0] op_sel_hi:[0,1,0]
	v_fma_mix_f32 v53, v11, v44, v53 op_sel:[0,1,0] op_sel_hi:[0,1,0]
	v_fma_mix_f32 v14, v12, v75, v14 op_sel:[0,0,0] op_sel_hi:[0,1,0]
	v_fma_mix_f32 v53, v12, v45, v53 op_sel:[0,0,0] op_sel_hi:[0,1,0]
	v_fma_mix_f32 v14, v13, v75, v14 op_sel:[0,1,0] op_sel_hi:[0,1,0]
	v_fma_mix_f32 v16, v10, v72, 0 op_sel:[0,0,0] op_sel_hi:[0,1,0]
	v_fma_mix_f32 v17, v11, v72, 0 op_sel:[0,1,0] op_sel_hi:[0,1,0]
	v_add_f32_dpp v20, v14, v14 quad_perm:[1,0,3,2] row_mask:0xf bank_mask:0xf bound_ctrl:1
	v_fma_mix_f32 v53, v13, v45, v53 op_sel:[0,1,0] op_sel_hi:[0,1,0]
	v_fma_mix_f32 v18, v12, v73, 0 op_sel:[0,0,0] op_sel_hi:[0,1,0]
	v_add_f32_dpp v20, v20, v20 quad_perm:[2,3,0,1] row_mask:0xf bank_mask:0xf bound_ctrl:1
	v_fma_mix_f32 v19, v13, v73, 0 op_sel:[0,1,0] op_sel_hi:[0,1,0]
	v_fma_mix_f32 v16, v82, v78, v16 op_sel:[0,0,0] op_sel_hi:[1,1,0]
	v_add_f32_dpp v20, v20, v20 row_half_mirror row_mask:0xf bank_mask:0xf bound_ctrl:1
	v_fma_mix_f32 v17, v82, v78, v17 op_sel:[0,1,0] op_sel_hi:[1,1,0]
	v_fma_mix_f32 v18, v82, v79, v18 op_sel:[0,0,0] op_sel_hi:[1,1,0]
	v_add_f32_dpp v20, v20, v20 row_mirror row_mask:0xf bank_mask:0xf bound_ctrl:1
	v_fma_mix_f32 v19, v82, v79, v19 op_sel:[0,1,0] op_sel_hi:[1,1,0]
	v_fma_mix_f32 v10, v20, v76, v16 op_sel:[0,0,0] op_sel_hi:[0,1,0]
	v_fma_mix_f32 v11, v20, v76, v17 op_sel:[0,1,0] op_sel_hi:[0,1,0]
	v_fma_mix_f32 v12, v20, v77, v18 op_sel:[0,0,0] op_sel_hi:[0,1,0]
	v_fma_mix_f32 v13, v20, v77, v19 op_sel:[0,1,0] op_sel_hi:[0,1,0]
	ds_read_b64 v[36:37], v6 offset:6168
	ds_read_b128 v[38:41], v6 offset:6416
	ds_read_b128 v[42:45], v6 offset:6672
	ds_read_u16 v46, v7 offset:6160
	v_fma_mix_f32 v14, v10, v86, 0 op_sel:[0,0,0] op_sel_hi:[0,1,0]
	v_fma_mix_f32 v54, v10, v80, 0 op_sel:[0,0,0] op_sel_hi:[0,1,0]
	v_fma_mix_f32 v14, v11, v86, v14 op_sel:[0,1,0] op_sel_hi:[0,1,0]
	v_fma_mix_f32 v54, v11, v80, v54 op_sel:[0,1,0] op_sel_hi:[0,1,0]
	v_fma_mix_f32 v14, v12, v87, v14 op_sel:[0,0,0] op_sel_hi:[0,1,0]
	v_fma_mix_f32 v54, v12, v81, v54 op_sel:[0,0,0] op_sel_hi:[0,1,0]
	v_fma_mix_f32 v14, v13, v87, v14 op_sel:[0,1,0] op_sel_hi:[0,1,0]
	v_fma_mix_f32 v16, v10, v84, 0 op_sel:[0,0,0] op_sel_hi:[0,1,0]
	v_fma_mix_f32 v17, v11, v84, 0 op_sel:[0,1,0] op_sel_hi:[0,1,0]
	v_add_f32_dpp v20, v14, v14 quad_perm:[1,0,3,2] row_mask:0xf bank_mask:0xf bound_ctrl:1
	v_fma_mix_f32 v54, v13, v81, v54 op_sel:[0,1,0] op_sel_hi:[0,1,0]
	v_fma_mix_f32 v18, v12, v85, 0 op_sel:[0,0,0] op_sel_hi:[0,1,0]
	v_add_f32_dpp v20, v20, v20 quad_perm:[2,3,0,1] row_mask:0xf bank_mask:0xf bound_ctrl:1
	v_fma_mix_f32 v19, v13, v85, 0 op_sel:[0,1,0] op_sel_hi:[0,1,0]
	v_fma_mix_f32 v16, v94, v90, v16 op_sel:[0,0,0] op_sel_hi:[1,1,0]
	v_add_f32_dpp v20, v20, v20 row_half_mirror row_mask:0xf bank_mask:0xf bound_ctrl:1
	v_fma_mix_f32 v17, v94, v90, v17 op_sel:[0,1,0] op_sel_hi:[1,1,0]
	v_fma_mix_f32 v18, v94, v91, v18 op_sel:[0,0,0] op_sel_hi:[1,1,0]
	v_add_f32_dpp v20, v20, v20 row_mirror row_mask:0xf bank_mask:0xf bound_ctrl:1
	v_fma_mix_f32 v19, v94, v91, v19 op_sel:[0,1,0] op_sel_hi:[1,1,0]
	v_fma_mix_f32 v10, v20, v88, v16 op_sel:[0,0,0] op_sel_hi:[0,1,0]
	v_fma_mix_f32 v11, v20, v88, v17 op_sel:[0,1,0] op_sel_hi:[0,1,0]
	v_fma_mix_f32 v12, v20, v89, v18 op_sel:[0,0,0] op_sel_hi:[0,1,0]
	v_fma_mix_f32 v13, v20, v89, v19 op_sel:[0,1,0] op_sel_hi:[0,1,0]
	s_waitcnt lgkmcnt(0)
	ds_read_b64 v[72:73], v6 offset:5144
	ds_read_b128 v[74:77], v6 offset:5392
	ds_read_b128 v[78:81], v6 offset:5648
	ds_read_u16 v82, v7 offset:5136
	v_fma_mix_f32 v14, v10, v26, 0 op_sel:[0,0,0] op_sel_hi:[0,1,0]
	v_fma_mix_f32 v55, v10, v92, 0 op_sel:[0,0,0] op_sel_hi:[0,1,0]
	v_fma_mix_f32 v14, v11, v26, v14 op_sel:[0,1,0] op_sel_hi:[0,1,0]
	v_fma_mix_f32 v55, v11, v92, v55 op_sel:[0,1,0] op_sel_hi:[0,1,0]
	v_fma_mix_f32 v14, v12, v27, v14 op_sel:[0,0,0] op_sel_hi:[0,1,0]
	v_fma_mix_f32 v55, v12, v93, v55 op_sel:[0,0,0] op_sel_hi:[0,1,0]
	v_fma_mix_f32 v14, v13, v27, v14 op_sel:[0,1,0] op_sel_hi:[0,1,0]
	v_fma_mix_f32 v16, v10, v24, 0 op_sel:[0,0,0] op_sel_hi:[0,1,0]
	v_fma_mix_f32 v17, v11, v24, 0 op_sel:[0,1,0] op_sel_hi:[0,1,0]
	v_add_f32_dpp v20, v14, v14 quad_perm:[1,0,3,2] row_mask:0xf bank_mask:0xf bound_ctrl:1
	v_fma_mix_f32 v55, v13, v93, v55 op_sel:[0,1,0] op_sel_hi:[0,1,0]
	v_fma_mix_f32 v18, v12, v25, 0 op_sel:[0,0,0] op_sel_hi:[0,1,0]
	v_add_f32_dpp v20, v20, v20 quad_perm:[2,3,0,1] row_mask:0xf bank_mask:0xf bound_ctrl:1
	v_fma_mix_f32 v19, v13, v25, 0 op_sel:[0,1,0] op_sel_hi:[0,1,0]
	v_fma_mix_f32 v16, v34, v30, v16 op_sel:[0,0,0] op_sel_hi:[1,1,0]
	v_add_f32_dpp v20, v20, v20 row_half_mirror row_mask:0xf bank_mask:0xf bound_ctrl:1
	v_fma_mix_f32 v17, v34, v30, v17 op_sel:[0,1,0] op_sel_hi:[1,1,0]
	v_fma_mix_f32 v18, v34, v31, v18 op_sel:[0,0,0] op_sel_hi:[1,1,0]
	v_add_f32_dpp v20, v20, v20 row_mirror row_mask:0xf bank_mask:0xf bound_ctrl:1
	v_fma_mix_f32 v19, v34, v31, v19 op_sel:[0,1,0] op_sel_hi:[1,1,0]
	v_fma_mix_f32 v10, v20, v28, v16 op_sel:[0,0,0] op_sel_hi:[0,1,0]
	v_fma_mix_f32 v11, v20, v28, v17 op_sel:[0,1,0] op_sel_hi:[0,1,0]
	v_fma_mix_f32 v12, v20, v29, v18 op_sel:[0,0,0] op_sel_hi:[0,1,0]
	v_fma_mix_f32 v13, v20, v29, v19 op_sel:[0,1,0] op_sel_hi:[0,1,0]
	ds_read_b64 v[84:85], v6 offset:4120
	ds_read_b128 v[86:89], v6 offset:4368
	ds_read_b128 v[90:93], v6 offset:4624
	ds_read_u16 v94, v7 offset:4112
	v_fma_mix_f32 v14, v10, v38, 0 op_sel:[0,0,0] op_sel_hi:[0,1,0]
	v_fma_mix_f32 v56, v10, v32, 0 op_sel:[0,0,0] op_sel_hi:[0,1,0]
	v_fma_mix_f32 v14, v11, v38, v14 op_sel:[0,1,0] op_sel_hi:[0,1,0]
	v_fma_mix_f32 v56, v11, v32, v56 op_sel:[0,1,0] op_sel_hi:[0,1,0]
	v_fma_mix_f32 v14, v12, v39, v14 op_sel:[0,0,0] op_sel_hi:[0,1,0]
	v_fma_mix_f32 v56, v12, v33, v56 op_sel:[0,0,0] op_sel_hi:[0,1,0]
	v_fma_mix_f32 v14, v13, v39, v14 op_sel:[0,1,0] op_sel_hi:[0,1,0]
	v_fma_mix_f32 v16, v10, v36, 0 op_sel:[0,0,0] op_sel_hi:[0,1,0]
	v_fma_mix_f32 v17, v11, v36, 0 op_sel:[0,1,0] op_sel_hi:[0,1,0]
	v_add_f32_dpp v20, v14, v14 quad_perm:[1,0,3,2] row_mask:0xf bank_mask:0xf bound_ctrl:1
	v_fma_mix_f32 v56, v13, v33, v56 op_sel:[0,1,0] op_sel_hi:[0,1,0]
	v_fma_mix_f32 v18, v12, v37, 0 op_sel:[0,0,0] op_sel_hi:[0,1,0]
	v_add_f32_dpp v20, v20, v20 quad_perm:[2,3,0,1] row_mask:0xf bank_mask:0xf bound_ctrl:1
	v_fma_mix_f32 v19, v13, v37, 0 op_sel:[0,1,0] op_sel_hi:[0,1,0]
	v_fma_mix_f32 v16, v46, v42, v16 op_sel:[0,0,0] op_sel_hi:[1,1,0]
	v_add_f32_dpp v20, v20, v20 row_half_mirror row_mask:0xf bank_mask:0xf bound_ctrl:1
	v_fma_mix_f32 v17, v46, v42, v17 op_sel:[0,1,0] op_sel_hi:[1,1,0]
	v_fma_mix_f32 v18, v46, v43, v18 op_sel:[0,0,0] op_sel_hi:[1,1,0]
	v_add_f32_dpp v20, v20, v20 row_mirror row_mask:0xf bank_mask:0xf bound_ctrl:1
	v_fma_mix_f32 v19, v46, v43, v19 op_sel:[0,1,0] op_sel_hi:[1,1,0]
	v_fma_mix_f32 v10, v20, v40, v16 op_sel:[0,0,0] op_sel_hi:[0,1,0]
	v_fma_mix_f32 v11, v20, v40, v17 op_sel:[0,1,0] op_sel_hi:[0,1,0]
	v_fma_mix_f32 v12, v20, v41, v18 op_sel:[0,0,0] op_sel_hi:[0,1,0]
	v_fma_mix_f32 v13, v20, v41, v19 op_sel:[0,1,0] op_sel_hi:[0,1,0]
	s_waitcnt lgkmcnt(0)
	ds_read_b64 v[24:25], v6 offset:3096
	ds_read_b128 v[26:29], v6 offset:3344
	ds_read_b128 v[30:33], v6 offset:3600
	ds_read_u16 v34, v7 offset:3088
	v_fma_mix_f32 v14, v10, v74, 0 op_sel:[0,0,0] op_sel_hi:[0,1,0]
	v_fma_mix_f32 v57, v10, v44, 0 op_sel:[0,0,0] op_sel_hi:[0,1,0]
	v_fma_mix_f32 v14, v11, v74, v14 op_sel:[0,1,0] op_sel_hi:[0,1,0]
	v_fma_mix_f32 v57, v11, v44, v57 op_sel:[0,1,0] op_sel_hi:[0,1,0]
	v_fma_mix_f32 v14, v12, v75, v14 op_sel:[0,0,0] op_sel_hi:[0,1,0]
	v_fma_mix_f32 v57, v12, v45, v57 op_sel:[0,0,0] op_sel_hi:[0,1,0]
	v_fma_mix_f32 v14, v13, v75, v14 op_sel:[0,1,0] op_sel_hi:[0,1,0]
	v_fma_mix_f32 v16, v10, v72, 0 op_sel:[0,0,0] op_sel_hi:[0,1,0]
	v_fma_mix_f32 v17, v11, v72, 0 op_sel:[0,1,0] op_sel_hi:[0,1,0]
	v_add_f32_dpp v20, v14, v14 quad_perm:[1,0,3,2] row_mask:0xf bank_mask:0xf bound_ctrl:1
	v_fma_mix_f32 v57, v13, v45, v57 op_sel:[0,1,0] op_sel_hi:[0,1,0]
	v_fma_mix_f32 v18, v12, v73, 0 op_sel:[0,0,0] op_sel_hi:[0,1,0]
	v_add_f32_dpp v20, v20, v20 quad_perm:[2,3,0,1] row_mask:0xf bank_mask:0xf bound_ctrl:1
	v_fma_mix_f32 v19, v13, v73, 0 op_sel:[0,1,0] op_sel_hi:[0,1,0]
	v_fma_mix_f32 v16, v82, v78, v16 op_sel:[0,0,0] op_sel_hi:[1,1,0]
	v_add_f32_dpp v20, v20, v20 row_half_mirror row_mask:0xf bank_mask:0xf bound_ctrl:1
	v_fma_mix_f32 v17, v82, v78, v17 op_sel:[0,1,0] op_sel_hi:[1,1,0]
	v_fma_mix_f32 v18, v82, v79, v18 op_sel:[0,0,0] op_sel_hi:[1,1,0]
	v_add_f32_dpp v20, v20, v20 row_mirror row_mask:0xf bank_mask:0xf bound_ctrl:1
	v_fma_mix_f32 v19, v82, v79, v19 op_sel:[0,1,0] op_sel_hi:[1,1,0]
	v_fma_mix_f32 v10, v20, v76, v16 op_sel:[0,0,0] op_sel_hi:[0,1,0]
	v_fma_mix_f32 v11, v20, v76, v17 op_sel:[0,1,0] op_sel_hi:[0,1,0]
	v_fma_mix_f32 v12, v20, v77, v18 op_sel:[0,0,0] op_sel_hi:[0,1,0]
	v_fma_mix_f32 v13, v20, v77, v19 op_sel:[0,1,0] op_sel_hi:[0,1,0]
	ds_read_b64 v[36:37], v6 offset:2072
	ds_read_b128 v[38:41], v6 offset:2320
	ds_read_b128 v[42:45], v6 offset:2576
	ds_read_u16 v46, v7 offset:2064
	v_fma_mix_f32 v14, v10, v86, 0 op_sel:[0,0,0] op_sel_hi:[0,1,0]
	v_fma_mix_f32 v58, v10, v80, 0 op_sel:[0,0,0] op_sel_hi:[0,1,0]
	v_fma_mix_f32 v14, v11, v86, v14 op_sel:[0,1,0] op_sel_hi:[0,1,0]
	v_fma_mix_f32 v58, v11, v80, v58 op_sel:[0,1,0] op_sel_hi:[0,1,0]
	v_fma_mix_f32 v14, v12, v87, v14 op_sel:[0,0,0] op_sel_hi:[0,1,0]
	v_fma_mix_f32 v58, v12, v81, v58 op_sel:[0,0,0] op_sel_hi:[0,1,0]
	v_fma_mix_f32 v14, v13, v87, v14 op_sel:[0,1,0] op_sel_hi:[0,1,0]
	v_fma_mix_f32 v16, v10, v84, 0 op_sel:[0,0,0] op_sel_hi:[0,1,0]
	v_fma_mix_f32 v17, v11, v84, 0 op_sel:[0,1,0] op_sel_hi:[0,1,0]
	v_add_f32_dpp v20, v14, v14 quad_perm:[1,0,3,2] row_mask:0xf bank_mask:0xf bound_ctrl:1
	v_fma_mix_f32 v58, v13, v81, v58 op_sel:[0,1,0] op_sel_hi:[0,1,0]
	v_fma_mix_f32 v18, v12, v85, 0 op_sel:[0,0,0] op_sel_hi:[0,1,0]
	v_add_f32_dpp v20, v20, v20 quad_perm:[2,3,0,1] row_mask:0xf bank_mask:0xf bound_ctrl:1
	v_fma_mix_f32 v19, v13, v85, 0 op_sel:[0,1,0] op_sel_hi:[0,1,0]
	v_fma_mix_f32 v16, v94, v90, v16 op_sel:[0,0,0] op_sel_hi:[1,1,0]
	v_add_f32_dpp v20, v20, v20 row_half_mirror row_mask:0xf bank_mask:0xf bound_ctrl:1
	v_fma_mix_f32 v17, v94, v90, v17 op_sel:[0,1,0] op_sel_hi:[1,1,0]
	v_fma_mix_f32 v18, v94, v91, v18 op_sel:[0,0,0] op_sel_hi:[1,1,0]
	v_add_f32_dpp v20, v20, v20 row_mirror row_mask:0xf bank_mask:0xf bound_ctrl:1
	v_fma_mix_f32 v19, v94, v91, v19 op_sel:[0,1,0] op_sel_hi:[1,1,0]
	v_fma_mix_f32 v10, v20, v88, v16 op_sel:[0,0,0] op_sel_hi:[0,1,0]
	v_fma_mix_f32 v11, v20, v88, v17 op_sel:[0,1,0] op_sel_hi:[0,1,0]
	v_fma_mix_f32 v12, v20, v89, v18 op_sel:[0,0,0] op_sel_hi:[0,1,0]
	v_fma_mix_f32 v13, v20, v89, v19 op_sel:[0,1,0] op_sel_hi:[0,1,0]
	s_waitcnt lgkmcnt(0)
	ds_read_b64 v[72:73], v6 offset:1048
	ds_read_b128 v[74:77], v6 offset:1296
	ds_read_b128 v[78:81], v6 offset:1552
	ds_read_u16 v82, v7 offset:1040
	v_fma_mix_f32 v14, v10, v26, 0 op_sel:[0,0,0] op_sel_hi:[0,1,0]
	v_fma_mix_f32 v59, v10, v92, 0 op_sel:[0,0,0] op_sel_hi:[0,1,0]
	v_fma_mix_f32 v14, v11, v26, v14 op_sel:[0,1,0] op_sel_hi:[0,1,0]
	v_fma_mix_f32 v59, v11, v92, v59 op_sel:[0,1,0] op_sel_hi:[0,1,0]
	v_fma_mix_f32 v14, v12, v27, v14 op_sel:[0,0,0] op_sel_hi:[0,1,0]
	v_fma_mix_f32 v59, v12, v93, v59 op_sel:[0,0,0] op_sel_hi:[0,1,0]
	v_fma_mix_f32 v14, v13, v27, v14 op_sel:[0,1,0] op_sel_hi:[0,1,0]
	v_fma_mix_f32 v16, v10, v24, 0 op_sel:[0,0,0] op_sel_hi:[0,1,0]
	v_fma_mix_f32 v17, v11, v24, 0 op_sel:[0,1,0] op_sel_hi:[0,1,0]
	v_add_f32_dpp v20, v14, v14 quad_perm:[1,0,3,2] row_mask:0xf bank_mask:0xf bound_ctrl:1
	v_fma_mix_f32 v59, v13, v93, v59 op_sel:[0,1,0] op_sel_hi:[0,1,0]
	v_fma_mix_f32 v18, v12, v25, 0 op_sel:[0,0,0] op_sel_hi:[0,1,0]
	v_add_f32_dpp v20, v20, v20 quad_perm:[2,3,0,1] row_mask:0xf bank_mask:0xf bound_ctrl:1
	v_fma_mix_f32 v19, v13, v25, 0 op_sel:[0,1,0] op_sel_hi:[0,1,0]
	v_fma_mix_f32 v16, v34, v30, v16 op_sel:[0,0,0] op_sel_hi:[1,1,0]
	v_add_f32_dpp v20, v20, v20 row_half_mirror row_mask:0xf bank_mask:0xf bound_ctrl:1
	v_fma_mix_f32 v17, v34, v30, v17 op_sel:[0,1,0] op_sel_hi:[1,1,0]
	v_fma_mix_f32 v18, v34, v31, v18 op_sel:[0,0,0] op_sel_hi:[1,1,0]
	v_add_f32_dpp v20, v20, v20 row_mirror row_mask:0xf bank_mask:0xf bound_ctrl:1
	v_fma_mix_f32 v19, v34, v31, v19 op_sel:[0,1,0] op_sel_hi:[1,1,0]
	v_fma_mix_f32 v10, v20, v28, v16 op_sel:[0,0,0] op_sel_hi:[0,1,0]
	v_fma_mix_f32 v11, v20, v28, v17 op_sel:[0,1,0] op_sel_hi:[0,1,0]
	v_fma_mix_f32 v12, v20, v29, v18 op_sel:[0,0,0] op_sel_hi:[0,1,0]
	v_fma_mix_f32 v13, v20, v29, v19 op_sel:[0,1,0] op_sel_hi:[0,1,0]
	ds_read_b128 v[100:103], v9
	ds_read_b64 v[84:85], v6 offset:24
	ds_read_b128 v[86:89], v6 offset:272
	ds_read_b128 v[90:93], v6 offset:528
	ds_read_u16 v94, v7 offset:16
	v_fma_mix_f32 v14, v10, v38, 0 op_sel:[0,0,0] op_sel_hi:[0,1,0]
	v_fma_mix_f32 v60, v10, v32, 0 op_sel:[0,0,0] op_sel_hi:[0,1,0]
	v_fma_mix_f32 v14, v11, v38, v14 op_sel:[0,1,0] op_sel_hi:[0,1,0]
	v_fma_mix_f32 v60, v11, v32, v60 op_sel:[0,1,0] op_sel_hi:[0,1,0]
	v_fma_mix_f32 v14, v12, v39, v14 op_sel:[0,0,0] op_sel_hi:[0,1,0]
	v_fma_mix_f32 v60, v12, v33, v60 op_sel:[0,0,0] op_sel_hi:[0,1,0]
	v_fma_mix_f32 v14, v13, v39, v14 op_sel:[0,1,0] op_sel_hi:[0,1,0]
	v_fma_mix_f32 v16, v10, v36, 0 op_sel:[0,0,0] op_sel_hi:[0,1,0]
	v_fma_mix_f32 v17, v11, v36, 0 op_sel:[0,1,0] op_sel_hi:[0,1,0]
	v_add_f32_dpp v20, v14, v14 quad_perm:[1,0,3,2] row_mask:0xf bank_mask:0xf bound_ctrl:1
	v_fma_mix_f32 v60, v13, v33, v60 op_sel:[0,1,0] op_sel_hi:[0,1,0]
	v_fma_mix_f32 v18, v12, v37, 0 op_sel:[0,0,0] op_sel_hi:[0,1,0]
	v_add_f32_dpp v20, v20, v20 quad_perm:[2,3,0,1] row_mask:0xf bank_mask:0xf bound_ctrl:1
	v_fma_mix_f32 v19, v13, v37, 0 op_sel:[0,1,0] op_sel_hi:[0,1,0]
	v_fma_mix_f32 v16, v46, v42, v16 op_sel:[0,0,0] op_sel_hi:[1,1,0]
	v_add_f32_dpp v20, v20, v20 row_half_mirror row_mask:0xf bank_mask:0xf bound_ctrl:1
	v_fma_mix_f32 v17, v46, v42, v17 op_sel:[0,1,0] op_sel_hi:[1,1,0]
	v_fma_mix_f32 v18, v46, v43, v18 op_sel:[0,0,0] op_sel_hi:[1,1,0]
	v_add_f32_dpp v20, v20, v20 row_mirror row_mask:0xf bank_mask:0xf bound_ctrl:1
	v_fma_mix_f32 v19, v46, v43, v19 op_sel:[0,1,0] op_sel_hi:[1,1,0]
	v_fma_mix_f32 v10, v20, v40, v16 op_sel:[0,0,0] op_sel_hi:[0,1,0]
	v_fma_mix_f32 v11, v20, v40, v17 op_sel:[0,1,0] op_sel_hi:[0,1,0]
	v_fma_mix_f32 v12, v20, v41, v18 op_sel:[0,0,0] op_sel_hi:[0,1,0]
	v_fma_mix_f32 v13, v20, v41, v19 op_sel:[0,1,0] op_sel_hi:[0,1,0]
	s_waitcnt lgkmcnt(0)
; DEVINL u16 f2bf(float a) { return (u16)(pk2(a, 0.f) & 0xffffu); }
; template <int DIR>
; DEVINL void rwkv_scan_dir(const Params& p, int task, int lane, int wave) {
;     ...
;   {
;     const float ylast = allred16(ypart);
;     ykeep = (seg == 15) ? ylast : ykeep;
;     const int q0 = 4096 - 16 + seg; yo[(long)(DIR ? (4095 - q0) : q0) * 1024] = f2bf(ykeep);
	v_add_u32_e32 v6, 0xffffc000, v6
	v_add_u32_e32 v7, 0xffffc000, v7
	v_and_b32_e32 v6, 0x1ffff, v6
	v_and_b32_e32 v7, 0x1ffff, v7
	ds_read_b64 v[24:25], v6 offset:15384
	ds_read_b128 v[26:29], v6 offset:15632
	ds_read_b128 v[30:33], v6 offset:15888
	ds_read_u16 v34, v7 offset:15376
	v_fma_mix_f32 v14, v10, v74, 0 op_sel:[0,0,0] op_sel_hi:[0,1,0]
	v_fma_mix_f32 v61, v10, v44, 0 op_sel:[0,0,0] op_sel_hi:[0,1,0]
	v_fma_mix_f32 v14, v11, v74, v14 op_sel:[0,1,0] op_sel_hi:[0,1,0]
	v_fma_mix_f32 v61, v11, v44, v61 op_sel:[0,1,0] op_sel_hi:[0,1,0]
	v_fma_mix_f32 v14, v12, v75, v14 op_sel:[0,0,0] op_sel_hi:[0,1,0]
	v_fma_mix_f32 v61, v12, v45, v61 op_sel:[0,0,0] op_sel_hi:[0,1,0]
	v_fma_mix_f32 v14, v13, v75, v14 op_sel:[0,1,0] op_sel_hi:[0,1,0]
	v_fma_mix_f32 v16, v10, v72, 0 op_sel:[0,0,0] op_sel_hi:[0,1,0]
	v_fma_mix_f32 v17, v11, v72, 0 op_sel:[0,1,0] op_sel_hi:[0,1,0]
	v_add_f32_dpp v20, v14, v14 quad_perm:[1,0,3,2] row_mask:0xf bank_mask:0xf bound_ctrl:1
	v_fma_mix_f32 v61, v13, v45, v61 op_sel:[0,1,0] op_sel_hi:[0,1,0]
	v_fma_mix_f32 v18, v12, v73, 0 op_sel:[0,0,0] op_sel_hi:[0,1,0]
	v_add_f32_dpp v20, v20, v20 quad_perm:[2,3,0,1] row_mask:0xf bank_mask:0xf bound_ctrl:1
	v_fma_mix_f32 v19, v13, v73, 0 op_sel:[0,1,0] op_sel_hi:[0,1,0]
	v_fma_mix_f32 v16, v82, v78, v16 op_sel:[0,0,0] op_sel_hi:[1,1,0]
	v_add_f32_dpp v20, v20, v20 row_half_mirror row_mask:0xf bank_mask:0xf bound_ctrl:1
	v_fma_mix_f32 v17, v82, v78, v17 op_sel:[0,1,0] op_sel_hi:[1,1,0]
	v_fma_mix_f32 v18, v82, v79, v18 op_sel:[0,0,0] op_sel_hi:[1,1,0]
	v_add_f32_dpp v20, v20, v20 row_mirror row_mask:0xf bank_mask:0xf bound_ctrl:1
	v_fma_mix_f32 v19, v82, v79, v19 op_sel:[0,1,0] op_sel_hi:[1,1,0]
	v_fma_mix_f32 v10, v20, v76, v16 op_sel:[0,0,0] op_sel_hi:[0,1,0]
	v_fma_mix_f32 v11, v20, v76, v17 op_sel:[0,1,0] op_sel_hi:[0,1,0]
	v_fma_mix_f32 v12, v20, v77, v18 op_sel:[0,0,0] op_sel_hi:[0,1,0]
	v_fma_mix_f32 v13, v20, v77, v19 op_sel:[0,1,0] op_sel_hi:[0,1,0]
	ds_read_b64 v[36:37], v6 offset:14360
	ds_read_b128 v[38:41], v6 offset:14608
	ds_read_b128 v[42:45], v6 offset:14864
	ds_read_u16 v46, v7 offset:14352
	v_fma_mix_f32 v14, v10, v86, 0 op_sel:[0,0,0] op_sel_hi:[0,1,0]
	v_fma_mix_f32 v62, v10, v80, 0 op_sel:[0,0,0] op_sel_hi:[0,1,0]
	v_fma_mix_f32 v14, v11, v86, v14 op_sel:[0,1,0] op_sel_hi:[0,1,0]
	v_fma_mix_f32 v62, v11, v80, v62 op_sel:[0,1,0] op_sel_hi:[0,1,0]
	v_fma_mix_f32 v14, v12, v87, v14 op_sel:[0,0,0] op_sel_hi:[0,1,0]
	v_fma_mix_f32 v62, v12, v81, v62 op_sel:[0,0,0] op_sel_hi:[0,1,0]
	v_fma_mix_f32 v14, v13, v87, v14 op_sel:[0,1,0] op_sel_hi:[0,1,0]
	v_fma_mix_f32 v16, v10, v84, 0 op_sel:[0,0,0] op_sel_hi:[0,1,0]
	v_fma_mix_f32 v17, v11, v84, 0 op_sel:[0,1,0] op_sel_hi:[0,1,0]
	v_add_f32_dpp v20, v14, v14 quad_perm:[1,0,3,2] row_mask:0xf bank_mask:0xf bound_ctrl:1
	v_fma_mix_f32 v62, v13, v81, v62 op_sel:[0,1,0] op_sel_hi:[0,1,0]
	v_fma_mix_f32 v18, v12, v85, 0 op_sel:[0,0,0] op_sel_hi:[0,1,0]
	v_add_f32_dpp v20, v20, v20 quad_perm:[2,3,0,1] row_mask:0xf bank_mask:0xf bound_ctrl:1
	v_fma_mix_f32 v19, v13, v85, 0 op_sel:[0,1,0] op_sel_hi:[0,1,0]
	v_fma_mix_f32 v16, v94, v90, v16 op_sel:[0,0,0] op_sel_hi:[1,1,0]
	v_add_f32_dpp v20, v20, v20 row_half_mirror row_mask:0xf bank_mask:0xf bound_ctrl:1
	v_fma_mix_f32 v17, v94, v90, v17 op_sel:[0,1,0] op_sel_hi:[1,1,0]
	v_fma_mix_f32 v18, v94, v91, v18 op_sel:[0,0,0] op_sel_hi:[1,1,0]
	v_add_f32_dpp v20, v20, v20 row_mirror row_mask:0xf bank_mask:0xf bound_ctrl:1
	v_fma_mix_f32 v19, v94, v91, v19 op_sel:[0,1,0] op_sel_hi:[1,1,0]
	v_fma_mix_f32 v10, v20, v88, v16 op_sel:[0,0,0] op_sel_hi:[0,1,0]
	v_fma_mix_f32 v11, v20, v88, v17 op_sel:[0,1,0] op_sel_hi:[0,1,0]
	v_fma_mix_f32 v12, v20, v89, v18 op_sel:[0,0,0] op_sel_hi:[0,1,0]
	v_fma_mix_f32 v13, v20, v89, v19 op_sel:[0,1,0] op_sel_hi:[0,1,0]
	s_waitcnt lgkmcnt(0)
	s_add_u32 s43, s43, 1
	s_cmp_lg_u32 s43, s45
	s_cbranch_scc1 .Lrw_blk_d1
	s_sub_u32 s15, s43, 2
	v_fma_mix_f32 v21, v10, v92, 0 op_sel:[0,0,0] op_sel_hi:[0,1,0]
	v_fma_mix_f32 v22, v12, v93, 0 op_sel:[0,0,0] op_sel_hi:[0,1,0]
	v_fma_mix_f32 v21, v11, v92, v21 op_sel:[0,1,0] op_sel_hi:[0,1,0]
	v_fma_mix_f32 v22, v13, v93, v22 op_sel:[0,1,0] op_sel_hi:[0,1,0]
	v_add_f32_e32 v63, v21, v22
	s_nop 1
	v_add_f32_dpp v48, v48, v48 row_ror:8 row_mask:0xf bank_mask:0x3
	v_add_f32_dpp v49, v49, v49 row_ror:8 row_mask:0xf bank_mask:0x3
	v_add_f32_dpp v50, v50, v50 row_ror:8 row_mask:0xf bank_mask:0x3
	v_add_f32_dpp v51, v51, v51 row_ror:8 row_mask:0xf bank_mask:0x3
	v_add_f32_dpp v52, v52, v52 row_ror:8 row_mask:0xf bank_mask:0x3
	v_add_f32_dpp v53, v53, v53 row_ror:8 row_mask:0xf bank_mask:0x3
	v_add_f32_dpp v54, v54, v54 row_ror:8 row_mask:0xf bank_mask:0x3
	v_add_f32_dpp v55, v55, v55 row_ror:8 row_mask:0xf bank_mask:0x3
	v_add_f32_dpp v48, v56, v56 row_ror:8 row_mask:0xf bank_mask:0xc
	v_add_f32_dpp v49, v57, v57 row_ror:8 row_mask:0xf bank_mask:0xc
	v_add_f32_dpp v50, v58, v58 row_ror:8 row_mask:0xf bank_mask:0xc
	v_add_f32_dpp v51, v59, v59 row_ror:8 row_mask:0xf bank_mask:0xc
	v_add_f32_dpp v52, v60, v60 row_ror:8 row_mask:0xf bank_mask:0xc
	v_add_f32_dpp v53, v61, v61 row_ror:8 row_mask:0xf bank_mask:0xc
	v_add_f32_dpp v54, v62, v62 row_ror:8 row_mask:0xf bank_mask:0xc
	v_add_f32_dpp v55, v63, v63 row_ror:8 row_mask:0xf bank_mask:0xc
	v_add_f32_dpp v48, v48, v48 row_ror:12 row_mask:0xf bank_mask:0x5
	v_add_f32_dpp v49, v49, v49 row_ror:12 row_mask:0xf bank_mask:0x5
	v_add_f32_dpp v50, v50, v50 row_ror:12 row_mask:0xf bank_mask:0x5
	v_add_f32_dpp v51, v51, v51 row_ror:12 row_mask:0xf bank_mask:0x5
	v_add_f32_dpp v48, v52, v52 row_ror:4 row_mask:0xf bank_mask:0xa
	v_add_f32_dpp v49, v53, v53 row_ror:4 row_mask:0xf bank_mask:0xa
	v_add_f32_dpp v50, v54, v54 row_ror:4 row_mask:0xf bank_mask:0xa
	v_add_f32_dpp v51, v55, v55 row_ror:4 row_mask:0xf bank_mask:0xa
	v_add_f32_dpp v64, v48, v48 quad_perm:[2,3,0,1] row_mask:0xf bank_mask:0xf bound_ctrl:1
	v_add_f32_dpp v65, v50, v50 quad_perm:[2,3,0,1] row_mask:0xf bank_mask:0xf bound_ctrl:1
	v_cndmask_b32_e64 v56, v64, v65, s[50:51]
	v_add_f32_dpp v64, v49, v49 quad_perm:[2,3,0,1] row_mask:0xf bank_mask:0xf bound_ctrl:1
	v_add_f32_dpp v65, v51, v51 quad_perm:[2,3,0,1] row_mask:0xf bank_mask:0xf bound_ctrl:1
	v_cndmask_b32_e64 v57, v64, v65, s[50:51]
	v_add_f32_dpp v64, v56, v56 quad_perm:[1,0,3,2] row_mask:0xf bank_mask:0xf bound_ctrl:1
	s_nop 0
	v_add_f32_dpp v65, v57, v57 quad_perm:[1,0,3,2] row_mask:0xf bank_mask:0xf bound_ctrl:1
	v_cndmask_b32_e64 v66, v64, v65, s[48:49]
	v_cvt_pk_bf16_f32 v66, v66, v66
	global_store_short v8, v66, s[12:13]
	s_sub_u32 s12, s12, 0x8000
	s_subb_u32 s13, s13, 0
